# main-loop fragment wait as an eight-rung counted ladder (a wait before every second MFMA where a new fragment is first used)
# speedup vs baseline: 1.0163x; 1.0085x over previous
.LBB0_403:
	s_add_u32 s14, s4, 0x100
	s_addc_u32 s15, s5, 0
	s_add_i32 s38, 0, 0x10000
	v_add_u32_e32 v12, s38, v193
	ds_read_b128 v[0:3], v12
	ds_read_b128 v[8:11], v12 offset:2048
	ds_read_b128 v[4:7], v12 offset:1024
	ds_read_b128 v[12:15], v12 offset:3072
	s_cmp_eq_u32 s37, 12
	s_cselect_b32 s19, s9, s15
	s_cselect_b32 s18, s8, s14
	s_cselect_b32 s17, s11, s36
	s_cselect_b32 s16, s10, s7
	v_lshl_add_u64 v[190:191], s[4:5], 0, v[186:187]
	s_add_i32 m0, s23, 0xc000
	ds_read_b128 v[16:19], v206
	ds_read_b128 v[24:27], v206 offset:2048
	ds_read_b128 v[162:165], v206 offset:4096
	ds_read_b128 v[170:173], v206 offset:6144
	ds_read_b128 v[20:23], v206 offset:1024
	ds_read_b128 v[28:31], v206 offset:3072
	ds_read_b128 v[166:169], v206 offset:5120
	ds_read_b128 v[174:177], v206 offset:7168
	global_load_lds_dwordx4 v[190:191], off
	v_lshl_add_u64 v[190:191], s[4:5], 0, v[188:189]
	s_add_i32 m0, s23, 0xe000
	s_nop 0
	global_load_lds_dwordx4 v[190:191], off
	s_waitcnt lgkmcnt(8)
	s_barrier
	s_waitcnt lgkmcnt(7)
	s_setprio 1
	v_mfma_f32_16x16x32_f16 v[158:161], v[0:3], v[16:19], v[158:161]
	v_mfma_f32_16x16x32_f16 v[142:145], v[8:11], v[16:19], v[142:145]
	s_waitcnt lgkmcnt(6)
	v_mfma_f32_16x16x32_f16 v[150:153], v[0:3], v[24:27], v[150:153]
	v_mfma_f32_16x16x32_f16 v[134:137], v[8:11], v[24:27], v[134:137]
	s_waitcnt lgkmcnt(5)
	v_mfma_f32_16x16x32_f16 v[154:157], v[0:3], v[162:165], v[154:157]
	v_mfma_f32_16x16x32_f16 v[138:141], v[8:11], v[162:165], v[138:141]
	s_waitcnt lgkmcnt(4)
	v_mfma_f32_16x16x32_f16 v[146:149], v[0:3], v[170:173], v[146:149]
	v_mfma_f32_16x16x32_f16 v[130:133], v[8:11], v[170:173], v[130:133]
	s_waitcnt lgkmcnt(3)
	v_mfma_f32_16x16x32_f16 v[158:161], v[4:7], v[20:23], v[158:161]
	v_mfma_f32_16x16x32_f16 v[142:145], v[12:15], v[20:23], v[142:145]
	s_waitcnt lgkmcnt(2)
	v_mfma_f32_16x16x32_f16 v[150:153], v[4:7], v[28:31], v[150:153]
	v_mfma_f32_16x16x32_f16 v[134:137], v[12:15], v[28:31], v[134:137]
	s_waitcnt lgkmcnt(1)
	v_mfma_f32_16x16x32_f16 v[154:157], v[4:7], v[166:169], v[154:157]
	v_mfma_f32_16x16x32_f16 v[138:141], v[12:15], v[166:169], v[138:141]
	s_waitcnt lgkmcnt(0)
	v_mfma_f32_16x16x32_f16 v[146:149], v[4:7], v[174:177], v[146:149]
	v_mfma_f32_16x16x32_f16 v[130:133], v[12:15], v[174:177], v[130:133]
	s_setprio 0
	s_barrier
	s_add_i32 s39, 0, 0x14000
	s_add_i32 s4, s38, s22
	v_add_u32_e32 v32, s39, v193
	v_lshl_add_u64 v[190:191], s[16:17], 0, v[178:179]
	s_mov_b32 m0, s4
	ds_read_b128 v[208:211], v32
	ds_read_b128 v[216:219], v32 offset:2048
	ds_read_b128 v[212:215], v32 offset:1024
	ds_read_b128 v[230:233], v32 offset:3072
	global_load_lds_dwordx4 v[190:191], off
	v_lshl_add_u64 v[238:239], s[16:17], 0, v[180:181]
	s_add_i32 m0, s4, 0x2000
	s_nop 0
	global_load_lds_dwordx4 v[238:239], off
	s_barrier
	s_waitcnt lgkmcnt(2)
	s_setprio 1
	v_mfma_f32_16x16x32_f16 v[94:97], v[208:211], v[16:19], v[94:97]
	v_mfma_f32_16x16x32_f16 v[16:19], v[216:219], v[16:19], v[78:81]
	s_waitcnt lgkmcnt(0)
	v_mfma_f32_16x16x32_f16 v[94:97], v[212:215], v[20:23], v[94:97]
	v_mfma_f32_16x16x32_f16 v[16:19], v[230:233], v[20:23], v[16:19]
	v_mfma_f32_16x16x32_f16 v[20:23], v[208:211], v[24:27], v[86:89]
	v_mfma_f32_16x16x32_f16 v[24:27], v[216:219], v[24:27], v[70:73]
	v_mfma_f32_16x16x32_f16 v[70:73], v[216:219], v[162:165], v[74:77]
	v_mfma_f32_16x16x32_f16 v[74:77], v[230:233], v[166:169], v[70:73]
	v_mfma_f32_16x16x32_f16 v[70:73], v[208:211], v[170:173], v[82:85]
	v_mfma_f32_16x16x32_f16 v[66:69], v[216:219], v[170:173], v[66:69]
	v_mfma_f32_16x16x32_f16 v[20:23], v[212:215], v[28:31], v[20:23]
	v_mfma_f32_16x16x32_f16 v[24:27], v[230:233], v[28:31], v[24:27]
	v_mfma_f32_16x16x32_f16 v[28:31], v[208:211], v[162:165], v[90:93]
	v_mfma_f32_16x16x32_f16 v[82:85], v[212:215], v[174:177], v[70:73]
	v_mfma_f32_16x16x32_f16 v[66:69], v[230:233], v[174:177], v[66:69]
	v_mfma_f32_16x16x32_f16 v[28:31], v[212:215], v[166:169], v[28:31]
	s_setprio 0
	s_mov_b32 m0, s23
	v_lshl_add_u64 v[240:241], s[18:19], 0, v[178:179]
	s_barrier
	ds_read_b128 v[70:73], v206 offset:16384
	ds_read_b128 v[86:89], v206 offset:18432
	ds_read_b128 v[162:165], v206 offset:20480
	ds_read_b128 v[170:173], v206 offset:22528
	ds_read_b128 v[78:81], v206 offset:17408
	ds_read_b128 v[90:93], v206 offset:19456
	ds_read_b128 v[166:169], v206 offset:21504
	ds_read_b128 v[174:177], v206 offset:23552
	global_load_lds_dwordx4 v[240:241], off
	v_lshl_add_u64 v[242:243], s[18:19], 0, v[180:181]
	s_mov_b32 m0, s24
	s_nop 0
	global_load_lds_dwordx4 v[242:243], off
	s_barrier
	s_waitcnt lgkmcnt(7)
	s_setprio 1
	v_mfma_f32_16x16x32_f16 v[126:129], v[0:3], v[70:73], v[126:129]
	v_mfma_f32_16x16x32_f16 v[110:113], v[8:11], v[70:73], v[110:113]
	s_waitcnt lgkmcnt(6)
	v_mfma_f32_16x16x32_f16 v[118:121], v[0:3], v[86:89], v[118:121]
	v_mfma_f32_16x16x32_f16 v[102:105], v[8:11], v[86:89], v[102:105]
	s_waitcnt lgkmcnt(5)
	v_mfma_f32_16x16x32_f16 v[122:125], v[0:3], v[162:165], v[122:125]
	v_mfma_f32_16x16x32_f16 v[106:109], v[8:11], v[162:165], v[106:109]
	s_waitcnt lgkmcnt(3)
	v_mfma_f32_16x16x32_f16 v[0:3], v[0:3], v[170:173], v[114:117]
	v_mfma_f32_16x16x32_f16 v[126:129], v[4:7], v[78:81], v[126:129]
	s_waitcnt lgkmcnt(2)
	v_mfma_f32_16x16x32_f16 v[110:113], v[12:15], v[78:81], v[110:113]
	v_mfma_f32_16x16x32_f16 v[118:121], v[4:7], v[90:93], v[118:121]
	s_waitcnt lgkmcnt(1)
	v_mfma_f32_16x16x32_f16 v[102:105], v[12:15], v[90:93], v[102:105]
	v_mfma_f32_16x16x32_f16 v[122:125], v[4:7], v[166:169], v[122:125]
	s_waitcnt lgkmcnt(0)
	v_mfma_f32_16x16x32_f16 v[106:109], v[12:15], v[166:169], v[106:109]
	v_mfma_f32_16x16x32_f16 v[0:3], v[4:7], v[174:177], v[0:3]
	v_mfma_f32_16x16x32_f16 v[4:7], v[8:11], v[170:173], v[98:101]
	v_mfma_f32_16x16x32_f16 v[4:7], v[12:15], v[174:177], v[4:7]
	s_setprio 0
	s_barrier
	s_add_u32 s4, s16, 0x40000
	s_addc_u32 s5, s17, 0
	s_add_i32 s38, s39, s22
	v_lshl_add_u64 v[8:9], s[4:5], 0, v[178:179]
	s_mov_b32 m0, s38
	s_nop 0
	global_load_lds_dwordx4 v[8:9], off
	v_lshl_add_u64 v[8:9], s[4:5], 0, v[180:181]
	s_add_i32 m0, s38, 0x2000
	s_nop 0
	global_load_lds_dwordx4 v[8:9], off
	s_waitcnt vmcnt(6)
	s_barrier
	s_setprio 1
	v_mfma_f32_16x16x32_f16 v[12:15], v[216:219], v[70:73], v[46:49]
	v_mfma_f32_16x16x32_f16 v[46:49], v[208:211], v[86:89], v[54:57]
	v_mfma_f32_16x16x32_f16 v[54:57], v[212:215], v[90:93], v[46:49]
	v_mfma_f32_16x16x32_f16 v[46:49], v[208:211], v[162:165], v[58:61]
	v_mfma_f32_16x16x32_f16 v[38:41], v[216:219], v[86:89], v[38:41]
	v_mfma_f32_16x16x32_f16 v[58:61], v[212:215], v[166:169], v[46:49]
	v_mfma_f32_16x16x32_f16 v[42:45], v[216:219], v[162:165], v[42:45]
	v_mfma_f32_16x16x32_f16 v[46:49], v[208:211], v[170:173], v[50:53]
	v_mfma_f32_16x16x32_f16 v[34:37], v[216:219], v[170:173], v[34:37]
	v_mfma_f32_16x16x32_f16 v[8:11], v[208:211], v[70:73], v[62:65]
	v_mfma_f32_16x16x32_f16 v[38:41], v[230:233], v[90:93], v[38:41]
	v_mfma_f32_16x16x32_f16 v[42:45], v[230:233], v[166:169], v[42:45]
	v_mfma_f32_16x16x32_f16 v[50:53], v[212:215], v[174:177], v[46:49]
	v_mfma_f32_16x16x32_f16 v[34:37], v[230:233], v[174:177], v[34:37]
	v_mfma_f32_16x16x32_f16 v[8:11], v[212:215], v[78:81], v[8:11]
	v_mfma_f32_16x16x32_f16 v[12:15], v[230:233], v[78:81], v[12:15]
	s_setprio 0
	s_add_i32 s38, 0, 0x18000
	v_add_u32_e32 v32, s38, v193
	s_barrier
	ds_read_b128 v[46:49], v32
	ds_read_b128 v[62:65], v32 offset:1024
	ds_read_b128 v[98:101], v32 offset:2048
	ds_read_b128 v[162:165], v32 offset:3072
	s_add_u32 s4, s18, 0x40000
	s_addc_u32 s5, s19, 0
	s_mov_b32 m0, s25
	v_lshl_add_u64 v[86:87], s[4:5], 0, v[178:179]
	ds_read_b128 v[70:73], v206 offset:32768
	ds_read_b128 v[78:81], v206 offset:33792
	ds_read_b128 v[90:93], v206 offset:34816
	ds_read_b128 v[114:117], v206 offset:35840
	ds_read_b128 v[166:169], v206 offset:36864
	ds_read_b128 v[170:173], v206 offset:37888
	ds_read_b128 v[174:177], v206 offset:38912
	ds_read_b128 v[208:211], v206 offset:39936
	global_load_lds_dwordx4 v[86:87], off
	v_lshl_add_u64 v[86:87], s[4:5], 0, v[180:181]
	s_mov_b32 m0, s26
	s_nop 0
	global_load_lds_dwordx4 v[86:87], off
	s_waitcnt lgkmcnt(8)
	s_barrier
	s_waitcnt lgkmcnt(6)
	s_setprio 1
	v_mfma_f32_16x16x32_f16 v[86:89], v[46:49], v[70:73], v[158:161]
	v_mfma_f32_16x16x32_f16 v[158:161], v[62:65], v[78:81], v[86:89]
	v_mfma_f32_16x16x32_f16 v[86:89], v[98:101], v[70:73], v[142:145]
	v_mfma_f32_16x16x32_f16 v[142:145], v[162:165], v[78:81], v[86:89]
	s_waitcnt lgkmcnt(4)
	v_mfma_f32_16x16x32_f16 v[86:89], v[46:49], v[90:93], v[150:153]
	v_mfma_f32_16x16x32_f16 v[150:153], v[62:65], v[114:117], v[86:89]
	v_mfma_f32_16x16x32_f16 v[86:89], v[98:101], v[90:93], v[134:137]
	v_mfma_f32_16x16x32_f16 v[134:137], v[162:165], v[114:117], v[86:89]
	s_waitcnt lgkmcnt(2)
	v_mfma_f32_16x16x32_f16 v[86:89], v[46:49], v[166:169], v[154:157]
	v_mfma_f32_16x16x32_f16 v[154:157], v[62:65], v[170:173], v[86:89]
	v_mfma_f32_16x16x32_f16 v[86:89], v[98:101], v[166:169], v[138:141]
	v_mfma_f32_16x16x32_f16 v[138:141], v[162:165], v[170:173], v[86:89]
	s_waitcnt lgkmcnt(0)
	v_mfma_f32_16x16x32_f16 v[86:89], v[46:49], v[174:177], v[146:149]
	v_mfma_f32_16x16x32_f16 v[146:149], v[62:65], v[208:211], v[86:89]
	v_mfma_f32_16x16x32_f16 v[86:89], v[98:101], v[174:177], v[130:133]
	v_mfma_f32_16x16x32_f16 v[130:133], v[162:165], v[208:211], v[86:89]
	s_setprio 0
	s_barrier
	s_add_i32 s18, 0, 0x1c000
	s_add_i32 s4, s38, s22
	v_add_u32_e32 v32, s18, v193
	s_nop 1
	v_lshl_add_u64 v[86:87], v[190:191], 0, s[84:85]
	s_mov_b32 m0, s4
	ds_read_b128 v[212:215], v32
	ds_read_b128 v[230:233], v32 offset:2048
	ds_read_b128 v[216:219], v32 offset:1024
	ds_read_b128 v[234:237], v32 offset:3072
	global_load_lds_dwordx4 v[86:87], off
	v_lshl_add_u64 v[86:87], v[238:239], 0, s[84:85]
	s_add_i32 m0, s4, 0x2000
	s_nop 0
	global_load_lds_dwordx4 v[86:87], off
	s_barrier
	s_waitcnt lgkmcnt(2)
	s_setprio 1
	v_mfma_f32_16x16x32_f16 v[86:89], v[212:215], v[70:73], v[94:97]
	v_mfma_f32_16x16x32_f16 v[16:19], v[230:233], v[70:73], v[16:19]
	s_waitcnt lgkmcnt(0)
	v_mfma_f32_16x16x32_f16 v[94:97], v[216:219], v[78:81], v[86:89]
	v_mfma_f32_16x16x32_f16 v[78:81], v[234:237], v[78:81], v[16:19]
	v_mfma_f32_16x16x32_f16 v[16:19], v[212:215], v[90:93], v[20:23]
	v_mfma_f32_16x16x32_f16 v[86:89], v[216:219], v[114:117], v[16:19]
	v_mfma_f32_16x16x32_f16 v[16:19], v[230:233], v[90:93], v[24:27]
	v_mfma_f32_16x16x32_f16 v[70:73], v[234:237], v[114:117], v[16:19]
	v_mfma_f32_16x16x32_f16 v[16:19], v[212:215], v[166:169], v[28:31]
	v_mfma_f32_16x16x32_f16 v[90:93], v[216:219], v[170:173], v[16:19]
	v_mfma_f32_16x16x32_f16 v[16:19], v[230:233], v[166:169], v[74:77]
	v_mfma_f32_16x16x32_f16 v[74:77], v[234:237], v[170:173], v[16:19]
	v_mfma_f32_16x16x32_f16 v[16:19], v[212:215], v[174:177], v[82:85]
	v_mfma_f32_16x16x32_f16 v[82:85], v[216:219], v[208:211], v[16:19]
	v_mfma_f32_16x16x32_f16 v[16:19], v[230:233], v[174:177], v[66:69]
	v_mfma_f32_16x16x32_f16 v[66:69], v[234:237], v[208:211], v[16:19]
	s_setprio 0
	s_mov_b32 m0, s28
	v_lshl_add_u64 v[114:115], v[240:241], 0, s[84:85]
	s_barrier
	s_nop 2
	ds_read_b128 v[16:19], v206 offset:49152
	ds_read_b128 v[20:23], v206 offset:50176
	ds_read_b128 v[24:27], v206 offset:51200
	ds_read_b128 v[28:31], v206 offset:52224
	ds_read_b128 v[166:169], v206 offset:53248
	ds_read_b128 v[174:177], v206 offset:55296
	ds_read_b128 v[170:173], v206 offset:54272
	ds_read_b128 v[208:211], v206 offset:56320
	global_load_lds_dwordx4 v[114:115], off
	v_lshl_add_u64 v[114:115], v[242:243], 0, s[84:85]
	s_mov_b32 m0, s29
	s_nop 0
	global_load_lds_dwordx4 v[114:115], off
	s_barrier
	s_waitcnt lgkmcnt(6)
	s_setprio 1
	v_mfma_f32_16x16x32_f16 v[114:117], v[46:49], v[16:19], v[126:129]
	v_mfma_f32_16x16x32_f16 v[126:129], v[62:65], v[20:23], v[114:117]
	s_waitcnt lgkmcnt(4)
	v_mfma_f32_16x16x32_f16 v[114:117], v[46:49], v[24:27], v[118:121]
	v_mfma_f32_16x16x32_f16 v[118:121], v[62:65], v[28:31], v[114:117]
	s_waitcnt lgkmcnt(2)
	v_mfma_f32_16x16x32_f16 v[114:117], v[46:49], v[166:169], v[122:125]
	v_mfma_f32_16x16x32_f16 v[0:3], v[46:49], v[174:177], v[0:3]
	v_mfma_f32_16x16x32_f16 v[110:113], v[98:101], v[16:19], v[110:113]
	v_mfma_f32_16x16x32_f16 v[102:105], v[98:101], v[24:27], v[102:105]
	s_waitcnt lgkmcnt(1)
	v_mfma_f32_16x16x32_f16 v[122:125], v[62:65], v[170:173], v[114:117]
	v_mfma_f32_16x16x32_f16 v[106:109], v[98:101], v[166:169], v[106:109]
	s_waitcnt lgkmcnt(0)
	v_mfma_f32_16x16x32_f16 v[114:117], v[62:65], v[208:211], v[0:3]
	v_mfma_f32_16x16x32_f16 v[0:3], v[98:101], v[174:177], v[4:7]
	v_mfma_f32_16x16x32_f16 v[110:113], v[162:165], v[20:23], v[110:113]
	v_mfma_f32_16x16x32_f16 v[102:105], v[162:165], v[28:31], v[102:105]
	v_mfma_f32_16x16x32_f16 v[106:109], v[162:165], v[170:173], v[106:109]
	v_mfma_f32_16x16x32_f16 v[98:101], v[162:165], v[208:211], v[0:3]
	s_setprio 0
	s_barrier
	s_add_u32 s4, s16, 0x40080
	s_addc_u32 s5, s17, 0
	s_add_i32 s16, s18, s22
	v_lshl_add_u64 v[0:1], s[4:5], 0, v[178:179]
	s_mov_b32 m0, s16
	s_nop 0
	global_load_lds_dwordx4 v[0:1], off
	v_lshl_add_u64 v[0:1], s[4:5], 0, v[180:181]
	s_add_i32 m0, s16, 0x2000
	s_nop 0
	global_load_lds_dwordx4 v[0:1], off
	s_waitcnt vmcnt(6)
	s_barrier
	s_setprio 1
	v_mfma_f32_16x16x32_f16 v[0:3], v[212:215], v[16:19], v[8:11]
	v_mfma_f32_16x16x32_f16 v[62:65], v[216:219], v[20:23], v[0:3]
	v_mfma_f32_16x16x32_f16 v[0:3], v[230:233], v[16:19], v[12:15]
	v_mfma_f32_16x16x32_f16 v[46:49], v[234:237], v[20:23], v[0:3]
	v_mfma_f32_16x16x32_f16 v[0:3], v[212:215], v[24:27], v[54:57]
	v_mfma_f32_16x16x32_f16 v[54:57], v[216:219], v[28:31], v[0:3]
	v_mfma_f32_16x16x32_f16 v[0:3], v[230:233], v[24:27], v[38:41]
	v_mfma_f32_16x16x32_f16 v[38:41], v[234:237], v[28:31], v[0:3]
	v_mfma_f32_16x16x32_f16 v[0:3], v[212:215], v[166:169], v[58:61]
	v_mfma_f32_16x16x32_f16 v[58:61], v[216:219], v[170:173], v[0:3]
	v_mfma_f32_16x16x32_f16 v[0:3], v[230:233], v[166:169], v[42:45]
	v_mfma_f32_16x16x32_f16 v[42:45], v[234:237], v[170:173], v[0:3]
	v_mfma_f32_16x16x32_f16 v[0:3], v[212:215], v[174:177], v[50:53]
	v_mfma_f32_16x16x32_f16 v[50:53], v[216:219], v[208:211], v[0:3]
	v_mfma_f32_16x16x32_f16 v[0:3], v[230:233], v[174:177], v[34:37]
	v_mfma_f32_16x16x32_f16 v[34:37], v[234:237], v[208:211], v[0:3]
	s_setprio 0
	s_add_i32 s37, s37, 2
	s_add_u32 s7, s7, 0x100
	s_addc_u32 s36, s36, 0
	s_cmp_gt_u32 s37, 13
	s_mov_b64 s[4:5], s[14:15]
	s_barrier
	s_cbranch_scc0 .LBB0_403
	s_lshl_b32 s7, s34, 8
	s_cmp_lt_i32 s35, 28
	s_mov_b64 s[4:5], -1
	s_cbranch_scc0 .LBB0_431
	s_add_i32 s16, s7, s27
	v_or_b32_e32 v207, s16, v192
	s_cmp_gt_i32 s35, 3
	s_cbranch_scc0 .LBB0_411
	s_add_i32 s4, s35, -12
	s_cmp_gt_u32 s4, 7
	s_mov_b64 s[4:5], -1
	s_cbranch_scc0 .LBB0_408
	s_lshl_b32 s4, s35, 8
	s_add_i32 s5, s4, 0xfffffc00
	s_cmp_lt_u32 s35, 12
	s_cselect_b32 s4, s4, s5
	v_and_b32_e32 v10, 7, v220
	v_and_b32_e32 v11, 8, v220
	v_cmp_ne_u32_e32 vcc, 0, v11
	v_and_b32_e32 v12, 0x60, v194
	v_lshlrev_b32_e32 v12, 1, v12
	v_lshl_or_b32 v12, v11, 2, v12
	v_and_b32_e32 v13, 0x18, v194
	v_or_b32_e32 v12, v12, v13
	v_or_b32_e32 v32, s4, v12
	v_or_b32_e32 v14, s16, v10
	v_mov_b64_e32 v[4:5], s[70:71]
	v_mad_i64_i32 v[0:1], s[4:5], v14, s33, v[4:5]
	v_lshlrev_b64 v[6:7], 1, v[32:33]
	v_lshl_add_u64 v[16:17], v[0:1], 0, v[6:7]
	v_mov_b32_e32 v32, 0x30000
	v_lshl_add_u64 v[18:19], v[16:17], 0, v[32:33]
	v_lshl_add_u64 v[20:21], v[18:19], 0, v[32:33]
	v_lshl_add_u64 v[22:23], v[20:21], 0, v[32:33]
	v_mov_b32_e32 v8, 0x180000
	v_mov_b32_e32 v9, 0
	v_lshl_add_u64 v[24:25], v[16:17], 0, v[8:9]
	v_lshl_add_u64 v[26:27], v[24:25], 0, v[32:33]
	v_lshl_add_u64 v[28:29], v[26:27], 0, v[32:33]
	v_lshl_add_u64 v[30:31], v[28:29], 0, v[32:33]
	v_mov_b32_e32 v8, 0x18000
	v_cvt_pk_f16_f32 v158, v158, v159
	v_cvt_pk_f16_f32 v159, v160, v161
	v_cvt_pk_f16_f32 v160, v142, v143
	v_cvt_pk_f16_f32 v161, v144, v145
	v_cvt_pk_f16_f32 v94, v94, v95
	v_cvt_pk_f16_f32 v95, v96, v97
	v_cvt_pk_f16_f32 v96, v78, v79
	v_cvt_pk_f16_f32 v97, v80, v81
	v_mov_b32_dpp v0, v158 row_ror:8 row_mask:0xf bank_mask:0xf
	v_mov_b32_dpp v1, v159 row_ror:8 row_mask:0xf bank_mask:0xf
	v_mov_b32_dpp v2, v160 row_ror:8 row_mask:0xf bank_mask:0xf
	v_mov_b32_dpp v3, v161 row_ror:8 row_mask:0xf bank_mask:0xf
	v_mov_b32_dpp v4, v94 row_ror:8 row_mask:0xf bank_mask:0xf
	v_mov_b32_dpp v5, v95 row_ror:8 row_mask:0xf bank_mask:0xf
	v_mov_b32_dpp v6, v96 row_ror:8 row_mask:0xf bank_mask:0xf
	v_mov_b32_dpp v7, v97 row_ror:8 row_mask:0xf bank_mask:0xf
	v_cndmask_b32_e32 v158, v158, v4, vcc
	v_cndmask_b32_e32 v159, v159, v5, vcc
	v_cndmask_b32_e32 v160, v160, v6, vcc
	v_cndmask_b32_e32 v161, v161, v7, vcc
	v_cndmask_b32_e32 v94, v0, v94, vcc
	v_cndmask_b32_e32 v95, v1, v95, vcc
	v_cndmask_b32_e32 v96, v2, v96, vcc
	v_cndmask_b32_e32 v97, v3, v97, vcc
	v_lshl_add_u64 v[10:11], v[16:17], 0, v[8:9]
	global_store_dwordx4 v[16:17], v[158:161], off
	global_store_dwordx4 v[10:11], v[94:97], off
	v_cvt_pk_f16_f32 v150, v150, v151
	v_cvt_pk_f16_f32 v151, v152, v153
	v_cvt_pk_f16_f32 v152, v134, v135
	v_cvt_pk_f16_f32 v153, v136, v137
	v_cvt_pk_f16_f32 v86, v86, v87
	v_cvt_pk_f16_f32 v87, v88, v89
	v_cvt_pk_f16_f32 v88, v70, v71
	v_cvt_pk_f16_f32 v89, v72, v73
	v_mov_b32_dpp v0, v150 row_ror:8 row_mask:0xf bank_mask:0xf
	v_mov_b32_dpp v1, v151 row_ror:8 row_mask:0xf bank_mask:0xf
	v_mov_b32_dpp v2, v152 row_ror:8 row_mask:0xf bank_mask:0xf
	v_mov_b32_dpp v3, v153 row_ror:8 row_mask:0xf bank_mask:0xf
	v_mov_b32_dpp v4, v86 row_ror:8 row_mask:0xf bank_mask:0xf
	v_mov_b32_dpp v5, v87 row_ror:8 row_mask:0xf bank_mask:0xf
	v_mov_b32_dpp v6, v88 row_ror:8 row_mask:0xf bank_mask:0xf
	v_mov_b32_dpp v7, v89 row_ror:8 row_mask:0xf bank_mask:0xf
	v_cndmask_b32_e32 v150, v150, v4, vcc
	v_cndmask_b32_e32 v151, v151, v5, vcc
	v_cndmask_b32_e32 v152, v152, v6, vcc
	v_cndmask_b32_e32 v153, v153, v7, vcc
	v_cndmask_b32_e32 v86, v0, v86, vcc
	v_cndmask_b32_e32 v87, v1, v87, vcc
	v_cndmask_b32_e32 v88, v2, v88, vcc
	v_cndmask_b32_e32 v89, v3, v89, vcc
	v_lshl_add_u64 v[10:11], v[18:19], 0, v[8:9]
	global_store_dwordx4 v[18:19], v[150:153], off
	global_store_dwordx4 v[10:11], v[86:89], off
	v_cvt_pk_f16_f32 v154, v154, v155
	v_cvt_pk_f16_f32 v155, v156, v157
	v_cvt_pk_f16_f32 v156, v138, v139
	v_cvt_pk_f16_f32 v157, v140, v141
	v_cvt_pk_f16_f32 v90, v90, v91
	v_cvt_pk_f16_f32 v91, v92, v93
	v_cvt_pk_f16_f32 v92, v74, v75
	v_cvt_pk_f16_f32 v93, v76, v77
	v_mov_b32_dpp v0, v154 row_ror:8 row_mask:0xf bank_mask:0xf
	v_mov_b32_dpp v1, v155 row_ror:8 row_mask:0xf bank_mask:0xf
	v_mov_b32_dpp v2, v156 row_ror:8 row_mask:0xf bank_mask:0xf
	v_mov_b32_dpp v3, v157 row_ror:8 row_mask:0xf bank_mask:0xf
	v_mov_b32_dpp v4, v90 row_ror:8 row_mask:0xf bank_mask:0xf
	v_mov_b32_dpp v5, v91 row_ror:8 row_mask:0xf bank_mask:0xf
	v_mov_b32_dpp v6, v92 row_ror:8 row_mask:0xf bank_mask:0xf
	v_mov_b32_dpp v7, v93 row_ror:8 row_mask:0xf bank_mask:0xf
	v_cndmask_b32_e32 v154, v154, v4, vcc
	v_cndmask_b32_e32 v155, v155, v5, vcc
	v_cndmask_b32_e32 v156, v156, v6, vcc
	v_cndmask_b32_e32 v157, v157, v7, vcc
	v_cndmask_b32_e32 v90, v0, v90, vcc
	v_cndmask_b32_e32 v91, v1, v91, vcc
	v_cndmask_b32_e32 v92, v2, v92, vcc
	v_cndmask_b32_e32 v93, v3, v93, vcc
	v_lshl_add_u64 v[10:11], v[20:21], 0, v[8:9]
	global_store_dwordx4 v[20:21], v[154:157], off
	global_store_dwordx4 v[10:11], v[90:93], off
	v_cvt_pk_f16_f32 v146, v146, v147
	v_cvt_pk_f16_f32 v147, v148, v149
	v_cvt_pk_f16_f32 v148, v130, v131
	v_cvt_pk_f16_f32 v149, v132, v133
	v_cvt_pk_f16_f32 v82, v82, v83
	v_cvt_pk_f16_f32 v83, v84, v85
	v_cvt_pk_f16_f32 v84, v66, v67
	v_cvt_pk_f16_f32 v85, v68, v69
	v_mov_b32_dpp v0, v146 row_ror:8 row_mask:0xf bank_mask:0xf
	v_mov_b32_dpp v1, v147 row_ror:8 row_mask:0xf bank_mask:0xf
	v_mov_b32_dpp v2, v148 row_ror:8 row_mask:0xf bank_mask:0xf
	v_mov_b32_dpp v3, v149 row_ror:8 row_mask:0xf bank_mask:0xf
	v_mov_b32_dpp v4, v82 row_ror:8 row_mask:0xf bank_mask:0xf
	v_mov_b32_dpp v5, v83 row_ror:8 row_mask:0xf bank_mask:0xf
	v_mov_b32_dpp v6, v84 row_ror:8 row_mask:0xf bank_mask:0xf
	v_mov_b32_dpp v7, v85 row_ror:8 row_mask:0xf bank_mask:0xf
	v_cndmask_b32_e32 v146, v146, v4, vcc
	v_cndmask_b32_e32 v147, v147, v5, vcc
	v_cndmask_b32_e32 v148, v148, v6, vcc
	v_cndmask_b32_e32 v149, v149, v7, vcc
	v_cndmask_b32_e32 v82, v0, v82, vcc
	v_cndmask_b32_e32 v83, v1, v83, vcc
	v_cndmask_b32_e32 v84, v2, v84, vcc
	v_cndmask_b32_e32 v85, v3, v85, vcc
	v_lshl_add_u64 v[10:11], v[22:23], 0, v[8:9]
	global_store_dwordx4 v[22:23], v[146:149], off
	global_store_dwordx4 v[10:11], v[82:85], off
	v_cvt_pk_f16_f32 v126, v126, v127
	v_cvt_pk_f16_f32 v127, v128, v129
	v_cvt_pk_f16_f32 v128, v110, v111
	v_cvt_pk_f16_f32 v129, v112, v113
	v_cvt_pk_f16_f32 v62, v62, v63
	v_cvt_pk_f16_f32 v63, v64, v65
	v_cvt_pk_f16_f32 v64, v46, v47
	v_cvt_pk_f16_f32 v65, v48, v49
	v_mov_b32_dpp v0, v126 row_ror:8 row_mask:0xf bank_mask:0xf
	v_mov_b32_dpp v1, v127 row_ror:8 row_mask:0xf bank_mask:0xf
	v_mov_b32_dpp v2, v128 row_ror:8 row_mask:0xf bank_mask:0xf
	v_mov_b32_dpp v3, v129 row_ror:8 row_mask:0xf bank_mask:0xf
	v_mov_b32_dpp v4, v62 row_ror:8 row_mask:0xf bank_mask:0xf
	v_mov_b32_dpp v5, v63 row_ror:8 row_mask:0xf bank_mask:0xf
	v_mov_b32_dpp v6, v64 row_ror:8 row_mask:0xf bank_mask:0xf
	v_mov_b32_dpp v7, v65 row_ror:8 row_mask:0xf bank_mask:0xf
	v_cndmask_b32_e32 v126, v126, v4, vcc
	v_cndmask_b32_e32 v127, v127, v5, vcc
	v_cndmask_b32_e32 v128, v128, v6, vcc
	v_cndmask_b32_e32 v129, v129, v7, vcc
	v_cndmask_b32_e32 v62, v0, v62, vcc
	v_cndmask_b32_e32 v63, v1, v63, vcc
	v_cndmask_b32_e32 v64, v2, v64, vcc
	v_cndmask_b32_e32 v65, v3, v65, vcc
	v_lshl_add_u64 v[10:11], v[24:25], 0, v[8:9]
	global_store_dwordx4 v[24:25], v[126:129], off
	global_store_dwordx4 v[10:11], v[62:65], off
	v_cvt_pk_f16_f32 v118, v118, v119
	v_cvt_pk_f16_f32 v119, v120, v121
	v_cvt_pk_f16_f32 v120, v102, v103
	v_cvt_pk_f16_f32 v121, v104, v105
	v_cvt_pk_f16_f32 v54, v54, v55
	v_cvt_pk_f16_f32 v55, v56, v57
	v_cvt_pk_f16_f32 v56, v38, v39
	v_cvt_pk_f16_f32 v57, v40, v41
	v_mov_b32_dpp v0, v118 row_ror:8 row_mask:0xf bank_mask:0xf
	v_mov_b32_dpp v1, v119 row_ror:8 row_mask:0xf bank_mask:0xf
	v_mov_b32_dpp v2, v120 row_ror:8 row_mask:0xf bank_mask:0xf
	v_mov_b32_dpp v3, v121 row_ror:8 row_mask:0xf bank_mask:0xf
	v_mov_b32_dpp v4, v54 row_ror:8 row_mask:0xf bank_mask:0xf
	v_mov_b32_dpp v5, v55 row_ror:8 row_mask:0xf bank_mask:0xf
	v_mov_b32_dpp v6, v56 row_ror:8 row_mask:0xf bank_mask:0xf
	v_mov_b32_dpp v7, v57 row_ror:8 row_mask:0xf bank_mask:0xf
	v_cndmask_b32_e32 v118, v118, v4, vcc
	v_cndmask_b32_e32 v119, v119, v5, vcc
	v_cndmask_b32_e32 v120, v120, v6, vcc
	v_cndmask_b32_e32 v121, v121, v7, vcc
	v_cndmask_b32_e32 v54, v0, v54, vcc
	v_cndmask_b32_e32 v55, v1, v55, vcc
	v_cndmask_b32_e32 v56, v2, v56, vcc
	v_cndmask_b32_e32 v57, v3, v57, vcc
	v_lshl_add_u64 v[10:11], v[26:27], 0, v[8:9]
	global_store_dwordx4 v[26:27], v[118:121], off
	global_store_dwordx4 v[10:11], v[54:57], off
	v_cvt_pk_f16_f32 v122, v122, v123
	v_cvt_pk_f16_f32 v123, v124, v125
	v_cvt_pk_f16_f32 v124, v106, v107
	v_cvt_pk_f16_f32 v125, v108, v109
	v_cvt_pk_f16_f32 v58, v58, v59
	v_cvt_pk_f16_f32 v59, v60, v61
	v_cvt_pk_f16_f32 v60, v42, v43
	v_cvt_pk_f16_f32 v61, v44, v45
	v_mov_b32_dpp v0, v122 row_ror:8 row_mask:0xf bank_mask:0xf
	v_mov_b32_dpp v1, v123 row_ror:8 row_mask:0xf bank_mask:0xf
	v_mov_b32_dpp v2, v124 row_ror:8 row_mask:0xf bank_mask:0xf
	v_mov_b32_dpp v3, v125 row_ror:8 row_mask:0xf bank_mask:0xf
	v_mov_b32_dpp v4, v58 row_ror:8 row_mask:0xf bank_mask:0xf
	v_mov_b32_dpp v5, v59 row_ror:8 row_mask:0xf bank_mask:0xf
	v_mov_b32_dpp v6, v60 row_ror:8 row_mask:0xf bank_mask:0xf
	v_mov_b32_dpp v7, v61 row_ror:8 row_mask:0xf bank_mask:0xf
	v_cndmask_b32_e32 v122, v122, v4, vcc
	v_cndmask_b32_e32 v123, v123, v5, vcc
	v_cndmask_b32_e32 v124, v124, v6, vcc
	v_cndmask_b32_e32 v125, v125, v7, vcc
	v_cndmask_b32_e32 v58, v0, v58, vcc
	v_cndmask_b32_e32 v59, v1, v59, vcc
	v_cndmask_b32_e32 v60, v2, v60, vcc
	v_cndmask_b32_e32 v61, v3, v61, vcc
	v_lshl_add_u64 v[10:11], v[28:29], 0, v[8:9]
	global_store_dwordx4 v[28:29], v[122:125], off
	global_store_dwordx4 v[10:11], v[58:61], off
	v_cvt_pk_f16_f32 v114, v114, v115
	v_cvt_pk_f16_f32 v115, v116, v117
	v_cvt_pk_f16_f32 v116, v98, v99
	v_cvt_pk_f16_f32 v117, v100, v101
	v_cvt_pk_f16_f32 v50, v50, v51
	v_cvt_pk_f16_f32 v51, v52, v53
	v_cvt_pk_f16_f32 v52, v34, v35
	v_cvt_pk_f16_f32 v53, v36, v37
	v_mov_b32_dpp v0, v114 row_ror:8 row_mask:0xf bank_mask:0xf
	v_mov_b32_dpp v1, v115 row_ror:8 row_mask:0xf bank_mask:0xf
	v_mov_b32_dpp v2, v116 row_ror:8 row_mask:0xf bank_mask:0xf
	v_mov_b32_dpp v3, v117 row_ror:8 row_mask:0xf bank_mask:0xf
	v_mov_b32_dpp v4, v50 row_ror:8 row_mask:0xf bank_mask:0xf
	v_mov_b32_dpp v5, v51 row_ror:8 row_mask:0xf bank_mask:0xf
	v_mov_b32_dpp v6, v52 row_ror:8 row_mask:0xf bank_mask:0xf
	v_mov_b32_dpp v7, v53 row_ror:8 row_mask:0xf bank_mask:0xf
	v_cndmask_b32_e32 v114, v114, v4, vcc
	v_cndmask_b32_e32 v115, v115, v5, vcc
	v_cndmask_b32_e32 v116, v116, v6, vcc
	v_cndmask_b32_e32 v117, v117, v7, vcc
	v_cndmask_b32_e32 v50, v0, v50, vcc
	v_cndmask_b32_e32 v51, v1, v51, vcc
	v_cndmask_b32_e32 v52, v2, v52, vcc
	v_cndmask_b32_e32 v53, v3, v53, vcc
	v_lshl_add_u64 v[10:11], v[30:31], 0, v[8:9]
	global_store_dwordx4 v[30:31], v[114:117], off
	global_store_dwordx4 v[10:11], v[50:53], off
	s_mov_b64 s[4:5], 0

.LBB0_940:
	s_add_u32 s20, s14, 0x100
	s_addc_u32 s21, s15, 0
	s_add_i32 s40, 0, 0x10000
	v_add_u32_e32 v32, s40, v209
	ds_read_b128 v[132:135], v32
	ds_read_b128 v[140:143], v32 offset:2048
	ds_read_b128 v[136:139], v32 offset:1024
	ds_read_b128 v[144:147], v32 offset:3072
	s_cmp_eq_u32 s11, 12
	s_cselect_b32 s25, s17, s21
	s_cselect_b32 s24, s16, s20
	s_cselect_b32 s23, s19, s3
	s_cselect_b32 s22, s18, s1
	v_lshl_add_u64 v[34:35], s[14:15], 0, v[200:201]
	s_add_i32 m0, s30, 0xc000
	ds_read_b128 v[148:151], v211
	ds_read_b128 v[156:159], v211 offset:2048
	ds_read_b128 v[164:167], v211 offset:4096
	ds_read_b128 v[172:175], v211 offset:6144
	ds_read_b128 v[152:155], v211 offset:1024
	ds_read_b128 v[160:163], v211 offset:3072
	ds_read_b128 v[168:171], v211 offset:5120
	ds_read_b128 v[176:179], v211 offset:7168
	global_load_lds_dwordx4 v[34:35], off
	v_lshl_add_u64 v[34:35], s[14:15], 0, v[202:203]
	s_add_i32 m0, s30, 0xe000
	s_nop 0
	global_load_lds_dwordx4 v[34:35], off
	s_waitcnt lgkmcnt(8)
	s_barrier
	s_waitcnt lgkmcnt(7)
	s_setprio 1
	v_mfma_f32_16x16x32_f16 v[128:131], v[132:135], v[148:151], v[128:131]
	v_mfma_f32_16x16x32_f16 v[124:127], v[140:143], v[148:151], v[124:127]
	s_waitcnt lgkmcnt(6)
	v_mfma_f32_16x16x32_f16 v[120:123], v[132:135], v[156:159], v[120:123]
	v_mfma_f32_16x16x32_f16 v[116:119], v[140:143], v[156:159], v[116:119]
	s_waitcnt lgkmcnt(5)
	v_mfma_f32_16x16x32_f16 v[112:115], v[132:135], v[164:167], v[112:115]
	v_mfma_f32_16x16x32_f16 v[108:111], v[140:143], v[164:167], v[108:111]
	s_waitcnt lgkmcnt(4)
	v_mfma_f32_16x16x32_f16 v[104:107], v[132:135], v[172:175], v[104:107]
	v_mfma_f32_16x16x32_f16 v[100:103], v[140:143], v[172:175], v[100:103]
	s_waitcnt lgkmcnt(3)
	v_mfma_f32_16x16x32_f16 v[128:131], v[136:139], v[152:155], v[128:131]
	v_mfma_f32_16x16x32_f16 v[124:127], v[144:147], v[152:155], v[124:127]
	s_waitcnt lgkmcnt(2)
	v_mfma_f32_16x16x32_f16 v[120:123], v[136:139], v[160:163], v[120:123]
	v_mfma_f32_16x16x32_f16 v[116:119], v[144:147], v[160:163], v[116:119]
	s_waitcnt lgkmcnt(1)
	v_mfma_f32_16x16x32_f16 v[112:115], v[136:139], v[168:171], v[112:115]
	v_mfma_f32_16x16x32_f16 v[108:111], v[144:147], v[168:171], v[108:111]
	s_waitcnt lgkmcnt(0)
	v_mfma_f32_16x16x32_f16 v[104:107], v[136:139], v[176:179], v[104:107]
	v_mfma_f32_16x16x32_f16 v[100:103], v[144:147], v[176:179], v[100:103]
	s_setprio 0
	s_barrier
	s_add_i32 s41, 0, 0x14000
	s_add_i32 s14, s40, s29
	v_add_u32_e32 v32, s41, v209
	v_lshl_add_u64 v[204:205], s[22:23], 0, v[196:197]
	s_mov_b32 m0, s14
	ds_read_b128 v[180:183], v32
	ds_read_b128 v[188:191], v32 offset:2048
	ds_read_b128 v[184:187], v32 offset:1024
	ds_read_b128 v[192:195], v32 offset:3072
	global_load_lds_dwordx4 v[204:205], off
	v_lshl_add_u64 v[206:207], s[22:23], 0, v[198:199]
	s_add_i32 m0, s14, 0x2000
	s_nop 0
	global_load_lds_dwordx4 v[206:207], off
	s_barrier
	s_waitcnt lgkmcnt(2)
	s_setprio 1
	v_mfma_f32_16x16x32_f16 v[96:99], v[180:183], v[148:151], v[96:99]
	v_mfma_f32_16x16x32_f16 v[92:95], v[188:191], v[148:151], v[92:95]
	v_mfma_f32_16x16x32_f16 v[88:91], v[180:183], v[156:159], v[88:91]
	v_mfma_f32_16x16x32_f16 v[84:87], v[188:191], v[156:159], v[84:87]
	v_mfma_f32_16x16x32_f16 v[80:83], v[180:183], v[164:167], v[80:83]
	v_mfma_f32_16x16x32_f16 v[76:79], v[188:191], v[164:167], v[76:79]
	v_mfma_f32_16x16x32_f16 v[72:75], v[180:183], v[172:175], v[72:75]
	v_mfma_f32_16x16x32_f16 v[68:71], v[188:191], v[172:175], v[68:71]
	s_waitcnt lgkmcnt(0)
	v_mfma_f32_16x16x32_f16 v[96:99], v[184:187], v[152:155], v[96:99]
	v_mfma_f32_16x16x32_f16 v[92:95], v[192:195], v[152:155], v[92:95]
	v_mfma_f32_16x16x32_f16 v[88:91], v[184:187], v[160:163], v[88:91]
	v_mfma_f32_16x16x32_f16 v[84:87], v[192:195], v[160:163], v[84:87]
	v_mfma_f32_16x16x32_f16 v[80:83], v[184:187], v[168:171], v[80:83]
	v_mfma_f32_16x16x32_f16 v[76:79], v[192:195], v[168:171], v[76:79]
	v_mfma_f32_16x16x32_f16 v[72:75], v[184:187], v[176:179], v[72:75]
	v_mfma_f32_16x16x32_f16 v[68:71], v[192:195], v[176:179], v[68:71]
	s_setprio 0
	s_mov_b32 m0, s30
	v_lshl_add_u64 v[212:213], s[24:25], 0, v[196:197]
	s_barrier
	ds_read_b128 v[148:151], v211 offset:16384
	ds_read_b128 v[156:159], v211 offset:18432
	ds_read_b128 v[164:167], v211 offset:20480
	ds_read_b128 v[172:175], v211 offset:22528
	ds_read_b128 v[152:155], v211 offset:17408
	ds_read_b128 v[160:163], v211 offset:19456
	ds_read_b128 v[168:171], v211 offset:21504
	ds_read_b128 v[176:179], v211 offset:23552
	global_load_lds_dwordx4 v[212:213], off
	v_lshl_add_u64 v[214:215], s[24:25], 0, v[198:199]
	s_mov_b32 m0, s31
	s_nop 0
	global_load_lds_dwordx4 v[214:215], off
	s_barrier
	s_waitcnt lgkmcnt(7)
	s_setprio 1
	v_mfma_f32_16x16x32_f16 v[64:67], v[132:135], v[148:151], v[64:67]
	v_mfma_f32_16x16x32_f16 v[60:63], v[140:143], v[148:151], v[60:63]
	s_waitcnt lgkmcnt(6)
	v_mfma_f32_16x16x32_f16 v[56:59], v[132:135], v[156:159], v[56:59]
	v_mfma_f32_16x16x32_f16 v[52:55], v[140:143], v[156:159], v[52:55]
	s_waitcnt lgkmcnt(5)
	v_mfma_f32_16x16x32_f16 v[48:51], v[132:135], v[164:167], v[48:51]
	v_mfma_f32_16x16x32_f16 v[44:47], v[140:143], v[164:167], v[44:47]
	s_waitcnt lgkmcnt(4)
	v_mfma_f32_16x16x32_f16 v[40:43], v[132:135], v[172:175], v[40:43]
	v_mfma_f32_16x16x32_f16 v[34:37], v[140:143], v[172:175], v[36:39]
	s_waitcnt lgkmcnt(3)
	v_mfma_f32_16x16x32_f16 v[64:67], v[136:139], v[152:155], v[64:67]
	v_mfma_f32_16x16x32_f16 v[60:63], v[144:147], v[152:155], v[60:63]
	s_waitcnt lgkmcnt(2)
	v_mfma_f32_16x16x32_f16 v[56:59], v[136:139], v[160:163], v[56:59]
	v_mfma_f32_16x16x32_f16 v[52:55], v[144:147], v[160:163], v[52:55]
	s_waitcnt lgkmcnt(1)
	v_mfma_f32_16x16x32_f16 v[48:51], v[136:139], v[168:171], v[48:51]
	v_mfma_f32_16x16x32_f16 v[44:47], v[144:147], v[168:171], v[44:47]
	s_waitcnt lgkmcnt(0)
	v_mfma_f32_16x16x32_f16 v[40:43], v[136:139], v[176:179], v[40:43]
	v_mfma_f32_16x16x32_f16 v[34:37], v[144:147], v[176:179], v[34:37]
	s_setprio 0
	s_barrier
	s_add_u32 s14, s22, 0x40000
	s_addc_u32 s15, s23, 0
	s_add_i32 s40, s41, s29
	v_lshl_add_u64 v[38:39], s[14:15], 0, v[196:197]
	s_mov_b32 m0, s40
	s_nop 0
	global_load_lds_dwordx4 v[38:39], off
	v_lshl_add_u64 v[38:39], s[14:15], 0, v[198:199]
	s_add_i32 m0, s40, 0x2000
	s_nop 0
	global_load_lds_dwordx4 v[38:39], off
	s_waitcnt vmcnt(6)
	s_barrier
	s_setprio 1
	v_mfma_f32_16x16x32_f16 v[28:31], v[180:183], v[148:151], v[28:31]
	v_mfma_f32_16x16x32_f16 v[24:27], v[188:191], v[148:151], v[24:27]
	v_mfma_f32_16x16x32_f16 v[20:23], v[180:183], v[156:159], v[20:23]
	v_mfma_f32_16x16x32_f16 v[16:19], v[188:191], v[156:159], v[16:19]
	v_mfma_f32_16x16x32_f16 v[12:15], v[180:183], v[164:167], v[12:15]
	v_mfma_f32_16x16x32_f16 v[8:11], v[188:191], v[164:167], v[8:11]
	v_mfma_f32_16x16x32_f16 v[4:7], v[180:183], v[172:175], v[4:7]
	v_mfma_f32_16x16x32_f16 v[0:3], v[188:191], v[172:175], v[0:3]
	v_mfma_f32_16x16x32_f16 v[28:31], v[184:187], v[152:155], v[28:31]
	v_mfma_f32_16x16x32_f16 v[24:27], v[192:195], v[152:155], v[24:27]
	v_mfma_f32_16x16x32_f16 v[20:23], v[184:187], v[160:163], v[20:23]
	v_mfma_f32_16x16x32_f16 v[16:19], v[192:195], v[160:163], v[16:19]
	v_mfma_f32_16x16x32_f16 v[12:15], v[184:187], v[168:171], v[12:15]
	v_mfma_f32_16x16x32_f16 v[8:11], v[192:195], v[168:171], v[8:11]
	v_mfma_f32_16x16x32_f16 v[4:7], v[184:187], v[176:179], v[4:7]
	v_mfma_f32_16x16x32_f16 v[0:3], v[192:195], v[176:179], v[0:3]
	s_setprio 0
	s_add_i32 s40, 0, 0x18000
	v_add_u32_e32 v32, s40, v209
	s_barrier
	ds_read_b128 v[132:135], v32
	ds_read_b128 v[140:143], v32 offset:2048
	ds_read_b128 v[136:139], v32 offset:1024
	ds_read_b128 v[144:147], v32 offset:3072
	s_add_u32 s14, s24, 0x40000
	s_addc_u32 s15, s25, 0
	s_mov_b32 m0, s34
	v_lshl_add_u64 v[38:39], s[14:15], 0, v[196:197]
	ds_read_b128 v[148:151], v211 offset:32768
	ds_read_b128 v[156:159], v211 offset:34816
	ds_read_b128 v[164:167], v211 offset:36864
	ds_read_b128 v[172:175], v211 offset:38912
	ds_read_b128 v[152:155], v211 offset:33792
	ds_read_b128 v[160:163], v211 offset:35840
	ds_read_b128 v[168:171], v211 offset:37888
	ds_read_b128 v[176:179], v211 offset:39936
	global_load_lds_dwordx4 v[38:39], off
	v_lshl_add_u64 v[38:39], s[14:15], 0, v[198:199]
	s_mov_b32 m0, s35
	s_nop 0
	global_load_lds_dwordx4 v[38:39], off
	s_waitcnt lgkmcnt(8)
	s_barrier
	s_waitcnt lgkmcnt(7)
	s_setprio 1
	v_mfma_f32_16x16x32_f16 v[128:131], v[132:135], v[148:151], v[128:131]
	v_mfma_f32_16x16x32_f16 v[124:127], v[140:143], v[148:151], v[124:127]
	s_waitcnt lgkmcnt(6)
	v_mfma_f32_16x16x32_f16 v[120:123], v[132:135], v[156:159], v[120:123]
	v_mfma_f32_16x16x32_f16 v[116:119], v[140:143], v[156:159], v[116:119]
	s_waitcnt lgkmcnt(5)
	v_mfma_f32_16x16x32_f16 v[112:115], v[132:135], v[164:167], v[112:115]
	v_mfma_f32_16x16x32_f16 v[108:111], v[140:143], v[164:167], v[108:111]
	s_waitcnt lgkmcnt(4)
	v_mfma_f32_16x16x32_f16 v[104:107], v[132:135], v[172:175], v[104:107]
	v_mfma_f32_16x16x32_f16 v[100:103], v[140:143], v[172:175], v[100:103]
	s_waitcnt lgkmcnt(3)
	v_mfma_f32_16x16x32_f16 v[128:131], v[136:139], v[152:155], v[128:131]
	v_mfma_f32_16x16x32_f16 v[124:127], v[144:147], v[152:155], v[124:127]
	s_waitcnt lgkmcnt(2)
	v_mfma_f32_16x16x32_f16 v[120:123], v[136:139], v[160:163], v[120:123]
	v_mfma_f32_16x16x32_f16 v[116:119], v[144:147], v[160:163], v[116:119]
	s_waitcnt lgkmcnt(1)
	v_mfma_f32_16x16x32_f16 v[112:115], v[136:139], v[168:171], v[112:115]
	v_mfma_f32_16x16x32_f16 v[108:111], v[144:147], v[168:171], v[108:111]
	s_waitcnt lgkmcnt(0)
	v_mfma_f32_16x16x32_f16 v[104:107], v[136:139], v[176:179], v[104:107]
	v_mfma_f32_16x16x32_f16 v[100:103], v[144:147], v[176:179], v[100:103]
	s_setprio 0
	s_barrier
	s_add_i32 s24, 0, 0x1c000
	s_add_i32 s14, s40, s29
	v_add_u32_e32 v32, s24, v209
	v_lshl_add_u64 v[38:39], v[204:205], 0, s[84:85]
	s_mov_b32 m0, s14
	ds_read_b128 v[180:183], v32
	ds_read_b128 v[188:191], v32 offset:2048
	ds_read_b128 v[184:187], v32 offset:1024
	ds_read_b128 v[192:195], v32 offset:3072
	global_load_lds_dwordx4 v[38:39], off
	v_lshl_add_u64 v[38:39], v[206:207], 0, s[84:85]
	s_add_i32 m0, s14, 0x2000
	s_nop 0
	global_load_lds_dwordx4 v[38:39], off
	s_barrier
	s_waitcnt lgkmcnt(2)
	s_setprio 1
	v_mfma_f32_16x16x32_f16 v[96:99], v[180:183], v[148:151], v[96:99]
	v_mfma_f32_16x16x32_f16 v[92:95], v[188:191], v[148:151], v[92:95]
	v_mfma_f32_16x16x32_f16 v[88:91], v[180:183], v[156:159], v[88:91]
	v_mfma_f32_16x16x32_f16 v[84:87], v[188:191], v[156:159], v[84:87]
	v_mfma_f32_16x16x32_f16 v[80:83], v[180:183], v[164:167], v[80:83]
	v_mfma_f32_16x16x32_f16 v[76:79], v[188:191], v[164:167], v[76:79]
	v_mfma_f32_16x16x32_f16 v[72:75], v[180:183], v[172:175], v[72:75]
	v_mfma_f32_16x16x32_f16 v[68:71], v[188:191], v[172:175], v[68:71]
	s_waitcnt lgkmcnt(0)
	v_mfma_f32_16x16x32_f16 v[96:99], v[184:187], v[152:155], v[96:99]
	v_mfma_f32_16x16x32_f16 v[92:95], v[192:195], v[152:155], v[92:95]
	v_mfma_f32_16x16x32_f16 v[88:91], v[184:187], v[160:163], v[88:91]
	v_mfma_f32_16x16x32_f16 v[84:87], v[192:195], v[160:163], v[84:87]
	v_mfma_f32_16x16x32_f16 v[80:83], v[184:187], v[168:171], v[80:83]
	v_mfma_f32_16x16x32_f16 v[76:79], v[192:195], v[168:171], v[76:79]
	v_mfma_f32_16x16x32_f16 v[72:75], v[184:187], v[176:179], v[72:75]
	v_mfma_f32_16x16x32_f16 v[68:71], v[192:195], v[176:179], v[68:71]
	s_setprio 0
	s_mov_b32 m0, s36
	v_lshl_add_u64 v[38:39], v[212:213], 0, s[84:85]
	s_barrier
	ds_read_b128 v[148:151], v211 offset:49152
	ds_read_b128 v[156:159], v211 offset:51200
	ds_read_b128 v[164:167], v211 offset:53248
	ds_read_b128 v[172:175], v211 offset:55296
	ds_read_b128 v[152:155], v211 offset:50176
	ds_read_b128 v[160:163], v211 offset:52224
	ds_read_b128 v[168:171], v211 offset:54272
	ds_read_b128 v[176:179], v211 offset:56320
	global_load_lds_dwordx4 v[38:39], off
	v_lshl_add_u64 v[38:39], v[214:215], 0, s[84:85]
	s_mov_b32 m0, s37
	s_nop 0
	global_load_lds_dwordx4 v[38:39], off
	s_barrier
	s_waitcnt lgkmcnt(7)
	s_setprio 1
	v_mfma_f32_16x16x32_f16 v[64:67], v[132:135], v[148:151], v[64:67]
	v_mfma_f32_16x16x32_f16 v[60:63], v[140:143], v[148:151], v[60:63]
	s_waitcnt lgkmcnt(6)
	v_mfma_f32_16x16x32_f16 v[56:59], v[132:135], v[156:159], v[56:59]
	v_mfma_f32_16x16x32_f16 v[52:55], v[140:143], v[156:159], v[52:55]
	s_waitcnt lgkmcnt(5)
	v_mfma_f32_16x16x32_f16 v[48:51], v[132:135], v[164:167], v[48:51]
	v_mfma_f32_16x16x32_f16 v[44:47], v[140:143], v[164:167], v[44:47]
	s_waitcnt lgkmcnt(4)
	v_mfma_f32_16x16x32_f16 v[38:41], v[132:135], v[172:175], v[40:43]
	v_mfma_f32_16x16x32_f16 v[34:37], v[140:143], v[172:175], v[34:37]
	s_waitcnt lgkmcnt(3)
	v_mfma_f32_16x16x32_f16 v[64:67], v[136:139], v[152:155], v[64:67]
	v_mfma_f32_16x16x32_f16 v[60:63], v[144:147], v[152:155], v[60:63]
	s_waitcnt lgkmcnt(2)
	v_mfma_f32_16x16x32_f16 v[56:59], v[136:139], v[160:163], v[56:59]
	v_mfma_f32_16x16x32_f16 v[52:55], v[144:147], v[160:163], v[52:55]
	s_waitcnt lgkmcnt(1)
	v_mfma_f32_16x16x32_f16 v[48:51], v[136:139], v[168:171], v[48:51]
	v_mfma_f32_16x16x32_f16 v[44:47], v[144:147], v[168:171], v[44:47]
	s_waitcnt lgkmcnt(0)
	v_mfma_f32_16x16x32_f16 v[40:43], v[136:139], v[176:179], v[38:41]
	v_mfma_f32_16x16x32_f16 v[36:39], v[144:147], v[176:179], v[34:37]
	s_setprio 0
	s_barrier
	s_add_u32 s14, s22, 0x40080
	s_addc_u32 s15, s23, 0
	s_add_i32 s22, s24, s29
	v_lshl_add_u64 v[34:35], s[14:15], 0, v[196:197]
	s_mov_b32 m0, s22
	s_nop 0
	global_load_lds_dwordx4 v[34:35], off
	v_lshl_add_u64 v[34:35], s[14:15], 0, v[198:199]
	s_add_i32 m0, s22, 0x2000
	s_nop 0
	global_load_lds_dwordx4 v[34:35], off
	s_waitcnt vmcnt(6)
	s_barrier
	s_setprio 1
	v_mfma_f32_16x16x32_f16 v[28:31], v[180:183], v[148:151], v[28:31]
	v_mfma_f32_16x16x32_f16 v[24:27], v[188:191], v[148:151], v[24:27]
	v_mfma_f32_16x16x32_f16 v[20:23], v[180:183], v[156:159], v[20:23]
	v_mfma_f32_16x16x32_f16 v[16:19], v[188:191], v[156:159], v[16:19]
	v_mfma_f32_16x16x32_f16 v[12:15], v[180:183], v[164:167], v[12:15]
	v_mfma_f32_16x16x32_f16 v[8:11], v[188:191], v[164:167], v[8:11]
	v_mfma_f32_16x16x32_f16 v[4:7], v[180:183], v[172:175], v[4:7]
	v_mfma_f32_16x16x32_f16 v[0:3], v[188:191], v[172:175], v[0:3]
	v_mfma_f32_16x16x32_f16 v[28:31], v[184:187], v[152:155], v[28:31]
	v_mfma_f32_16x16x32_f16 v[24:27], v[192:195], v[152:155], v[24:27]
	v_mfma_f32_16x16x32_f16 v[20:23], v[184:187], v[160:163], v[20:23]
	v_mfma_f32_16x16x32_f16 v[16:19], v[192:195], v[160:163], v[16:19]
	v_mfma_f32_16x16x32_f16 v[12:15], v[184:187], v[168:171], v[12:15]
	v_mfma_f32_16x16x32_f16 v[8:11], v[192:195], v[168:171], v[8:11]
	v_mfma_f32_16x16x32_f16 v[4:7], v[184:187], v[176:179], v[4:7]
	v_mfma_f32_16x16x32_f16 v[0:3], v[192:195], v[176:179], v[0:3]
	s_setprio 0
	s_add_i32 s11, s11, 2
	s_add_u32 s1, s1, 0x100
	s_addc_u32 s3, s3, 0
	s_cmp_gt_u32 s11, 13
	s_mov_b64 s[14:15], s[20:21]
	s_barrier
	s_cbranch_scc0 .LBB0_940
	v_lshl_add_u32 v34, s12, 8, v208
	v_lshl_or_b32 v156, s10, 8, v210
	s_cmp_lg_u32 s13, 0
	s_cselect_b64 s[10:11], -1, 0
	s_cmp_eq_u32 s13, 0
	v_ashrrev_i32_e32 v157, 31, v156
	v_ashrrev_i32_e32 v35, 31, v34
	v_mad_i64_i32 v[158:159], s[12:13], v34, s33, 0
	v_or_b32_e32 v160, 16, v34
	v_or_b32_e32 v162, 32, v34
	v_or_b32_e32 v164, 48, v34
	s_cbranch_scc1 .LBB0_946
	v_lshl_add_u64 v[132:133], s[70:71], 0, v[158:159]
	v_lshlrev_b64 v[166:167], 1, v[156:157]
	v_lshl_add_u64 v[132:133], v[132:133], 0, v[166:167]
	s_mov_b64 s[16:17], 0x2800
	v_mov_b64_e32 v[168:169], s[70:71]
	s_movk_i32 s1, 0x2000
	v_lshl_add_u64 v[134:135], v[132:133], 0, s[16:17]
	v_mad_i64_i32 v[136:137], s[12:13], v160, s33, v[168:169]
	v_add_co_u32_e32 v132, vcc, s1, v132
	v_lshl_add_u64 v[136:137], v[136:137], 0, v[166:167]
	s_nop 0
	v_addc_co_u32_e32 v133, vcc, 0, v133, vcc
	v_lshl_add_u64 v[138:139], v[136:137], 0, s[16:17]
	v_mad_i64_i32 v[140:141], s[12:13], v162, s33, v[168:169]
	v_add_co_u32_e32 v136, vcc, s1, v136
	v_lshl_add_u64 v[140:141], v[140:141], 0, v[166:167]
	s_nop 0
	v_addc_co_u32_e32 v137, vcc, 0, v137, vcc
	v_mad_i64_i32 v[144:145], s[12:13], v164, s33, v[168:169]
	global_load_dwordx4 v[170:173], v[132:133], off offset:2048
	global_load_dwordx4 v[152:155], v[136:137], off offset:2048
	global_load_dwordx4 v[174:177], v[134:135], off offset:256
	global_load_dwordx4 v[148:151], v[138:139], off offset:256
	v_add_co_u32_e32 v132, vcc, s1, v140
	v_lshl_add_u64 v[144:145], v[144:145], 0, v[166:167]
	s_nop 0
	v_addc_co_u32_e32 v133, vcc, 0, v141, vcc
	v_add_co_u32_e32 v134, vcc, s1, v144
	v_lshl_add_u64 v[142:143], v[140:141], 0, s[16:17]
	s_nop 0
	v_addc_co_u32_e32 v135, vcc, 0, v145, vcc
	v_lshl_add_u64 v[178:179], v[144:145], 0, s[16:17]
	global_load_dwordx4 v[144:147], v[132:133], off offset:2048
	global_load_dwordx4 v[136:139], v[134:135], off offset:2048
	s_nop 0
	global_load_dwordx4 v[140:143], v[142:143], off offset:256
	s_nop 0
	global_load_dwordx4 v[132:135], v[178:179], off offset:256
	v_ashrrev_i32_e32 v161, 31, v160
	v_ashrrev_i32_e32 v163, 31, v162
	v_ashrrev_i32_e32 v165, 31, v164
	s_waitcnt vmcnt(0)
	v_cvt_f32_f16_e32 v32, v170
	v_cvt_f32_f16_sdwa v170, v170 dst_sel:DWORD dst_unused:UNUSED_PAD src0_sel:WORD_1
	v_lshlrev_b64 v[178:179], 11, v[34:35]
	v_readlane_b32 s14, v252, 9
	v_max_f32_e32 v32, 0xc1f00000, v32
	v_max_f32_e32 v35, 0xc1f00000, v170
	v_cvt_f32_f16_e32 v170, v171
	v_cvt_f32_f16_sdwa v171, v171 dst_sel:DWORD dst_unused:UNUSED_PAD src0_sel:WORD_1
	v_mul_f32_e32 v35, 0xbfb8aa3b, v35
	v_exp_f32_e32 v35, v35
	v_max_f32_e32 v170, 0xc1f00000, v170
	v_mul_f32_e32 v170, 0xbfb8aa3b, v170
	v_exp_f32_e32 v180, v170
	v_max_f32_e32 v170, 0xc1f00000, v171
	v_mul_f32_e32 v170, 0xbfb8aa3b, v170
	v_cvt_f32_f16_e32 v171, v172
	v_exp_f32_e32 v181, v170
	v_cvt_f32_f16_sdwa v170, v172 dst_sel:DWORD dst_unused:UNUSED_PAD src0_sel:WORD_1
	v_mul_f32_e32 v32, 0xbfb8aa3b, v32
	v_max_f32_e32 v171, 0xc1f00000, v171
	v_mul_f32_e32 v171, 0xbfb8aa3b, v171
	v_max_f32_e32 v170, 0xc1f00000, v170
	v_mul_f32_e32 v170, 0xbfb8aa3b, v170
	v_exp_f32_e32 v182, v171
	v_cvt_f32_f16_e32 v171, v173
	v_exp_f32_e32 v183, v170
	v_cvt_f32_f16_sdwa v170, v173 dst_sel:DWORD dst_unused:UNUSED_PAD src0_sel:WORD_1
	v_exp_f32_e32 v32, v32
	v_max_f32_e32 v171, 0xc1f00000, v171
	v_mul_f32_e32 v171, 0xbfb8aa3b, v171
	v_max_f32_e32 v170, 0xc1f00000, v170
	v_mul_f32_e32 v170, 0xbfb8aa3b, v170
	v_add_f32_e32 v35, 1.0, v35
	v_exp_f32_e32 v184, v171
	v_exp_f32_e32 v185, v170
	v_rcp_f32_e32 v170, v35
	v_add_f32_e32 v35, 1.0, v180
	v_rcp_f32_e32 v171, v35
	v_add_f32_e32 v35, 1.0, v181
	v_add_f32_e32 v32, 1.0, v32
	v_rcp_f32_e32 v172, v35
	v_add_f32_e32 v35, 1.0, v182
	v_rcp_f32_e32 v32, v32
	v_rcp_f32_e32 v173, v35
	v_add_f32_e32 v35, 1.0, v183
	v_rcp_f32_e32 v180, v35
	v_add_f32_e32 v35, 1.0, v184
	v_rcp_f32_e32 v181, v35
	v_mov_b32_e32 v182, v129
	v_mov_b32_e32 v183, v130
	v_pk_mul_f32 v[170:171], v[182:183], v[170:171]
	v_pk_mov_b32 v[182:183], v[130:131], v[124:125] op_sel:[1,0]
	v_add_f32_e32 v35, 1.0, v185
	v_fma_mixlo_f16 v32, v128, v32, 0
	v_cvt_pk_f16_f32 v171, v170, v171
	v_pk_mul_f32 v[172:173], v[182:183], v[172:173]
	v_rcp_f32_e32 v35, v35
	v_pack_b32_f16 v170, v32, v171
	v_cvt_pk_f16_f32 v32, v172, v173
	v_mov_b32_e32 v172, v125
	v_mov_b32_e32 v173, v126
	v_pk_mul_f32 v[172:173], v[172:173], v[180:181]
	v_readlane_b32 s15, v252, 10
	v_cvt_pk_f16_f32 v173, v172, v173
	v_alignbit_b32 v172, v173, v32, 16
	v_lshrrev_b32_e32 v173, 16, v173
	v_lshl_add_u64 v[178:179], s[14:15], 0, v[178:179]
	v_alignbit_b32 v171, v32, v171, 16
	v_fma_mixhi_f16 v173, v127, v35, 0
	v_lshl_add_u64 v[178:179], v[178:179], 0, v[166:167]
	global_store_dwordx4 v[178:179], v[170:173], off
	v_cvt_f32_f16_sdwa v35, v174 dst_sel:DWORD dst_unused:UNUSED_PAD src0_sel:WORD_1
	v_cvt_f32_f16_e32 v32, v174
	v_cvt_f32_f16_e32 v170, v175
	v_cvt_f32_f16_sdwa v171, v175 dst_sel:DWORD dst_unused:UNUSED_PAD src0_sel:WORD_1
	v_max_f32_e32 v35, 0xc1f00000, v35
	v_mul_f32_e32 v35, 0xbfb8aa3b, v35
	v_max_f32_e32 v170, 0xc1f00000, v170
	v_mul_f32_e32 v170, 0xbfb8aa3b, v170
	v_exp_f32_e32 v172, v170
	v_max_f32_e32 v170, 0xc1f00000, v171
	v_mul_f32_e32 v170, 0xbfb8aa3b, v170
	v_cvt_f32_f16_e32 v171, v176
	v_exp_f32_e32 v173, v170
	v_cvt_f32_f16_sdwa v170, v176 dst_sel:DWORD dst_unused:UNUSED_PAD src0_sel:WORD_1
	v_exp_f32_e32 v35, v35
	v_max_f32_e32 v171, 0xc1f00000, v171
	v_mul_f32_e32 v171, 0xbfb8aa3b, v171
	v_max_f32_e32 v170, 0xc1f00000, v170
	v_mul_f32_e32 v170, 0xbfb8aa3b, v170
	v_exp_f32_e32 v174, v171
	v_cvt_f32_f16_e32 v171, v177
	v_exp_f32_e32 v175, v170
	v_cvt_f32_f16_sdwa v170, v177 dst_sel:DWORD dst_unused:UNUSED_PAD src0_sel:WORD_1
	v_max_f32_e32 v32, 0xc1f00000, v32
	v_mul_f32_e32 v32, 0xbfb8aa3b, v32
	v_exp_f32_e32 v32, v32
	v_max_f32_e32 v171, 0xc1f00000, v171
	v_max_f32_e32 v170, 0xc1f00000, v170
	v_mul_f32_e32 v171, 0xbfb8aa3b, v171
	v_mul_f32_e32 v170, 0xbfb8aa3b, v170
	v_add_f32_e32 v35, 1.0, v35
	v_exp_f32_e32 v176, v171
	v_exp_f32_e32 v177, v170
	v_rcp_f32_e32 v170, v35
	v_add_f32_e32 v35, 1.0, v172
	v_rcp_f32_e32 v171, v35
	v_add_f32_e32 v35, 1.0, v173
	v_add_f32_e32 v32, 1.0, v32
	v_rcp_f32_e32 v172, v35
	v_add_f32_e32 v35, 1.0, v174
	v_rcp_f32_e32 v32, v32
	v_rcp_f32_e32 v173, v35
	v_add_f32_e32 v35, 1.0, v175
	v_rcp_f32_e32 v174, v35
	v_add_f32_e32 v35, 1.0, v176
	v_rcp_f32_e32 v175, v35
	v_add_f32_e32 v35, 1.0, v177
	v_mov_b32_e32 v176, v97
	v_mov_b32_e32 v177, v98
	v_pk_mul_f32 v[170:171], v[176:177], v[170:171]
	v_pk_mov_b32 v[176:177], v[98:99], v[92:93] op_sel:[1,0]
	v_fma_mixlo_f16 v32, v96, v32, 0
	v_cvt_pk_f16_f32 v171, v170, v171
	v_pk_mul_f32 v[172:173], v[176:177], v[172:173]
	v_rcp_f32_e32 v35, v35
	v_pack_b32_f16 v170, v32, v171
	v_cvt_pk_f16_f32 v32, v172, v173
	v_mov_b32_e32 v172, v93
	v_mov_b32_e32 v173, v94
	v_pk_mul_f32 v[172:173], v[172:173], v[174:175]
	v_alignbit_b32 v171, v32, v171, 16
	v_cvt_pk_f16_f32 v173, v172, v173
	v_alignbit_b32 v172, v173, v32, 16
	v_lshrrev_b32_e32 v173, 16, v173
	v_fma_mixhi_f16 v173, v95, v35, 0
	v_cvt_f32_f16_e32 v32, v152
	v_cvt_f32_f16_sdwa v35, v152 dst_sel:DWORD dst_unused:UNUSED_PAD src0_sel:WORD_1
	v_cvt_f32_f16_e32 v152, v153
	v_cvt_f32_f16_sdwa v153, v153 dst_sel:DWORD dst_unused:UNUSED_PAD src0_sel:WORD_1
	global_store_dwordx4 v[178:179], v[170:173], off offset:256
	v_max_f32_e32 v35, 0xc1f00000, v35
	v_max_f32_e32 v152, 0xc1f00000, v152
	v_mul_f32_e32 v152, 0xbfb8aa3b, v152
	v_lshlrev_b64 v[170:171], 11, v[160:161]
	v_exp_f32_e32 v161, v152
	v_max_f32_e32 v152, 0xc1f00000, v153
	v_mul_f32_e32 v152, 0xbfb8aa3b, v152
	v_cvt_f32_f16_e32 v153, v154
	v_exp_f32_e32 v172, v152
	v_cvt_f32_f16_sdwa v152, v154 dst_sel:DWORD dst_unused:UNUSED_PAD src0_sel:WORD_1
	v_mul_f32_e32 v35, 0xbfb8aa3b, v35
	v_max_f32_e32 v153, 0xc1f00000, v153
	v_mul_f32_e32 v153, 0xbfb8aa3b, v153
	v_max_f32_e32 v152, 0xc1f00000, v152
	v_mul_f32_e32 v152, 0xbfb8aa3b, v152
	v_exp_f32_e32 v173, v153
	v_cvt_f32_f16_e32 v153, v155
	v_exp_f32_e32 v174, v152
	v_cvt_f32_f16_sdwa v152, v155 dst_sel:DWORD dst_unused:UNUSED_PAD src0_sel:WORD_1
	v_exp_f32_e32 v35, v35
	v_max_f32_e32 v32, 0xc1f00000, v32
	v_mul_f32_e32 v32, 0xbfb8aa3b, v32
	v_exp_f32_e32 v32, v32
	v_max_f32_e32 v153, 0xc1f00000, v153
	v_max_f32_e32 v152, 0xc1f00000, v152
	v_mul_f32_e32 v153, 0xbfb8aa3b, v153
	v_mul_f32_e32 v152, 0xbfb8aa3b, v152
	v_add_f32_e32 v35, 1.0, v35
	v_exp_f32_e32 v175, v153
	v_exp_f32_e32 v176, v152
	v_rcp_f32_e32 v152, v35
	v_add_f32_e32 v35, 1.0, v161
	v_rcp_f32_e32 v153, v35
	v_add_f32_e32 v35, 1.0, v172
	v_add_f32_e32 v32, 1.0, v32
	v_rcp_f32_e32 v154, v35
	v_add_f32_e32 v35, 1.0, v173
	v_rcp_f32_e32 v32, v32
	v_rcp_f32_e32 v155, v35
	v_add_f32_e32 v35, 1.0, v174
	v_rcp_f32_e32 v172, v35
	v_add_f32_e32 v35, 1.0, v175
	v_rcp_f32_e32 v173, v35
	v_mov_b32_e32 v174, v121
	v_mov_b32_e32 v175, v122
	v_pk_mul_f32 v[152:153], v[174:175], v[152:153]
	v_pk_mov_b32 v[174:175], v[122:123], v[116:117] op_sel:[1,0]
	v_add_f32_e32 v35, 1.0, v176
	v_fma_mixlo_f16 v32, v120, v32, 0
	v_cvt_pk_f16_f32 v153, v152, v153
	v_pk_mul_f32 v[154:155], v[174:175], v[154:155]
	v_rcp_f32_e32 v35, v35
	v_pack_b32_f16 v152, v32, v153
	v_cvt_pk_f16_f32 v32, v154, v155
	v_mov_b32_e32 v154, v117
	v_mov_b32_e32 v155, v118
	v_pk_mul_f32 v[154:155], v[154:155], v[172:173]
	v_alignbit_b32 v153, v32, v153, 16
	v_cvt_pk_f16_f32 v155, v154, v155
	v_alignbit_b32 v154, v155, v32, 16
	v_lshrrev_b32_e32 v155, 16, v155
	v_fma_mixhi_f16 v155, v119, v35, 0
	v_cvt_f32_f16_e32 v32, v148
	v_cvt_f32_f16_sdwa v35, v148 dst_sel:DWORD dst_unused:UNUSED_PAD src0_sel:WORD_1
	v_cvt_f32_f16_e32 v148, v149
	v_cvt_f32_f16_sdwa v149, v149 dst_sel:DWORD dst_unused:UNUSED_PAD src0_sel:WORD_1
	v_lshl_add_u64 v[170:171], s[14:15], 0, v[170:171]
	v_lshl_add_u64 v[170:171], v[170:171], 0, v[166:167]
	v_max_f32_e32 v148, 0xc1f00000, v148
	v_mul_f32_e32 v148, 0xbfb8aa3b, v148
	global_store_dwordx4 v[170:171], v[152:155], off
	v_max_f32_e32 v35, 0xc1f00000, v35
	v_mul_f32_e32 v35, 0xbfb8aa3b, v35
	v_exp_f32_e32 v152, v148
	v_max_f32_e32 v148, 0xc1f00000, v149
	v_mul_f32_e32 v148, 0xbfb8aa3b, v148
	v_cvt_f32_f16_e32 v149, v150
	v_exp_f32_e32 v153, v148
	v_cvt_f32_f16_sdwa v148, v150 dst_sel:DWORD dst_unused:UNUSED_PAD src0_sel:WORD_1
	v_exp_f32_e32 v35, v35
	v_max_f32_e32 v149, 0xc1f00000, v149
	v_mul_f32_e32 v149, 0xbfb8aa3b, v149
	v_max_f32_e32 v148, 0xc1f00000, v148
	v_mul_f32_e32 v148, 0xbfb8aa3b, v148
	v_exp_f32_e32 v154, v149
	v_cvt_f32_f16_e32 v149, v151
	v_exp_f32_e32 v155, v148
	v_cvt_f32_f16_sdwa v148, v151 dst_sel:DWORD dst_unused:UNUSED_PAD src0_sel:WORD_1
	v_max_f32_e32 v32, 0xc1f00000, v32
	v_mul_f32_e32 v32, 0xbfb8aa3b, v32
	v_exp_f32_e32 v32, v32
	v_max_f32_e32 v149, 0xc1f00000, v149
	v_max_f32_e32 v148, 0xc1f00000, v148
	v_mul_f32_e32 v149, 0xbfb8aa3b, v149
	v_mul_f32_e32 v148, 0xbfb8aa3b, v148
	v_add_f32_e32 v35, 1.0, v35
	v_exp_f32_e32 v161, v149
	v_exp_f32_e32 v172, v148
	v_rcp_f32_e32 v148, v35
	v_add_f32_e32 v35, 1.0, v152
	v_rcp_f32_e32 v149, v35
	v_add_f32_e32 v35, 1.0, v153
	v_add_f32_e32 v32, 1.0, v32
	v_rcp_f32_e32 v150, v35
	v_add_f32_e32 v35, 1.0, v154
	v_rcp_f32_e32 v32, v32
	v_rcp_f32_e32 v151, v35
	v_add_f32_e32 v35, 1.0, v155
	v_rcp_f32_e32 v152, v35
	v_add_f32_e32 v35, 1.0, v161
	v_rcp_f32_e32 v153, v35
	v_mov_b32_e32 v154, v89
	v_mov_b32_e32 v155, v90
	v_pk_mul_f32 v[148:149], v[154:155], v[148:149]
	v_pk_mov_b32 v[154:155], v[90:91], v[84:85] op_sel:[1,0]
	v_add_f32_e32 v35, 1.0, v172
	v_fma_mixlo_f16 v32, v88, v32, 0
	v_cvt_pk_f16_f32 v149, v148, v149
	v_pk_mul_f32 v[150:151], v[154:155], v[150:151]
	v_rcp_f32_e32 v35, v35
	v_pack_b32_f16 v148, v32, v149
	v_cvt_pk_f16_f32 v32, v150, v151
	v_mov_b32_e32 v150, v85
	v_mov_b32_e32 v151, v86
	v_pk_mul_f32 v[150:151], v[150:151], v[152:153]
	v_alignbit_b32 v149, v32, v149, 16
	v_cvt_pk_f16_f32 v151, v150, v151
	v_alignbit_b32 v150, v151, v32, 16
	v_lshrrev_b32_e32 v151, 16, v151
	v_fma_mixhi_f16 v151, v87, v35, 0
	v_cvt_f32_f16_e32 v32, v144
	v_cvt_f32_f16_sdwa v35, v144 dst_sel:DWORD dst_unused:UNUSED_PAD src0_sel:WORD_1
	v_cvt_f32_f16_e32 v144, v145
	v_cvt_f32_f16_sdwa v145, v145 dst_sel:DWORD dst_unused:UNUSED_PAD src0_sel:WORD_1
	global_store_dwordx4 v[170:171], v[148:151], off offset:256
	v_max_f32_e32 v35, 0xc1f00000, v35
	v_max_f32_e32 v144, 0xc1f00000, v144
	v_mul_f32_e32 v144, 0xbfb8aa3b, v144
	v_exp_f32_e32 v150, v144
	v_max_f32_e32 v144, 0xc1f00000, v145
	v_mul_f32_e32 v144, 0xbfb8aa3b, v144
	v_cvt_f32_f16_e32 v145, v146
	v_exp_f32_e32 v151, v144
	v_cvt_f32_f16_sdwa v144, v146 dst_sel:DWORD dst_unused:UNUSED_PAD src0_sel:WORD_1
	v_mul_f32_e32 v35, 0xbfb8aa3b, v35
	v_max_f32_e32 v145, 0xc1f00000, v145
	v_mul_f32_e32 v145, 0xbfb8aa3b, v145
	v_max_f32_e32 v144, 0xc1f00000, v144
	v_mul_f32_e32 v144, 0xbfb8aa3b, v144
	v_exp_f32_e32 v152, v145
	v_cvt_f32_f16_e32 v145, v147
	v_exp_f32_e32 v153, v144
	v_cvt_f32_f16_sdwa v144, v147 dst_sel:DWORD dst_unused:UNUSED_PAD src0_sel:WORD_1
	v_exp_f32_e32 v35, v35
	v_max_f32_e32 v32, 0xc1f00000, v32
	v_mul_f32_e32 v32, 0xbfb8aa3b, v32
	v_exp_f32_e32 v32, v32
	v_max_f32_e32 v145, 0xc1f00000, v145
	v_max_f32_e32 v144, 0xc1f00000, v144
	v_mul_f32_e32 v145, 0xbfb8aa3b, v145
	v_mul_f32_e32 v144, 0xbfb8aa3b, v144
	v_add_f32_e32 v35, 1.0, v35
	v_exp_f32_e32 v154, v145
	v_exp_f32_e32 v155, v144
	v_rcp_f32_e32 v144, v35
	v_add_f32_e32 v35, 1.0, v150
	v_rcp_f32_e32 v145, v35
	v_add_f32_e32 v35, 1.0, v151
	v_add_f32_e32 v32, 1.0, v32
	v_rcp_f32_e32 v146, v35
	v_add_f32_e32 v35, 1.0, v152
	v_rcp_f32_e32 v32, v32
	v_rcp_f32_e32 v147, v35
	v_add_f32_e32 v35, 1.0, v153
	v_rcp_f32_e32 v150, v35
	v_add_f32_e32 v35, 1.0, v154
	v_rcp_f32_e32 v151, v35
	v_mov_b32_e32 v152, v113
	v_mov_b32_e32 v153, v114
	v_pk_mul_f32 v[144:145], v[152:153], v[144:145]
	v_pk_mov_b32 v[152:153], v[114:115], v[108:109] op_sel:[1,0]
	v_add_f32_e32 v35, 1.0, v155
	v_fma_mixlo_f16 v32, v112, v32, 0
	v_cvt_pk_f16_f32 v145, v144, v145
	v_pk_mul_f32 v[146:147], v[152:153], v[146:147]
	v_rcp_f32_e32 v35, v35
	v_pack_b32_f16 v144, v32, v145
	v_cvt_pk_f16_f32 v32, v146, v147
	v_mov_b32_e32 v146, v109
	v_mov_b32_e32 v147, v110
	v_pk_mul_f32 v[146:147], v[146:147], v[150:151]
	v_alignbit_b32 v145, v32, v145, 16
	v_cvt_pk_f16_f32 v147, v146, v147
	v_alignbit_b32 v146, v147, v32, 16
	v_lshrrev_b32_e32 v147, 16, v147
	v_fma_mixhi_f16 v147, v111, v35, 0
	v_cvt_f32_f16_e32 v32, v140
	v_cvt_f32_f16_sdwa v35, v140 dst_sel:DWORD dst_unused:UNUSED_PAD src0_sel:WORD_1
	v_cvt_f32_f16_e32 v140, v141
	v_cvt_f32_f16_sdwa v141, v141 dst_sel:DWORD dst_unused:UNUSED_PAD src0_sel:WORD_1
	v_lshlrev_b64 v[148:149], 11, v[162:163]
	v_lshl_add_u64 v[148:149], s[14:15], 0, v[148:149]
	v_max_f32_e32 v140, 0xc1f00000, v140
	v_lshl_add_u64 v[148:149], v[148:149], 0, v[166:167]
	v_mul_f32_e32 v140, 0xbfb8aa3b, v140
	global_store_dwordx4 v[148:149], v[144:147], off
	v_max_f32_e32 v35, 0xc1f00000, v35
	v_mul_f32_e32 v35, 0xbfb8aa3b, v35
	v_exp_f32_e32 v144, v140
	v_max_f32_e32 v140, 0xc1f00000, v141
	v_mul_f32_e32 v140, 0xbfb8aa3b, v140
	v_cvt_f32_f16_e32 v141, v142
	v_exp_f32_e32 v145, v140
	v_cvt_f32_f16_sdwa v140, v142 dst_sel:DWORD dst_unused:UNUSED_PAD src0_sel:WORD_1
	v_exp_f32_e32 v35, v35
	v_max_f32_e32 v141, 0xc1f00000, v141
	v_mul_f32_e32 v141, 0xbfb8aa3b, v141
	v_max_f32_e32 v140, 0xc1f00000, v140
	v_mul_f32_e32 v140, 0xbfb8aa3b, v140
	v_exp_f32_e32 v146, v141
	v_cvt_f32_f16_e32 v141, v143
	v_exp_f32_e32 v147, v140
	v_cvt_f32_f16_sdwa v140, v143 dst_sel:DWORD dst_unused:UNUSED_PAD src0_sel:WORD_1
	v_max_f32_e32 v32, 0xc1f00000, v32
	v_mul_f32_e32 v32, 0xbfb8aa3b, v32
	v_exp_f32_e32 v32, v32
	v_max_f32_e32 v141, 0xc1f00000, v141
	v_max_f32_e32 v140, 0xc1f00000, v140
	v_mul_f32_e32 v141, 0xbfb8aa3b, v141
	v_mul_f32_e32 v140, 0xbfb8aa3b, v140
	v_add_f32_e32 v35, 1.0, v35
	v_exp_f32_e32 v150, v141
	v_exp_f32_e32 v151, v140
	v_rcp_f32_e32 v140, v35
	v_add_f32_e32 v35, 1.0, v144
	v_rcp_f32_e32 v141, v35
	v_add_f32_e32 v35, 1.0, v145
	v_add_f32_e32 v32, 1.0, v32
	v_rcp_f32_e32 v142, v35
	v_add_f32_e32 v35, 1.0, v146
	v_rcp_f32_e32 v32, v32
	v_rcp_f32_e32 v143, v35
	v_add_f32_e32 v35, 1.0, v147
	v_rcp_f32_e32 v144, v35
	v_add_f32_e32 v35, 1.0, v150
	v_rcp_f32_e32 v145, v35
	v_mov_b32_e32 v146, v81
	v_mov_b32_e32 v147, v82
	v_pk_mul_f32 v[140:141], v[146:147], v[140:141]
	v_pk_mov_b32 v[146:147], v[82:83], v[76:77] op_sel:[1,0]
	v_add_f32_e32 v35, 1.0, v151
	v_fma_mixlo_f16 v32, v80, v32, 0
	v_cvt_pk_f16_f32 v141, v140, v141
	v_pk_mul_f32 v[142:143], v[146:147], v[142:143]
	v_rcp_f32_e32 v35, v35
	v_pack_b32_f16 v140, v32, v141
	v_cvt_pk_f16_f32 v32, v142, v143
	v_mov_b32_e32 v142, v77
	v_mov_b32_e32 v143, v78
	v_pk_mul_f32 v[142:143], v[142:143], v[144:145]
	v_alignbit_b32 v141, v32, v141, 16
	v_cvt_pk_f16_f32 v143, v142, v143
	v_alignbit_b32 v142, v143, v32, 16
	v_lshrrev_b32_e32 v143, 16, v143
	v_fma_mixhi_f16 v143, v79, v35, 0
	v_cvt_f32_f16_e32 v32, v136
	v_cvt_f32_f16_sdwa v35, v136 dst_sel:DWORD dst_unused:UNUSED_PAD src0_sel:WORD_1
	v_cvt_f32_f16_e32 v136, v137
	v_cvt_f32_f16_sdwa v137, v137 dst_sel:DWORD dst_unused:UNUSED_PAD src0_sel:WORD_1
	global_store_dwordx4 v[148:149], v[140:143], off offset:256
	v_max_f32_e32 v35, 0xc1f00000, v35
	v_max_f32_e32 v136, 0xc1f00000, v136
	v_mul_f32_e32 v136, 0xbfb8aa3b, v136
	v_exp_f32_e32 v142, v136
	v_max_f32_e32 v136, 0xc1f00000, v137
	v_mul_f32_e32 v136, 0xbfb8aa3b, v136
	v_cvt_f32_f16_e32 v137, v138
	v_exp_f32_e32 v143, v136
	v_cvt_f32_f16_sdwa v136, v138 dst_sel:DWORD dst_unused:UNUSED_PAD src0_sel:WORD_1
	v_mul_f32_e32 v35, 0xbfb8aa3b, v35
	v_max_f32_e32 v137, 0xc1f00000, v137
	v_mul_f32_e32 v137, 0xbfb8aa3b, v137
	v_max_f32_e32 v136, 0xc1f00000, v136
	v_mul_f32_e32 v136, 0xbfb8aa3b, v136
	v_exp_f32_e32 v144, v137
	v_cvt_f32_f16_e32 v137, v139
	v_exp_f32_e32 v145, v136
	v_cvt_f32_f16_sdwa v136, v139 dst_sel:DWORD dst_unused:UNUSED_PAD src0_sel:WORD_1
	v_exp_f32_e32 v35, v35
	v_max_f32_e32 v32, 0xc1f00000, v32
	v_mul_f32_e32 v32, 0xbfb8aa3b, v32
	v_exp_f32_e32 v32, v32
	v_max_f32_e32 v137, 0xc1f00000, v137
	v_max_f32_e32 v136, 0xc1f00000, v136
	v_mul_f32_e32 v137, 0xbfb8aa3b, v137
	v_mul_f32_e32 v136, 0xbfb8aa3b, v136
	v_add_f32_e32 v35, 1.0, v35
	v_exp_f32_e32 v146, v137
	v_exp_f32_e32 v147, v136
	v_rcp_f32_e32 v136, v35
	v_add_f32_e32 v35, 1.0, v142
	v_rcp_f32_e32 v137, v35
	v_add_f32_e32 v35, 1.0, v143
	v_add_f32_e32 v32, 1.0, v32
	v_rcp_f32_e32 v138, v35
	v_add_f32_e32 v35, 1.0, v144
	v_rcp_f32_e32 v32, v32
	v_rcp_f32_e32 v139, v35
	v_add_f32_e32 v35, 1.0, v145
	v_rcp_f32_e32 v142, v35
	v_add_f32_e32 v35, 1.0, v146
	v_rcp_f32_e32 v143, v35
	v_mov_b32_e32 v144, v105
	v_mov_b32_e32 v145, v106
	v_pk_mul_f32 v[136:137], v[144:145], v[136:137]
	v_pk_mov_b32 v[144:145], v[106:107], v[100:101] op_sel:[1,0]
	v_add_f32_e32 v35, 1.0, v147
	v_fma_mixlo_f16 v32, v104, v32, 0
	v_cvt_pk_f16_f32 v137, v136, v137
	v_pk_mul_f32 v[138:139], v[144:145], v[138:139]
	v_rcp_f32_e32 v35, v35
	v_pack_b32_f16 v136, v32, v137
	v_cvt_pk_f16_f32 v32, v138, v139
	v_mov_b32_e32 v138, v101
	v_mov_b32_e32 v139, v102
	v_pk_mul_f32 v[138:139], v[138:139], v[142:143]
	v_alignbit_b32 v137, v32, v137, 16
	v_cvt_pk_f16_f32 v139, v138, v139
	v_alignbit_b32 v138, v139, v32, 16
	v_lshrrev_b32_e32 v139, 16, v139
	v_fma_mixhi_f16 v139, v103, v35, 0
	v_cvt_f32_f16_e32 v32, v132
	v_cvt_f32_f16_sdwa v35, v132 dst_sel:DWORD dst_unused:UNUSED_PAD src0_sel:WORD_1
	v_cvt_f32_f16_e32 v132, v133
	v_cvt_f32_f16_sdwa v133, v133 dst_sel:DWORD dst_unused:UNUSED_PAD src0_sel:WORD_1
	v_lshlrev_b64 v[140:141], 11, v[164:165]
	v_lshl_add_u64 v[140:141], s[14:15], 0, v[140:141]
	v_max_f32_e32 v132, 0xc1f00000, v132
	v_lshl_add_u64 v[140:141], v[140:141], 0, v[166:167]
	v_mul_f32_e32 v132, 0xbfb8aa3b, v132
	global_store_dwordx4 v[140:141], v[136:139], off
	v_max_f32_e32 v35, 0xc1f00000, v35
	v_mul_f32_e32 v35, 0xbfb8aa3b, v35
	v_exp_f32_e32 v136, v132
	v_max_f32_e32 v132, 0xc1f00000, v133
	v_mul_f32_e32 v132, 0xbfb8aa3b, v132
	v_cvt_f32_f16_e32 v133, v134
	v_exp_f32_e32 v137, v132
	v_cvt_f32_f16_sdwa v132, v134 dst_sel:DWORD dst_unused:UNUSED_PAD src0_sel:WORD_1
	v_exp_f32_e32 v35, v35
	v_max_f32_e32 v133, 0xc1f00000, v133
	v_mul_f32_e32 v133, 0xbfb8aa3b, v133
	v_max_f32_e32 v132, 0xc1f00000, v132
	v_mul_f32_e32 v132, 0xbfb8aa3b, v132
	v_exp_f32_e32 v138, v133
	v_cvt_f32_f16_e32 v133, v135
	v_exp_f32_e32 v139, v132
	v_cvt_f32_f16_sdwa v132, v135 dst_sel:DWORD dst_unused:UNUSED_PAD src0_sel:WORD_1
	v_max_f32_e32 v32, 0xc1f00000, v32
	v_mul_f32_e32 v32, 0xbfb8aa3b, v32
	v_exp_f32_e32 v32, v32
	v_max_f32_e32 v133, 0xc1f00000, v133
	v_max_f32_e32 v132, 0xc1f00000, v132
	v_mul_f32_e32 v133, 0xbfb8aa3b, v133
	v_mul_f32_e32 v132, 0xbfb8aa3b, v132
	v_add_f32_e32 v35, 1.0, v35
	v_exp_f32_e32 v142, v133
	v_exp_f32_e32 v143, v132
	v_rcp_f32_e32 v132, v35
	v_add_f32_e32 v35, 1.0, v136
	v_rcp_f32_e32 v133, v35
	v_add_f32_e32 v35, 1.0, v137
	v_add_f32_e32 v32, 1.0, v32
	v_rcp_f32_e32 v134, v35
	v_add_f32_e32 v35, 1.0, v138
	v_rcp_f32_e32 v32, v32
	v_rcp_f32_e32 v135, v35
	v_add_f32_e32 v35, 1.0, v139
	v_rcp_f32_e32 v136, v35
	v_add_f32_e32 v35, 1.0, v142
	v_rcp_f32_e32 v137, v35
	v_mov_b32_e32 v138, v73
	v_mov_b32_e32 v139, v74
	v_pk_mul_f32 v[132:133], v[138:139], v[132:133]
	v_pk_mov_b32 v[138:139], v[74:75], v[68:69] op_sel:[1,0]
	v_add_f32_e32 v35, 1.0, v143
	v_fma_mixlo_f16 v32, v72, v32, 0
	v_cvt_pk_f16_f32 v133, v132, v133
	v_pk_mul_f32 v[134:135], v[138:139], v[134:135]
	v_rcp_f32_e32 v35, v35
	v_pack_b32_f16 v132, v32, v133
	v_cvt_pk_f16_f32 v32, v134, v135
	v_mov_b32_e32 v134, v69
	v_mov_b32_e32 v135, v70
	v_pk_mul_f32 v[134:135], v[134:135], v[136:137]
	v_alignbit_b32 v133, v32, v133, 16
	v_cvt_pk_f16_f32 v135, v134, v135
	v_alignbit_b32 v134, v135, v32, 16
	v_lshrrev_b32_e32 v135, 16, v135
	v_fma_mixhi_f16 v135, v71, v35, 0
	global_store_dwordx4 v[140:141], v[132:135], off offset:256
	v_add_u32_e32 v184, 0x80, v34
	s_nop 0
	v_mad_i64_i32 v[132:133], s[12:13], v184, s33, v[168:169]
	v_lshl_add_u64 v[132:133], v[132:133], 0, v[166:167]
	v_add_u32_e32 v174, 0x90, v34
	v_lshl_add_u64 v[134:135], v[132:133], 0, s[16:17]
	v_mad_i64_i32 v[136:137], s[12:13], v174, s33, v[168:169]
	v_add_co_u32_e32 v132, vcc, s1, v132
	v_lshl_add_u64 v[136:137], v[136:137], 0, v[166:167]
	v_add_u32_e32 v172, 0xa0, v34
	v_addc_co_u32_e32 v133, vcc, 0, v133, vcc
	v_lshl_add_u64 v[138:139], v[136:137], 0, s[16:17]
	v_mad_i64_i32 v[140:141], s[12:13], v172, s33, v[168:169]
	v_add_co_u32_e32 v136, vcc, s1, v136
	v_lshl_add_u64 v[140:141], v[140:141], 0, v[166:167]
	v_add_u32_e32 v170, 0xb0, v34
	v_addc_co_u32_e32 v137, vcc, 0, v137, vcc
	v_mad_i64_i32 v[144:145], s[12:13], v170, s33, v[168:169]
	global_load_dwordx4 v[176:179], v[132:133], off offset:2048
	global_load_dwordx4 v[152:155], v[136:137], off offset:2048
	global_load_dwordx4 v[180:183], v[134:135], off offset:256
	global_load_dwordx4 v[148:151], v[138:139], off offset:256
	v_add_co_u32_e32 v132, vcc, s1, v140
	v_lshl_add_u64 v[144:145], v[144:145], 0, v[166:167]
	s_nop 0
	v_addc_co_u32_e32 v133, vcc, 0, v141, vcc
	v_add_co_u32_e32 v134, vcc, s1, v144
	v_lshl_add_u64 v[142:143], v[140:141], 0, s[16:17]
	s_nop 0
	v_addc_co_u32_e32 v135, vcc, 0, v145, vcc
	v_lshl_add_u64 v[168:169], v[144:145], 0, s[16:17]
	global_load_dwordx4 v[144:147], v[132:133], off offset:2048
	global_load_dwordx4 v[136:139], v[134:135], off offset:2048
	s_nop 0
	global_load_dwordx4 v[140:143], v[142:143], off offset:256
	s_nop 0
	global_load_dwordx4 v[132:135], v[168:169], off offset:256
	v_ashrrev_i32_e32 v185, 31, v184
	v_ashrrev_i32_e32 v175, 31, v174
	v_ashrrev_i32_e32 v173, 31, v172
	v_ashrrev_i32_e32 v171, 31, v170
	s_waitcnt vmcnt(0)
	v_cvt_f32_f16_e32 v32, v176
	v_cvt_f32_f16_sdwa v35, v176 dst_sel:DWORD dst_unused:UNUSED_PAD src0_sel:WORD_1
	v_cvt_f32_f16_sdwa v176, v178 dst_sel:DWORD dst_unused:UNUSED_PAD src0_sel:WORD_1
	v_cvt_f32_f16_e32 v161, v177
	v_cvt_f32_f16_sdwa v163, v177 dst_sel:DWORD dst_unused:UNUSED_PAD src0_sel:WORD_1
	v_cvt_f32_f16_e32 v165, v178
	v_max_f32_e32 v176, 0xc1f00000, v176
	v_max_f32_e32 v35, 0xc1f00000, v35
	v_mul_f32_e32 v176, 0xbfb8aa3b, v176
	v_lshlrev_b64 v[168:169], 11, v[184:185]
	v_mul_f32_e32 v35, 0xbfb8aa3b, v35
	v_max_f32_e32 v161, 0xc1f00000, v161
	v_cvt_f32_f16_e32 v177, v179
	v_exp_f32_e32 v184, v176
	v_cvt_f32_f16_sdwa v176, v179 dst_sel:DWORD dst_unused:UNUSED_PAD src0_sel:WORD_1
	v_exp_f32_e32 v35, v35
	v_mul_f32_e32 v161, 0xbfb8aa3b, v161
	v_max_f32_e32 v163, 0xc1f00000, v163
	v_max_f32_e32 v32, 0xc1f00000, v32
	v_exp_f32_e32 v161, v161
	v_mul_f32_e32 v163, 0xbfb8aa3b, v163
	v_max_f32_e32 v165, 0xc1f00000, v165
	v_mul_f32_e32 v32, 0xbfb8aa3b, v32
	v_exp_f32_e32 v163, v163
	v_mul_f32_e32 v165, 0xbfb8aa3b, v165
	v_exp_f32_e32 v32, v32
	v_exp_f32_e32 v165, v165
	v_max_f32_e32 v177, 0xc1f00000, v177
	v_max_f32_e32 v176, 0xc1f00000, v176
	v_mul_f32_e32 v177, 0xbfb8aa3b, v177
	v_mul_f32_e32 v176, 0xbfb8aa3b, v176
	v_add_f32_e32 v35, 1.0, v35
	v_exp_f32_e32 v185, v177
	v_exp_f32_e32 v186, v176
	v_rcp_f32_e32 v176, v35
	v_add_f32_e32 v35, 1.0, v161
	v_rcp_f32_e32 v177, v35
	v_add_f32_e32 v35, 1.0, v163
	v_add_f32_e32 v32, 1.0, v32
	v_rcp_f32_e32 v178, v35
	v_add_f32_e32 v35, 1.0, v165
	v_rcp_f32_e32 v32, v32
	v_rcp_f32_e32 v179, v35
	v_add_f32_e32 v35, 1.0, v184
	v_rcp_f32_e32 v184, v35
	v_add_f32_e32 v35, 1.0, v185
	v_rcp_f32_e32 v185, v35
	v_add_f32_e32 v35, 1.0, v186
	v_mov_b32_e32 v186, v65
	v_mov_b32_e32 v187, v66
	v_pk_mul_f32 v[176:177], v[186:187], v[176:177]
	v_pk_mov_b32 v[186:187], v[66:67], v[60:61] op_sel:[1,0]
	v_fma_mixlo_f16 v32, v64, v32, 0
	v_cvt_pk_f16_f32 v161, v176, v177
	v_pk_mul_f32 v[178:179], v[186:187], v[178:179]
	v_rcp_f32_e32 v35, v35
	v_pack_b32_f16 v176, v32, v161
	v_cvt_pk_f16_f32 v32, v178, v179
	v_mov_b32_e32 v178, v61
	v_mov_b32_e32 v179, v62
	v_pk_mul_f32 v[178:179], v[178:179], v[184:185]
	v_alignbit_b32 v177, v32, v161, 16
	v_cvt_pk_f16_f32 v161, v178, v179
	v_lshrrev_b32_e32 v179, 16, v161
	v_lshl_add_u64 v[168:169], s[14:15], 0, v[168:169]
	v_alignbit_b32 v178, v161, v32, 16
	v_fma_mixhi_f16 v179, v63, v35, 0
	v_lshl_add_u64 v[168:169], v[168:169], 0, v[166:167]
	global_store_dwordx4 v[168:169], v[176:179], off
	v_cvt_f32_f16_sdwa v35, v180 dst_sel:DWORD dst_unused:UNUSED_PAD src0_sel:WORD_1
	v_cvt_f32_f16_e32 v161, v181
	v_cvt_f32_f16_sdwa v176, v182 dst_sel:DWORD dst_unused:UNUSED_PAD src0_sel:WORD_1
	v_cvt_f32_f16_sdwa v163, v181 dst_sel:DWORD dst_unused:UNUSED_PAD src0_sel:WORD_1
	v_cvt_f32_f16_e32 v32, v180
	v_cvt_f32_f16_e32 v165, v182
	v_max_f32_e32 v176, 0xc1f00000, v176
	v_max_f32_e32 v35, 0xc1f00000, v35
	v_mul_f32_e32 v176, 0xbfb8aa3b, v176
	v_mul_f32_e32 v35, 0xbfb8aa3b, v35
	v_max_f32_e32 v161, 0xc1f00000, v161
	v_cvt_f32_f16_e32 v177, v183
	v_exp_f32_e32 v180, v176
	v_cvt_f32_f16_sdwa v176, v183 dst_sel:DWORD dst_unused:UNUSED_PAD src0_sel:WORD_1
	v_exp_f32_e32 v35, v35
	v_mul_f32_e32 v161, 0xbfb8aa3b, v161
	v_max_f32_e32 v163, 0xc1f00000, v163
	v_max_f32_e32 v32, 0xc1f00000, v32
	v_exp_f32_e32 v161, v161
	v_mul_f32_e32 v163, 0xbfb8aa3b, v163
	v_max_f32_e32 v165, 0xc1f00000, v165
	v_mul_f32_e32 v32, 0xbfb8aa3b, v32
	v_exp_f32_e32 v163, v163
	v_mul_f32_e32 v165, 0xbfb8aa3b, v165
	v_exp_f32_e32 v32, v32
	v_exp_f32_e32 v165, v165
	v_max_f32_e32 v177, 0xc1f00000, v177
	v_max_f32_e32 v176, 0xc1f00000, v176
	v_mul_f32_e32 v177, 0xbfb8aa3b, v177
	v_mul_f32_e32 v176, 0xbfb8aa3b, v176
	v_add_f32_e32 v35, 1.0, v35
	v_exp_f32_e32 v181, v177
	v_exp_f32_e32 v182, v176
	v_rcp_f32_e32 v176, v35
	v_add_f32_e32 v35, 1.0, v161
	v_rcp_f32_e32 v177, v35
	v_add_f32_e32 v35, 1.0, v163
	v_add_f32_e32 v32, 1.0, v32
	v_rcp_f32_e32 v178, v35
	v_add_f32_e32 v35, 1.0, v165
	v_rcp_f32_e32 v32, v32
	v_rcp_f32_e32 v179, v35
	v_add_f32_e32 v35, 1.0, v180
	v_rcp_f32_e32 v180, v35
	v_add_f32_e32 v35, 1.0, v181
	v_rcp_f32_e32 v181, v35
	v_add_f32_e32 v35, 1.0, v182
	v_mov_b32_e32 v182, v29
	v_mov_b32_e32 v183, v30
	v_pk_mul_f32 v[176:177], v[182:183], v[176:177]
	v_pk_mov_b32 v[182:183], v[30:31], v[24:25] op_sel:[1,0]
	v_fma_mixlo_f16 v32, v28, v32, 0
	v_cvt_pk_f16_f32 v161, v176, v177
	v_pk_mul_f32 v[178:179], v[182:183], v[178:179]
	v_rcp_f32_e32 v35, v35
	v_pack_b32_f16 v176, v32, v161
	v_cvt_pk_f16_f32 v32, v178, v179
	v_mov_b32_e32 v178, v25
	v_mov_b32_e32 v179, v26
	v_pk_mul_f32 v[178:179], v[178:179], v[180:181]
	v_alignbit_b32 v177, v32, v161, 16
	v_cvt_pk_f16_f32 v161, v178, v179
	v_lshrrev_b32_e32 v179, 16, v161
	v_alignbit_b32 v178, v161, v32, 16
	v_fma_mixhi_f16 v179, v27, v35, 0
	v_cvt_f32_f16_e32 v32, v152
	v_cvt_f32_f16_sdwa v35, v152 dst_sel:DWORD dst_unused:UNUSED_PAD src0_sel:WORD_1
	v_cvt_f32_f16_e32 v152, v153
	v_cvt_f32_f16_sdwa v153, v153 dst_sel:DWORD dst_unused:UNUSED_PAD src0_sel:WORD_1
	global_store_dwordx4 v[168:169], v[176:179], off offset:256
	v_max_f32_e32 v35, 0xc1f00000, v35
	v_max_f32_e32 v152, 0xc1f00000, v152
	v_mul_f32_e32 v152, 0xbfb8aa3b, v152
	v_exp_f32_e32 v161, v152
	v_max_f32_e32 v152, 0xc1f00000, v153
	v_mul_f32_e32 v152, 0xbfb8aa3b, v152
	v_cvt_f32_f16_e32 v153, v154
	v_exp_f32_e32 v163, v152
	v_cvt_f32_f16_sdwa v152, v154 dst_sel:DWORD dst_unused:UNUSED_PAD src0_sel:WORD_1
	v_lshlrev_b64 v[168:169], 11, v[174:175]
	v_max_f32_e32 v153, 0xc1f00000, v153
	v_mul_f32_e32 v153, 0xbfb8aa3b, v153
	v_max_f32_e32 v152, 0xc1f00000, v152
	v_mul_f32_e32 v152, 0xbfb8aa3b, v152
	v_mul_f32_e32 v35, 0xbfb8aa3b, v35
	v_exp_f32_e32 v165, v153
	v_cvt_f32_f16_e32 v153, v155
	v_exp_f32_e32 v174, v152
	v_cvt_f32_f16_sdwa v152, v155 dst_sel:DWORD dst_unused:UNUSED_PAD src0_sel:WORD_1
	v_exp_f32_e32 v35, v35
	v_max_f32_e32 v32, 0xc1f00000, v32
	v_mul_f32_e32 v32, 0xbfb8aa3b, v32
	v_exp_f32_e32 v32, v32
	v_max_f32_e32 v153, 0xc1f00000, v153
	v_max_f32_e32 v152, 0xc1f00000, v152
	v_mul_f32_e32 v153, 0xbfb8aa3b, v153
	v_mul_f32_e32 v152, 0xbfb8aa3b, v152
	v_add_f32_e32 v35, 1.0, v35
	v_exp_f32_e32 v175, v153
	v_exp_f32_e32 v176, v152
	v_rcp_f32_e32 v152, v35
	v_add_f32_e32 v35, 1.0, v161
	v_rcp_f32_e32 v153, v35
	v_add_f32_e32 v35, 1.0, v163
	v_add_f32_e32 v32, 1.0, v32
	v_rcp_f32_e32 v154, v35
	v_add_f32_e32 v35, 1.0, v165
	v_rcp_f32_e32 v32, v32
	v_rcp_f32_e32 v155, v35
	v_add_f32_e32 v35, 1.0, v174
	v_rcp_f32_e32 v174, v35
	v_add_f32_e32 v35, 1.0, v175
	v_rcp_f32_e32 v175, v35
	v_add_f32_e32 v35, 1.0, v176
	v_mov_b32_e32 v176, v57
	v_mov_b32_e32 v177, v58
	v_pk_mul_f32 v[152:153], v[176:177], v[152:153]
	v_pk_mov_b32 v[176:177], v[58:59], v[52:53] op_sel:[1,0]
	v_fma_mixlo_f16 v32, v56, v32, 0
	v_cvt_pk_f16_f32 v153, v152, v153
	v_pk_mul_f32 v[154:155], v[176:177], v[154:155]
	v_rcp_f32_e32 v35, v35
	v_pack_b32_f16 v152, v32, v153
	v_cvt_pk_f16_f32 v32, v154, v155
	v_mov_b32_e32 v154, v53
	v_mov_b32_e32 v155, v54
	v_pk_mul_f32 v[154:155], v[154:155], v[174:175]
	v_alignbit_b32 v153, v32, v153, 16
	v_cvt_pk_f16_f32 v155, v154, v155
	v_alignbit_b32 v154, v155, v32, 16
	v_lshrrev_b32_e32 v155, 16, v155
	v_fma_mixhi_f16 v155, v55, v35, 0
	v_cvt_f32_f16_e32 v32, v148
	v_cvt_f32_f16_sdwa v35, v148 dst_sel:DWORD dst_unused:UNUSED_PAD src0_sel:WORD_1
	v_cvt_f32_f16_e32 v148, v149
	v_cvt_f32_f16_sdwa v149, v149 dst_sel:DWORD dst_unused:UNUSED_PAD src0_sel:WORD_1
	v_lshl_add_u64 v[168:169], s[14:15], 0, v[168:169]
	v_lshl_add_u64 v[168:169], v[168:169], 0, v[166:167]
	v_max_f32_e32 v148, 0xc1f00000, v148
	v_mul_f32_e32 v148, 0xbfb8aa3b, v148
	global_store_dwordx4 v[168:169], v[152:155], off
	v_max_f32_e32 v35, 0xc1f00000, v35
	v_mul_f32_e32 v35, 0xbfb8aa3b, v35
	v_exp_f32_e32 v152, v148
	v_max_f32_e32 v148, 0xc1f00000, v149
	v_mul_f32_e32 v148, 0xbfb8aa3b, v148
	v_cvt_f32_f16_e32 v149, v150
	v_exp_f32_e32 v153, v148
	v_cvt_f32_f16_sdwa v148, v150 dst_sel:DWORD dst_unused:UNUSED_PAD src0_sel:WORD_1
	v_exp_f32_e32 v35, v35
	v_max_f32_e32 v149, 0xc1f00000, v149
	v_mul_f32_e32 v149, 0xbfb8aa3b, v149
	v_max_f32_e32 v148, 0xc1f00000, v148
	v_mul_f32_e32 v148, 0xbfb8aa3b, v148
	v_exp_f32_e32 v154, v149
	v_cvt_f32_f16_e32 v149, v151
	v_exp_f32_e32 v155, v148
	v_cvt_f32_f16_sdwa v148, v151 dst_sel:DWORD dst_unused:UNUSED_PAD src0_sel:WORD_1
	v_max_f32_e32 v32, 0xc1f00000, v32
	v_mul_f32_e32 v32, 0xbfb8aa3b, v32
	v_exp_f32_e32 v32, v32
	v_max_f32_e32 v149, 0xc1f00000, v149
	v_max_f32_e32 v148, 0xc1f00000, v148
	v_mul_f32_e32 v149, 0xbfb8aa3b, v149
	v_mul_f32_e32 v148, 0xbfb8aa3b, v148
	v_add_f32_e32 v35, 1.0, v35
	v_exp_f32_e32 v161, v149
	v_exp_f32_e32 v163, v148
	v_rcp_f32_e32 v148, v35
	v_add_f32_e32 v35, 1.0, v152
	v_rcp_f32_e32 v149, v35
	v_add_f32_e32 v35, 1.0, v153
	v_add_f32_e32 v32, 1.0, v32
	v_rcp_f32_e32 v150, v35
	v_add_f32_e32 v35, 1.0, v154
	v_rcp_f32_e32 v32, v32
	v_rcp_f32_e32 v151, v35
	v_add_f32_e32 v35, 1.0, v155
	v_rcp_f32_e32 v152, v35
	v_add_f32_e32 v35, 1.0, v161
	v_rcp_f32_e32 v153, v35
	v_mov_b32_e32 v154, v21
	v_mov_b32_e32 v155, v22
	v_pk_mul_f32 v[148:149], v[154:155], v[148:149]
	v_pk_mov_b32 v[154:155], v[22:23], v[16:17] op_sel:[1,0]
	v_add_f32_e32 v35, 1.0, v163
	v_fma_mixlo_f16 v32, v20, v32, 0
	v_cvt_pk_f16_f32 v149, v148, v149
	v_pk_mul_f32 v[150:151], v[154:155], v[150:151]
	v_rcp_f32_e32 v35, v35
	v_pack_b32_f16 v148, v32, v149
	v_cvt_pk_f16_f32 v32, v150, v151
	v_mov_b32_e32 v150, v17
	v_mov_b32_e32 v151, v18
	v_pk_mul_f32 v[150:151], v[150:151], v[152:153]
	v_alignbit_b32 v149, v32, v149, 16
	v_cvt_pk_f16_f32 v151, v150, v151
	v_alignbit_b32 v150, v151, v32, 16
	v_lshrrev_b32_e32 v151, 16, v151
	v_fma_mixhi_f16 v151, v19, v35, 0
	v_cvt_f32_f16_e32 v32, v144
	v_cvt_f32_f16_sdwa v35, v144 dst_sel:DWORD dst_unused:UNUSED_PAD src0_sel:WORD_1
	v_cvt_f32_f16_e32 v144, v145
	v_cvt_f32_f16_sdwa v145, v145 dst_sel:DWORD dst_unused:UNUSED_PAD src0_sel:WORD_1
	global_store_dwordx4 v[168:169], v[148:151], off offset:256
	v_max_f32_e32 v35, 0xc1f00000, v35
	v_max_f32_e32 v144, 0xc1f00000, v144
	v_mul_f32_e32 v144, 0xbfb8aa3b, v144
	v_exp_f32_e32 v150, v144
	v_max_f32_e32 v144, 0xc1f00000, v145
	v_mul_f32_e32 v144, 0xbfb8aa3b, v144
	v_cvt_f32_f16_e32 v145, v146
	v_exp_f32_e32 v151, v144
	v_cvt_f32_f16_sdwa v144, v146 dst_sel:DWORD dst_unused:UNUSED_PAD src0_sel:WORD_1
	v_mul_f32_e32 v35, 0xbfb8aa3b, v35
	v_max_f32_e32 v145, 0xc1f00000, v145
	v_mul_f32_e32 v145, 0xbfb8aa3b, v145
	v_max_f32_e32 v144, 0xc1f00000, v144
	v_mul_f32_e32 v144, 0xbfb8aa3b, v144
	v_exp_f32_e32 v152, v145
	v_cvt_f32_f16_e32 v145, v147
	v_exp_f32_e32 v153, v144
	v_cvt_f32_f16_sdwa v144, v147 dst_sel:DWORD dst_unused:UNUSED_PAD src0_sel:WORD_1
	v_exp_f32_e32 v35, v35
	v_max_f32_e32 v32, 0xc1f00000, v32
	v_mul_f32_e32 v32, 0xbfb8aa3b, v32
	v_exp_f32_e32 v32, v32
	v_max_f32_e32 v145, 0xc1f00000, v145
	v_max_f32_e32 v144, 0xc1f00000, v144
	v_mul_f32_e32 v145, 0xbfb8aa3b, v145
	v_mul_f32_e32 v144, 0xbfb8aa3b, v144
	v_add_f32_e32 v35, 1.0, v35
	v_exp_f32_e32 v154, v145
	v_exp_f32_e32 v155, v144
	v_rcp_f32_e32 v144, v35
	v_add_f32_e32 v35, 1.0, v150
	v_rcp_f32_e32 v145, v35
	v_add_f32_e32 v35, 1.0, v151
	v_add_f32_e32 v32, 1.0, v32
	v_rcp_f32_e32 v146, v35
	v_add_f32_e32 v35, 1.0, v152
	v_rcp_f32_e32 v32, v32
	v_rcp_f32_e32 v147, v35
	v_add_f32_e32 v35, 1.0, v153
	v_rcp_f32_e32 v150, v35
	v_add_f32_e32 v35, 1.0, v154
	v_rcp_f32_e32 v151, v35
	v_mov_b32_e32 v152, v49
	v_mov_b32_e32 v153, v50
	v_pk_mul_f32 v[144:145], v[152:153], v[144:145]
	v_pk_mov_b32 v[152:153], v[50:51], v[44:45] op_sel:[1,0]
	v_add_f32_e32 v35, 1.0, v155
	v_fma_mixlo_f16 v32, v48, v32, 0
	v_cvt_pk_f16_f32 v145, v144, v145
	v_pk_mul_f32 v[146:147], v[152:153], v[146:147]
	v_rcp_f32_e32 v35, v35
	v_pack_b32_f16 v144, v32, v145
	v_cvt_pk_f16_f32 v32, v146, v147
	v_mov_b32_e32 v146, v45
	v_mov_b32_e32 v147, v46
	v_pk_mul_f32 v[146:147], v[146:147], v[150:151]
	v_alignbit_b32 v145, v32, v145, 16
	v_cvt_pk_f16_f32 v147, v146, v147
	v_alignbit_b32 v146, v147, v32, 16
	v_lshrrev_b32_e32 v147, 16, v147
	v_fma_mixhi_f16 v147, v47, v35, 0
	v_cvt_f32_f16_e32 v32, v140
	v_cvt_f32_f16_sdwa v35, v140 dst_sel:DWORD dst_unused:UNUSED_PAD src0_sel:WORD_1
	v_cvt_f32_f16_e32 v140, v141
	v_cvt_f32_f16_sdwa v141, v141 dst_sel:DWORD dst_unused:UNUSED_PAD src0_sel:WORD_1
	v_lshlrev_b64 v[148:149], 11, v[172:173]
	v_lshl_add_u64 v[148:149], s[14:15], 0, v[148:149]
	v_max_f32_e32 v140, 0xc1f00000, v140
	v_lshl_add_u64 v[148:149], v[148:149], 0, v[166:167]
	v_mul_f32_e32 v140, 0xbfb8aa3b, v140
	global_store_dwordx4 v[148:149], v[144:147], off
	v_max_f32_e32 v35, 0xc1f00000, v35
	v_mul_f32_e32 v35, 0xbfb8aa3b, v35
	v_exp_f32_e32 v144, v140
	v_max_f32_e32 v140, 0xc1f00000, v141
	v_mul_f32_e32 v140, 0xbfb8aa3b, v140
	v_cvt_f32_f16_e32 v141, v142
	v_exp_f32_e32 v145, v140
	v_cvt_f32_f16_sdwa v140, v142 dst_sel:DWORD dst_unused:UNUSED_PAD src0_sel:WORD_1
	v_exp_f32_e32 v35, v35
	v_max_f32_e32 v141, 0xc1f00000, v141
	v_mul_f32_e32 v141, 0xbfb8aa3b, v141
	v_max_f32_e32 v140, 0xc1f00000, v140
	v_mul_f32_e32 v140, 0xbfb8aa3b, v140
	v_exp_f32_e32 v146, v141
	v_cvt_f32_f16_e32 v141, v143
	v_exp_f32_e32 v147, v140
	v_cvt_f32_f16_sdwa v140, v143 dst_sel:DWORD dst_unused:UNUSED_PAD src0_sel:WORD_1
	v_max_f32_e32 v32, 0xc1f00000, v32
	v_mul_f32_e32 v32, 0xbfb8aa3b, v32
	v_exp_f32_e32 v32, v32
	v_max_f32_e32 v141, 0xc1f00000, v141
	v_max_f32_e32 v140, 0xc1f00000, v140
	v_mul_f32_e32 v141, 0xbfb8aa3b, v141
	v_mul_f32_e32 v140, 0xbfb8aa3b, v140
	v_add_f32_e32 v35, 1.0, v35
	v_exp_f32_e32 v150, v141
	v_exp_f32_e32 v151, v140
	v_rcp_f32_e32 v140, v35
	v_add_f32_e32 v35, 1.0, v144
	v_rcp_f32_e32 v141, v35
	v_add_f32_e32 v35, 1.0, v145
	v_add_f32_e32 v32, 1.0, v32
	v_rcp_f32_e32 v142, v35
	v_add_f32_e32 v35, 1.0, v146
	v_rcp_f32_e32 v32, v32
	v_rcp_f32_e32 v143, v35
	v_add_f32_e32 v35, 1.0, v147
	v_rcp_f32_e32 v144, v35
	v_add_f32_e32 v35, 1.0, v150
	v_rcp_f32_e32 v145, v35
	v_mov_b32_e32 v146, v13
	v_mov_b32_e32 v147, v14
	v_pk_mul_f32 v[140:141], v[146:147], v[140:141]
	v_pk_mov_b32 v[146:147], v[14:15], v[8:9] op_sel:[1,0]
	v_add_f32_e32 v35, 1.0, v151
	v_fma_mixlo_f16 v32, v12, v32, 0
	v_cvt_pk_f16_f32 v141, v140, v141
	v_pk_mul_f32 v[142:143], v[146:147], v[142:143]
	v_rcp_f32_e32 v35, v35
	v_pack_b32_f16 v140, v32, v141
	v_cvt_pk_f16_f32 v32, v142, v143
	v_mov_b32_e32 v142, v9
	v_mov_b32_e32 v143, v10
	v_pk_mul_f32 v[142:143], v[142:143], v[144:145]
	v_alignbit_b32 v141, v32, v141, 16
	v_cvt_pk_f16_f32 v143, v142, v143
	v_alignbit_b32 v142, v143, v32, 16
	v_lshrrev_b32_e32 v143, 16, v143
	v_fma_mixhi_f16 v143, v11, v35, 0
	v_cvt_f32_f16_e32 v32, v136
	v_cvt_f32_f16_sdwa v35, v136 dst_sel:DWORD dst_unused:UNUSED_PAD src0_sel:WORD_1
	v_cvt_f32_f16_e32 v136, v137
	v_cvt_f32_f16_sdwa v137, v137 dst_sel:DWORD dst_unused:UNUSED_PAD src0_sel:WORD_1
	global_store_dwordx4 v[148:149], v[140:143], off offset:256
	v_max_f32_e32 v35, 0xc1f00000, v35
	v_max_f32_e32 v136, 0xc1f00000, v136
	v_mul_f32_e32 v136, 0xbfb8aa3b, v136
	v_exp_f32_e32 v142, v136
	v_max_f32_e32 v136, 0xc1f00000, v137
	v_mul_f32_e32 v136, 0xbfb8aa3b, v136
	v_cvt_f32_f16_e32 v137, v138
	v_exp_f32_e32 v143, v136
	v_cvt_f32_f16_sdwa v136, v138 dst_sel:DWORD dst_unused:UNUSED_PAD src0_sel:WORD_1
	v_mul_f32_e32 v35, 0xbfb8aa3b, v35
	v_max_f32_e32 v137, 0xc1f00000, v137
	v_mul_f32_e32 v137, 0xbfb8aa3b, v137
	v_max_f32_e32 v136, 0xc1f00000, v136
	v_mul_f32_e32 v136, 0xbfb8aa3b, v136
	v_exp_f32_e32 v144, v137
	v_cvt_f32_f16_e32 v137, v139
	v_exp_f32_e32 v145, v136
	v_cvt_f32_f16_sdwa v136, v139 dst_sel:DWORD dst_unused:UNUSED_PAD src0_sel:WORD_1
	v_exp_f32_e32 v35, v35
	v_max_f32_e32 v32, 0xc1f00000, v32
	v_mul_f32_e32 v32, 0xbfb8aa3b, v32
	v_exp_f32_e32 v32, v32
	v_max_f32_e32 v137, 0xc1f00000, v137
	v_max_f32_e32 v136, 0xc1f00000, v136
	v_mul_f32_e32 v137, 0xbfb8aa3b, v137
	v_mul_f32_e32 v136, 0xbfb8aa3b, v136
	v_add_f32_e32 v35, 1.0, v35
	v_exp_f32_e32 v146, v137
	v_exp_f32_e32 v147, v136
	v_rcp_f32_e32 v136, v35
	v_add_f32_e32 v35, 1.0, v142
	v_rcp_f32_e32 v137, v35
	v_add_f32_e32 v35, 1.0, v143
	v_add_f32_e32 v32, 1.0, v32
	v_rcp_f32_e32 v138, v35
	v_add_f32_e32 v35, 1.0, v144
	v_rcp_f32_e32 v32, v32
	v_rcp_f32_e32 v139, v35
	v_add_f32_e32 v35, 1.0, v145
	v_rcp_f32_e32 v142, v35
	v_add_f32_e32 v35, 1.0, v146
	v_rcp_f32_e32 v143, v35
	v_mov_b32_e32 v144, v41
	v_mov_b32_e32 v145, v42
	v_pk_mul_f32 v[136:137], v[144:145], v[136:137]
	v_pk_mov_b32 v[144:145], v[42:43], v[36:37] op_sel:[1,0]
	v_add_f32_e32 v35, 1.0, v147
	v_fma_mixlo_f16 v32, v40, v32, 0
	v_cvt_pk_f16_f32 v137, v136, v137
	v_pk_mul_f32 v[138:139], v[144:145], v[138:139]
	v_rcp_f32_e32 v35, v35
	v_pack_b32_f16 v136, v32, v137
	v_cvt_pk_f16_f32 v32, v138, v139
	v_mov_b32_e32 v138, v37
	v_mov_b32_e32 v139, v38
	v_pk_mul_f32 v[138:139], v[138:139], v[142:143]
	v_alignbit_b32 v137, v32, v137, 16
	v_cvt_pk_f16_f32 v139, v138, v139
	v_alignbit_b32 v138, v139, v32, 16
	v_lshrrev_b32_e32 v139, 16, v139
	v_fma_mixhi_f16 v139, v39, v35, 0
	v_cvt_f32_f16_e32 v32, v132
	v_cvt_f32_f16_sdwa v35, v132 dst_sel:DWORD dst_unused:UNUSED_PAD src0_sel:WORD_1
	v_cvt_f32_f16_e32 v132, v133
	v_cvt_f32_f16_sdwa v133, v133 dst_sel:DWORD dst_unused:UNUSED_PAD src0_sel:WORD_1
	v_lshlrev_b64 v[140:141], 11, v[170:171]
	v_lshl_add_u64 v[140:141], s[14:15], 0, v[140:141]
	v_max_f32_e32 v132, 0xc1f00000, v132
	v_lshl_add_u64 v[140:141], v[140:141], 0, v[166:167]
	v_mul_f32_e32 v132, 0xbfb8aa3b, v132
	global_store_dwordx4 v[140:141], v[136:139], off
	v_max_f32_e32 v35, 0xc1f00000, v35
	v_mul_f32_e32 v35, 0xbfb8aa3b, v35
	v_exp_f32_e32 v136, v132
	v_max_f32_e32 v132, 0xc1f00000, v133
	v_mul_f32_e32 v132, 0xbfb8aa3b, v132
	v_cvt_f32_f16_e32 v133, v134
	v_exp_f32_e32 v137, v132
	v_cvt_f32_f16_sdwa v132, v134 dst_sel:DWORD dst_unused:UNUSED_PAD src0_sel:WORD_1
	v_exp_f32_e32 v35, v35
	v_max_f32_e32 v133, 0xc1f00000, v133
	v_mul_f32_e32 v133, 0xbfb8aa3b, v133
	v_max_f32_e32 v132, 0xc1f00000, v132
	v_mul_f32_e32 v132, 0xbfb8aa3b, v132
	v_exp_f32_e32 v138, v133
	v_cvt_f32_f16_e32 v133, v135
	v_exp_f32_e32 v139, v132
	v_cvt_f32_f16_sdwa v132, v135 dst_sel:DWORD dst_unused:UNUSED_PAD src0_sel:WORD_1
	v_max_f32_e32 v32, 0xc1f00000, v32
	v_mul_f32_e32 v32, 0xbfb8aa3b, v32
	v_exp_f32_e32 v32, v32
	v_max_f32_e32 v133, 0xc1f00000, v133
	v_max_f32_e32 v132, 0xc1f00000, v132
	v_mul_f32_e32 v133, 0xbfb8aa3b, v133
	v_mul_f32_e32 v132, 0xbfb8aa3b, v132
	v_add_f32_e32 v35, 1.0, v35
	v_exp_f32_e32 v142, v133
	v_exp_f32_e32 v143, v132
	v_rcp_f32_e32 v132, v35
	v_add_f32_e32 v35, 1.0, v136
	v_rcp_f32_e32 v133, v35
	v_add_f32_e32 v35, 1.0, v137
	v_add_f32_e32 v32, 1.0, v32
	v_rcp_f32_e32 v134, v35
	v_add_f32_e32 v35, 1.0, v138
	v_rcp_f32_e32 v32, v32
	v_rcp_f32_e32 v135, v35
	v_add_f32_e32 v35, 1.0, v139
	v_rcp_f32_e32 v136, v35
	v_add_f32_e32 v35, 1.0, v142
	v_rcp_f32_e32 v137, v35
	v_mov_b32_e32 v138, v5
	v_mov_b32_e32 v139, v6
	v_pk_mul_f32 v[132:133], v[138:139], v[132:133]
	v_pk_mov_b32 v[138:139], v[6:7], v[0:1] op_sel:[1,0]
	v_add_f32_e32 v35, 1.0, v143
	v_fma_mixlo_f16 v32, v4, v32, 0
	v_cvt_pk_f16_f32 v133, v132, v133
	v_pk_mul_f32 v[134:135], v[138:139], v[134:135]
	v_rcp_f32_e32 v35, v35
	v_pack_b32_f16 v132, v32, v133
	v_cvt_pk_f16_f32 v32, v134, v135
	v_mov_b32_e32 v134, v1
	v_mov_b32_e32 v135, v2
	v_pk_mul_f32 v[134:135], v[134:135], v[136:137]
	v_alignbit_b32 v133, v32, v133, 16
	v_cvt_pk_f16_f32 v135, v134, v135
	v_alignbit_b32 v134, v135, v32, 16
	v_lshrrev_b32_e32 v135, 16, v135
	v_fma_mixhi_f16 v135, v3, v35, 0
	global_store_dwordx4 v[140:141], v[132:135], off offset:256
	s_cbranch_execnz .LBB0_944

.LBB0_958:
	s_add_u32 s12, s10, 0x100
	s_addc_u32 s13, s11, 0
	s_add_i32 s38, 0, 0x10000
	v_add_u32_e32 v142, s38, v196
	ds_read_b128 v[122:125], v142
	ds_read_b128 v[138:141], v142 offset:2048
	ds_read_b128 v[130:133], v142 offset:1024
	ds_read_b128 v[142:145], v142 offset:3072
	s_cmp_eq_u32 s37, 12
	s_cselect_b32 s17, s7, s13
	s_cselect_b32 s16, s6, s12
	s_cselect_b32 s15, s9, s36
	s_cselect_b32 s14, s8, s35
	v_lshl_add_u64 v[230:231], s[10:11], 0, v[188:189]
	s_add_i32 m0, s21, 0xc000
	ds_read_b128 v[146:149], v198
	ds_read_b128 v[192:195], v198 offset:2048
	ds_read_b128 v[204:207], v198 offset:4096
	ds_read_b128 v[212:215], v198 offset:6144
	ds_read_b128 v[150:153], v198 offset:1024
	ds_read_b128 v[200:203], v198 offset:3072
	ds_read_b128 v[208:211], v198 offset:5120
	ds_read_b128 v[216:219], v198 offset:7168
	global_load_lds_dwordx4 v[230:231], off
	v_lshl_add_u64 v[230:231], s[10:11], 0, v[190:191]
	s_add_i32 m0, s21, 0xe000
	s_nop 0
	global_load_lds_dwordx4 v[230:231], off
	s_waitcnt lgkmcnt(8)
	s_barrier
	s_waitcnt lgkmcnt(7)
	s_setprio 1
	v_mfma_f32_16x16x32_f16 v[134:137], v[122:125], v[146:149], v[134:137]
	v_mfma_f32_16x16x32_f16 v[126:129], v[138:141], v[146:149], v[126:129]
	s_waitcnt lgkmcnt(6)
	v_mfma_f32_16x16x32_f16 v[110:113], v[122:125], v[192:195], v[110:113]
	v_mfma_f32_16x16x32_f16 v[106:109], v[138:141], v[192:195], v[106:109]
	s_waitcnt lgkmcnt(5)
	v_mfma_f32_16x16x32_f16 v[94:97], v[122:125], v[204:207], v[94:97]
	v_mfma_f32_16x16x32_f16 v[90:93], v[138:141], v[204:207], v[90:93]
	s_waitcnt lgkmcnt(4)
	v_mfma_f32_16x16x32_f16 v[78:81], v[122:125], v[212:215], v[78:81]
	v_mfma_f32_16x16x32_f16 v[74:77], v[138:141], v[212:215], v[74:77]
	s_waitcnt lgkmcnt(3)
	v_mfma_f32_16x16x32_f16 v[134:137], v[130:133], v[150:153], v[134:137]
	v_mfma_f32_16x16x32_f16 v[126:129], v[142:145], v[150:153], v[126:129]
	s_waitcnt lgkmcnt(2)
	v_mfma_f32_16x16x32_f16 v[110:113], v[130:133], v[200:203], v[110:113]
	v_mfma_f32_16x16x32_f16 v[106:109], v[142:145], v[200:203], v[106:109]
	s_waitcnt lgkmcnt(1)
	v_mfma_f32_16x16x32_f16 v[94:97], v[130:133], v[208:211], v[94:97]
	v_mfma_f32_16x16x32_f16 v[90:93], v[142:145], v[208:211], v[90:93]
	s_waitcnt lgkmcnt(0)
	v_mfma_f32_16x16x32_f16 v[78:81], v[130:133], v[216:219], v[78:81]
	v_mfma_f32_16x16x32_f16 v[74:77], v[142:145], v[216:219], v[74:77]
	s_setprio 0
	s_barrier
	s_add_i32 s39, 0, 0x14000
	s_add_i32 s10, s38, s20
	v_add_u32_e32 v199, s39, v196
	v_lshl_add_u64 v[246:247], s[14:15], 0, v[32:33]
	s_mov_b32 m0, s10
	ds_read_b128 v[230:233], v199
	ds_read_b128 v[238:241], v199 offset:2048
	ds_read_b128 v[234:237], v199 offset:1024
	ds_read_b128 v[242:245], v199 offset:3072
	global_load_lds_dwordx4 v[246:247], off
	v_lshl_add_u64 v[248:249], s[14:15], 0, v[154:155]
	s_add_i32 m0, s10, 0x2000
	s_nop 0
	global_load_lds_dwordx4 v[248:249], off
	s_barrier
	s_waitcnt lgkmcnt(2)
	s_setprio 1
	v_mfma_f32_16x16x32_f16 v[118:121], v[230:233], v[146:149], v[118:121]
	v_mfma_f32_16x16x32_f16 v[114:117], v[238:241], v[146:149], v[114:117]
	v_mfma_f32_16x16x32_f16 v[102:105], v[230:233], v[192:195], v[102:105]
	v_mfma_f32_16x16x32_f16 v[98:101], v[238:241], v[192:195], v[98:101]
	v_mfma_f32_16x16x32_f16 v[86:89], v[230:233], v[204:207], v[86:89]
	v_mfma_f32_16x16x32_f16 v[82:85], v[238:241], v[204:207], v[82:85]
	v_mfma_f32_16x16x32_f16 v[70:73], v[230:233], v[212:215], v[70:73]
	v_mfma_f32_16x16x32_f16 v[66:69], v[238:241], v[212:215], v[66:69]
	s_waitcnt lgkmcnt(0)
	v_mfma_f32_16x16x32_f16 v[118:121], v[234:237], v[150:153], v[118:121]
	v_mfma_f32_16x16x32_f16 v[114:117], v[242:245], v[150:153], v[114:117]
	v_mfma_f32_16x16x32_f16 v[102:105], v[234:237], v[200:203], v[102:105]
	v_mfma_f32_16x16x32_f16 v[98:101], v[242:245], v[200:203], v[98:101]
	v_mfma_f32_16x16x32_f16 v[86:89], v[234:237], v[208:211], v[86:89]
	v_mfma_f32_16x16x32_f16 v[82:85], v[242:245], v[208:211], v[82:85]
	v_mfma_f32_16x16x32_f16 v[70:73], v[234:237], v[216:219], v[70:73]
	v_mfma_f32_16x16x32_f16 v[66:69], v[242:245], v[216:219], v[66:69]
	s_setprio 0
	s_mov_b32 m0, s21
	v_lshl_add_u64 v[228:229], s[16:17], 0, v[32:33]
	s_barrier
	ds_read_b128 v[146:149], v198 offset:16384
	ds_read_b128 v[192:195], v198 offset:18432
	ds_read_b128 v[204:207], v198 offset:20480
	ds_read_b128 v[212:215], v198 offset:22528
	ds_read_b128 v[150:153], v198 offset:17408
	ds_read_b128 v[200:203], v198 offset:19456
	ds_read_b128 v[208:211], v198 offset:21504
	ds_read_b128 v[216:219], v198 offset:23552
	global_load_lds_dwordx4 v[228:229], off
	v_lshl_add_u64 v[222:223], s[16:17], 0, v[154:155]
	s_mov_b32 m0, s22
	s_nop 0
	global_load_lds_dwordx4 v[222:223], off
	s_barrier
	s_waitcnt lgkmcnt(7)
	s_setprio 1
	v_mfma_f32_16x16x32_f16 v[62:65], v[122:125], v[146:149], v[62:65]
	v_mfma_f32_16x16x32_f16 v[58:61], v[138:141], v[146:149], v[58:61]
	s_waitcnt lgkmcnt(6)
	v_mfma_f32_16x16x32_f16 v[46:49], v[122:125], v[192:195], v[46:49]
	v_mfma_f32_16x16x32_f16 v[42:45], v[138:141], v[192:195], v[42:45]
	s_waitcnt lgkmcnt(5)
	v_mfma_f32_16x16x32_f16 v[28:31], v[122:125], v[204:207], v[28:31]
	v_mfma_f32_16x16x32_f16 v[24:27], v[138:141], v[204:207], v[24:27]
	s_waitcnt lgkmcnt(4)
	v_mfma_f32_16x16x32_f16 v[12:15], v[122:125], v[212:215], v[12:15]
	v_mfma_f32_16x16x32_f16 v[8:11], v[138:141], v[212:215], v[8:11]
	s_waitcnt lgkmcnt(3)
	v_mfma_f32_16x16x32_f16 v[62:65], v[130:133], v[150:153], v[62:65]
	v_mfma_f32_16x16x32_f16 v[58:61], v[142:145], v[150:153], v[58:61]
	s_waitcnt lgkmcnt(2)
	v_mfma_f32_16x16x32_f16 v[46:49], v[130:133], v[200:203], v[46:49]
	v_mfma_f32_16x16x32_f16 v[42:45], v[142:145], v[200:203], v[42:45]
	s_waitcnt lgkmcnt(1)
	v_mfma_f32_16x16x32_f16 v[28:31], v[130:133], v[208:211], v[28:31]
	v_mfma_f32_16x16x32_f16 v[24:27], v[142:145], v[208:211], v[24:27]
	s_waitcnt lgkmcnt(0)
	v_mfma_f32_16x16x32_f16 v[12:15], v[130:133], v[216:219], v[12:15]
	v_mfma_f32_16x16x32_f16 v[8:11], v[142:145], v[216:219], v[8:11]
	s_setprio 0
	s_barrier
	s_add_u32 s10, s14, 0x40000
	s_addc_u32 s11, s15, 0
	s_add_i32 s38, s39, s20
	v_lshl_add_u64 v[122:123], s[10:11], 0, v[32:33]
	s_mov_b32 m0, s38
	s_nop 0
	global_load_lds_dwordx4 v[122:123], off
	v_lshl_add_u64 v[122:123], s[10:11], 0, v[154:155]
	s_add_i32 m0, s38, 0x2000
	s_nop 0
	global_load_lds_dwordx4 v[122:123], off
	s_waitcnt vmcnt(6)
	s_barrier
	s_setprio 1
	v_mfma_f32_16x16x32_f16 v[54:57], v[230:233], v[146:149], v[54:57]
	v_mfma_f32_16x16x32_f16 v[50:53], v[238:241], v[146:149], v[50:53]
	v_mfma_f32_16x16x32_f16 v[38:41], v[230:233], v[192:195], v[38:41]
	v_mfma_f32_16x16x32_f16 v[34:37], v[238:241], v[192:195], v[34:37]
	v_mfma_f32_16x16x32_f16 v[20:23], v[230:233], v[204:207], v[20:23]
	v_mfma_f32_16x16x32_f16 v[16:19], v[238:241], v[204:207], v[16:19]
	v_mfma_f32_16x16x32_f16 v[4:7], v[230:233], v[212:215], v[4:7]
	v_mfma_f32_16x16x32_f16 v[0:3], v[238:241], v[212:215], v[0:3]
	v_mfma_f32_16x16x32_f16 v[54:57], v[234:237], v[150:153], v[54:57]
	v_mfma_f32_16x16x32_f16 v[50:53], v[242:245], v[150:153], v[50:53]
	v_mfma_f32_16x16x32_f16 v[38:41], v[234:237], v[200:203], v[38:41]
	v_mfma_f32_16x16x32_f16 v[34:37], v[242:245], v[200:203], v[34:37]
	v_mfma_f32_16x16x32_f16 v[20:23], v[234:237], v[208:211], v[20:23]
	v_mfma_f32_16x16x32_f16 v[16:19], v[242:245], v[208:211], v[16:19]
	v_mfma_f32_16x16x32_f16 v[4:7], v[234:237], v[216:219], v[4:7]
	v_mfma_f32_16x16x32_f16 v[0:3], v[242:245], v[216:219], v[0:3]
	s_setprio 0
	s_add_i32 s38, 0, 0x18000
	v_add_u32_e32 v142, s38, v196
	s_barrier
	ds_read_b128 v[122:125], v142
	ds_read_b128 v[138:141], v142 offset:2048
	ds_read_b128 v[130:133], v142 offset:1024
	ds_read_b128 v[142:145], v142 offset:3072
	s_add_u32 s10, s16, 0x40000
	s_addc_u32 s11, s17, 0
	s_mov_b32 m0, s23
	v_lshl_add_u64 v[230:231], s[10:11], 0, v[32:33]
	ds_read_b128 v[146:149], v198 offset:32768
	ds_read_b128 v[192:195], v198 offset:34816
	ds_read_b128 v[204:207], v198 offset:36864
	ds_read_b128 v[212:215], v198 offset:38912
	ds_read_b128 v[150:153], v198 offset:33792
	ds_read_b128 v[200:203], v198 offset:35840
	ds_read_b128 v[208:211], v198 offset:37888
	ds_read_b128 v[216:219], v198 offset:39936
	global_load_lds_dwordx4 v[230:231], off
	v_lshl_add_u64 v[230:231], s[10:11], 0, v[154:155]
	s_mov_b32 m0, s24
	s_nop 0
	global_load_lds_dwordx4 v[230:231], off
	s_waitcnt lgkmcnt(8)
	s_barrier
	s_waitcnt lgkmcnt(7)
	s_setprio 1
	v_mfma_f32_16x16x32_f16 v[134:137], v[122:125], v[146:149], v[134:137]
	v_mfma_f32_16x16x32_f16 v[126:129], v[138:141], v[146:149], v[126:129]
	s_waitcnt lgkmcnt(6)
	v_mfma_f32_16x16x32_f16 v[110:113], v[122:125], v[192:195], v[110:113]
	v_mfma_f32_16x16x32_f16 v[106:109], v[138:141], v[192:195], v[106:109]
	s_waitcnt lgkmcnt(5)
	v_mfma_f32_16x16x32_f16 v[94:97], v[122:125], v[204:207], v[94:97]
	v_mfma_f32_16x16x32_f16 v[90:93], v[138:141], v[204:207], v[90:93]
	s_waitcnt lgkmcnt(4)
	v_mfma_f32_16x16x32_f16 v[78:81], v[122:125], v[212:215], v[78:81]
	v_mfma_f32_16x16x32_f16 v[74:77], v[138:141], v[212:215], v[74:77]
	s_waitcnt lgkmcnt(3)
	v_mfma_f32_16x16x32_f16 v[134:137], v[130:133], v[150:153], v[134:137]
	v_mfma_f32_16x16x32_f16 v[126:129], v[142:145], v[150:153], v[126:129]
	s_waitcnt lgkmcnt(2)
	v_mfma_f32_16x16x32_f16 v[110:113], v[130:133], v[200:203], v[110:113]
	v_mfma_f32_16x16x32_f16 v[106:109], v[142:145], v[200:203], v[106:109]
	s_waitcnt lgkmcnt(1)
	v_mfma_f32_16x16x32_f16 v[94:97], v[130:133], v[208:211], v[94:97]
	v_mfma_f32_16x16x32_f16 v[90:93], v[142:145], v[208:211], v[90:93]
	s_waitcnt lgkmcnt(0)
	v_mfma_f32_16x16x32_f16 v[78:81], v[130:133], v[216:219], v[78:81]
	v_mfma_f32_16x16x32_f16 v[74:77], v[142:145], v[216:219], v[74:77]
	s_setprio 0
	s_barrier
	s_add_i32 s16, 0, 0x1c000
	s_add_i32 s10, s38, s20
	v_add_u32_e32 v199, s16, v196
	v_lshl_add_u64 v[246:247], v[246:247], 0, s[84:85]
	s_mov_b32 m0, s10
	ds_read_b128 v[230:233], v199
	ds_read_b128 v[238:241], v199 offset:2048
	ds_read_b128 v[234:237], v199 offset:1024
	ds_read_b128 v[242:245], v199 offset:3072
	global_load_lds_dwordx4 v[246:247], off
	v_lshl_add_u64 v[246:247], v[248:249], 0, s[84:85]
	s_add_i32 m0, s10, 0x2000
	s_nop 0
	global_load_lds_dwordx4 v[246:247], off
	s_barrier
	s_waitcnt lgkmcnt(2)
	s_setprio 1
	v_mfma_f32_16x16x32_f16 v[118:121], v[230:233], v[146:149], v[118:121]
	v_mfma_f32_16x16x32_f16 v[114:117], v[238:241], v[146:149], v[114:117]
	v_mfma_f32_16x16x32_f16 v[102:105], v[230:233], v[192:195], v[102:105]
	v_mfma_f32_16x16x32_f16 v[98:101], v[238:241], v[192:195], v[98:101]
	v_mfma_f32_16x16x32_f16 v[86:89], v[230:233], v[204:207], v[86:89]
	v_mfma_f32_16x16x32_f16 v[82:85], v[238:241], v[204:207], v[82:85]
	v_mfma_f32_16x16x32_f16 v[70:73], v[230:233], v[212:215], v[70:73]
	v_mfma_f32_16x16x32_f16 v[66:69], v[238:241], v[212:215], v[66:69]
	s_waitcnt lgkmcnt(0)
	v_mfma_f32_16x16x32_f16 v[118:121], v[234:237], v[150:153], v[118:121]
	v_mfma_f32_16x16x32_f16 v[114:117], v[242:245], v[150:153], v[114:117]
	v_mfma_f32_16x16x32_f16 v[102:105], v[234:237], v[200:203], v[102:105]
	v_mfma_f32_16x16x32_f16 v[98:101], v[242:245], v[200:203], v[98:101]
	v_mfma_f32_16x16x32_f16 v[86:89], v[234:237], v[208:211], v[86:89]
	v_mfma_f32_16x16x32_f16 v[82:85], v[242:245], v[208:211], v[82:85]
	v_mfma_f32_16x16x32_f16 v[70:73], v[234:237], v[216:219], v[70:73]
	v_mfma_f32_16x16x32_f16 v[66:69], v[242:245], v[216:219], v[66:69]
	s_setprio 0
	s_mov_b32 m0, s25
	v_lshl_add_u64 v[228:229], v[228:229], 0, s[84:85]
	s_barrier
	ds_read_b128 v[146:149], v198 offset:49152
	ds_read_b128 v[192:195], v198 offset:51200
	ds_read_b128 v[204:207], v198 offset:53248
	ds_read_b128 v[212:215], v198 offset:55296
	ds_read_b128 v[150:153], v198 offset:50176
	ds_read_b128 v[200:203], v198 offset:52224
	ds_read_b128 v[208:211], v198 offset:54272
	ds_read_b128 v[216:219], v198 offset:56320
	global_load_lds_dwordx4 v[228:229], off
	v_lshl_add_u64 v[222:223], v[222:223], 0, s[84:85]
	s_mov_b32 m0, s27
	s_nop 0
	global_load_lds_dwordx4 v[222:223], off
	s_barrier
	s_waitcnt lgkmcnt(7)
	s_setprio 1
	v_mfma_f32_16x16x32_f16 v[62:65], v[122:125], v[146:149], v[62:65]
	v_mfma_f32_16x16x32_f16 v[58:61], v[138:141], v[146:149], v[58:61]
	s_waitcnt lgkmcnt(6)
	v_mfma_f32_16x16x32_f16 v[46:49], v[122:125], v[192:195], v[46:49]
	v_mfma_f32_16x16x32_f16 v[42:45], v[138:141], v[192:195], v[42:45]
	s_waitcnt lgkmcnt(5)
	v_mfma_f32_16x16x32_f16 v[28:31], v[122:125], v[204:207], v[28:31]
	v_mfma_f32_16x16x32_f16 v[24:27], v[138:141], v[204:207], v[24:27]
	s_waitcnt lgkmcnt(4)
	v_mfma_f32_16x16x32_f16 v[12:15], v[122:125], v[212:215], v[12:15]
	v_mfma_f32_16x16x32_f16 v[8:11], v[138:141], v[212:215], v[8:11]
	s_waitcnt lgkmcnt(3)
	v_mfma_f32_16x16x32_f16 v[62:65], v[130:133], v[150:153], v[62:65]
	v_mfma_f32_16x16x32_f16 v[58:61], v[142:145], v[150:153], v[58:61]
	s_waitcnt lgkmcnt(2)
	v_mfma_f32_16x16x32_f16 v[46:49], v[130:133], v[200:203], v[46:49]
	v_mfma_f32_16x16x32_f16 v[42:45], v[142:145], v[200:203], v[42:45]
	s_waitcnt lgkmcnt(1)
	v_mfma_f32_16x16x32_f16 v[28:31], v[130:133], v[208:211], v[28:31]
	v_mfma_f32_16x16x32_f16 v[24:27], v[142:145], v[208:211], v[24:27]
	s_waitcnt lgkmcnt(0)
	v_mfma_f32_16x16x32_f16 v[12:15], v[130:133], v[216:219], v[12:15]
	v_mfma_f32_16x16x32_f16 v[8:11], v[142:145], v[216:219], v[8:11]
	s_setprio 0
	s_barrier
	s_add_u32 s10, s14, 0x40080
	s_addc_u32 s11, s15, 0
	s_add_i32 s14, s16, s20
	v_lshl_add_u64 v[122:123], s[10:11], 0, v[32:33]
	s_mov_b32 m0, s14
	s_nop 0
	global_load_lds_dwordx4 v[122:123], off
	v_lshl_add_u64 v[122:123], s[10:11], 0, v[154:155]
	s_add_i32 m0, s14, 0x2000
	s_nop 0
	global_load_lds_dwordx4 v[122:123], off
	s_waitcnt vmcnt(6)
	s_barrier
	s_setprio 1
	v_mfma_f32_16x16x32_f16 v[54:57], v[230:233], v[146:149], v[54:57]
	v_mfma_f32_16x16x32_f16 v[50:53], v[238:241], v[146:149], v[50:53]
	v_mfma_f32_16x16x32_f16 v[38:41], v[230:233], v[192:195], v[38:41]
	v_mfma_f32_16x16x32_f16 v[34:37], v[238:241], v[192:195], v[34:37]
	v_mfma_f32_16x16x32_f16 v[20:23], v[230:233], v[204:207], v[20:23]
	v_mfma_f32_16x16x32_f16 v[16:19], v[238:241], v[204:207], v[16:19]
	v_mfma_f32_16x16x32_f16 v[4:7], v[230:233], v[212:215], v[4:7]
	v_mfma_f32_16x16x32_f16 v[0:3], v[238:241], v[212:215], v[0:3]
	v_mfma_f32_16x16x32_f16 v[54:57], v[234:237], v[150:153], v[54:57]
	v_mfma_f32_16x16x32_f16 v[50:53], v[242:245], v[150:153], v[50:53]
	v_mfma_f32_16x16x32_f16 v[38:41], v[234:237], v[200:203], v[38:41]
	v_mfma_f32_16x16x32_f16 v[34:37], v[242:245], v[200:203], v[34:37]
	v_mfma_f32_16x16x32_f16 v[20:23], v[234:237], v[208:211], v[20:23]
	v_mfma_f32_16x16x32_f16 v[16:19], v[242:245], v[208:211], v[16:19]
	v_mfma_f32_16x16x32_f16 v[4:7], v[234:237], v[216:219], v[4:7]
	v_mfma_f32_16x16x32_f16 v[0:3], v[242:245], v[216:219], v[0:3]
	s_setprio 0
	s_add_i32 s37, s37, 2
	s_add_u32 s35, s35, 0x100
	s_addc_u32 s36, s36, 0
	s_cmp_gt_u32 s37, 13
	s_mov_b64 s[10:11], s[12:13]
	s_barrier
	s_cbranch_scc0 .LBB0_958
	s_cmp_eq_u32 s34, 2
	s_movk_i32 s6, 0x2800
	v_lshl_or_b32 v122, s31, 8, v197
	s_cselect_b32 s6, 0x2000, s6
	s_mov_b32 s7, 0x23a3c000
	s_cselect_b32 s8, s7, 0x23abc000
	s_add_u32 s6, s70, s6
	v_ashrrev_i32_e32 v123, 31, v122
	s_addc_u32 s7, s71, 0
	v_lshlrev_b64 v[192:193], 1, v[122:123]
	v_lshl_add_u64 v[194:195], s[6:7], 0, v[192:193]
	v_lshl_add_u64 v[122:123], v[194:195], 0, v[156:157]
	v_lshl_add_u64 v[124:125], v[194:195], 0, v[158:159]
	v_lshl_add_u64 v[130:131], v[194:195], 0, v[160:161]
	v_lshl_add_u64 v[208:209], v[194:195], 0, v[162:163]
	global_load_dwordx4 v[200:203], v[122:123], off
	global_load_dwordx4 v[204:207], v[122:123], off offset:256
	global_load_dwordx4 v[150:153], v[124:125], off
	global_load_dwordx4 v[146:149], v[124:125], off offset:256
	global_load_dwordx4 v[142:145], v[130:131], off
	global_load_dwordx4 v[138:141], v[130:131], off offset:256
	s_nop 0
	global_load_dwordx4 v[130:133], v[208:209], off
	global_load_dwordx4 v[122:125], v[208:209], off offset:256
	v_readlane_b32 s36, v252, 26
	v_readlane_b32 s42, v252, 32
	v_readlane_b32 s43, v252, 33
	s_add_u32 s6, s42, s8
	s_addc_u32 s7, s43, 0
	v_readlane_b32 s37, v252, 27
	v_readlane_b32 s38, v252, 28
	v_readlane_b32 s39, v252, 29
	v_readlane_b32 s40, v252, 30
	v_readlane_b32 s41, v252, 31
	v_lshl_add_u64 v[192:193], s[6:7], 0, v[192:193]
	s_waitcnt vmcnt(0)
	v_cvt_f32_f16_e32 v199, v200
	v_cvt_f32_f16_sdwa v200, v200 dst_sel:DWORD dst_unused:UNUSED_PAD src0_sel:WORD_1
	v_cvt_f32_f16_e32 v210, v201
	v_lshl_add_u64 v[208:209], v[192:193], 0, v[164:165]
	v_max_f32_e32 v199, 0xc1f00000, v199
	v_mul_f32_e32 v199, 0xbfb8aa3b, v199
	v_exp_f32_e32 v199, v199
	v_max_f32_e32 v200, 0xc1f00000, v200
	v_max_f32_e32 v210, 0xc1f00000, v210
	v_mul_f32_e32 v200, 0xbfb8aa3b, v200
	v_add_f32_e32 v199, 1.0, v199
	v_rcp_f32_e32 v199, v199
	v_exp_f32_e32 v200, v200
	v_mul_f32_e32 v210, 0xbfb8aa3b, v210
	v_exp_f32_e32 v211, v210
	v_fma_mixlo_f16 v199, v134, v199, 0
	v_add_f32_e32 v134, 1.0, v200
	v_rcp_f32_e32 v210, v134
	v_add_f32_e32 v134, 1.0, v211
	v_cvt_f32_f16_sdwa v200, v201 dst_sel:DWORD dst_unused:UNUSED_PAD src0_sel:WORD_1
	v_rcp_f32_e32 v211, v134
	v_mov_b32_e32 v134, v135
	v_mov_b32_e32 v135, v136
	v_cvt_f32_f16_e32 v136, v202
	v_max_f32_e32 v200, 0xc1f00000, v200
	v_mul_f32_e32 v200, 0xbfb8aa3b, v200
	v_exp_f32_e32 v200, v200
	v_max_f32_e32 v136, 0xc1f00000, v136
	v_mul_f32_e32 v136, 0xbfb8aa3b, v136
	v_exp_f32_e32 v136, v136
	v_pk_mul_f32 v[134:135], v[134:135], v[210:211]
	s_nop 0
	v_cvt_pk_f16_f32 v135, v134, v135
	v_add_f32_e32 v134, 1.0, v200
	v_rcp_f32_e32 v200, v134
	v_add_f32_e32 v134, 1.0, v136
	v_rcp_f32_e32 v201, v134
	v_pk_mov_b32 v[136:137], v[136:137], v[126:127] op_sel:[1,0]
	v_cvt_f32_f16_sdwa v126, v202 dst_sel:DWORD dst_unused:UNUSED_PAD src0_sel:WORD_1
	v_pack_b32_f16 v134, v199, v135
	v_pk_mul_f32 v[136:137], v[136:137], v[200:201]
	v_cvt_f32_f16_sdwa v200, v203 dst_sel:DWORD dst_unused:UNUSED_PAD src0_sel:WORD_1
	v_cvt_pk_f16_f32 v199, v136, v137
	v_cvt_f32_f16_e32 v136, v203
	v_max_f32_e32 v126, 0xc1f00000, v126
	v_mul_f32_e32 v126, 0xbfb8aa3b, v126
	v_exp_f32_e32 v126, v126
	v_max_f32_e32 v136, 0xc1f00000, v136
	v_mul_f32_e32 v136, 0xbfb8aa3b, v136
	v_exp_f32_e32 v137, v136
	v_add_f32_e32 v126, 1.0, v126
	v_rcp_f32_e32 v136, v126
	v_alignbit_b32 v135, v199, v135, 16
	v_add_f32_e32 v126, 1.0, v137
	v_rcp_f32_e32 v137, v126
	v_mov_b32_e32 v126, v127
	v_mov_b32_e32 v127, v128
	v_cvt_f32_f16_e32 v128, v204
	v_pk_mul_f32 v[126:127], v[126:127], v[136:137]
	s_nop 0
	v_cvt_pk_f16_f32 v126, v126, v127
	v_max_f32_e32 v127, 0xc1f00000, v200
	v_mul_f32_e32 v127, 0xbfb8aa3b, v127
	v_exp_f32_e32 v127, v127
	v_alignbit_b32 v136, v126, v199, 16
	v_lshrrev_b32_e32 v137, 16, v126
	v_add_f32_e32 v126, 1.0, v127
	v_rcp_f32_e32 v126, v126
	v_max_f32_e32 v127, 0xc1f00000, v128
	v_mul_f32_e32 v127, 0xbfb8aa3b, v127
	v_exp_f32_e32 v127, v127
	v_fma_mixhi_f16 v137, v129, v126, 0
	v_cvt_f32_f16_sdwa v126, v204 dst_sel:DWORD dst_unused:UNUSED_PAD src0_sel:WORD_1
	v_cvt_f32_f16_e32 v128, v205
	v_add_f32_e32 v127, 1.0, v127
	v_rcp_f32_e32 v127, v127
	v_max_f32_e32 v126, 0xc1f00000, v126
	v_mul_f32_e32 v126, 0xbfb8aa3b, v126
	v_max_f32_e32 v128, 0xc1f00000, v128
	v_exp_f32_e32 v126, v126
	v_mul_f32_e32 v128, 0xbfb8aa3b, v128
	v_exp_f32_e32 v128, v128
	v_fma_mixlo_f16 v129, v118, v127, 0
	v_add_f32_e32 v118, 1.0, v126
	v_rcp_f32_e32 v126, v118
	v_add_f32_e32 v118, 1.0, v128
	v_rcp_f32_e32 v127, v118
	v_cvt_f32_f16_sdwa v128, v205 dst_sel:DWORD dst_unused:UNUSED_PAD src0_sel:WORD_1
	v_mov_b32_e32 v118, v119
	v_mov_b32_e32 v119, v120
	v_cvt_f32_f16_e32 v120, v206
	v_max_f32_e32 v128, 0xc1f00000, v128
	v_mul_f32_e32 v128, 0xbfb8aa3b, v128
	v_exp_f32_e32 v128, v128
	v_max_f32_e32 v120, 0xc1f00000, v120
	v_mul_f32_e32 v120, 0xbfb8aa3b, v120
	v_exp_f32_e32 v120, v120
	v_pk_mul_f32 v[118:119], v[118:119], v[126:127]
	v_add_f32_e32 v126, 1.0, v128
	v_rcp_f32_e32 v126, v126
	v_add_f32_e32 v120, 1.0, v120
	v_rcp_f32_e32 v127, v120
	v_pk_mov_b32 v[120:121], v[120:121], v[114:115] op_sel:[1,0]
	v_cvt_f32_f16_sdwa v114, v206 dst_sel:DWORD dst_unused:UNUSED_PAD src0_sel:WORD_1
	v_cvt_pk_f16_f32 v119, v118, v119
	v_pk_mul_f32 v[120:121], v[120:121], v[126:127]
	v_cvt_f32_f16_sdwa v127, v207 dst_sel:DWORD dst_unused:UNUSED_PAD src0_sel:WORD_1
	v_cvt_pk_f16_f32 v126, v120, v121
	v_cvt_f32_f16_e32 v120, v207
	v_max_f32_e32 v114, 0xc1f00000, v114
	v_mul_f32_e32 v114, 0xbfb8aa3b, v114
	v_exp_f32_e32 v114, v114
	v_max_f32_e32 v120, 0xc1f00000, v120
	v_mul_f32_e32 v120, 0xbfb8aa3b, v120
	v_exp_f32_e32 v121, v120
	v_add_f32_e32 v114, 1.0, v114
	v_rcp_f32_e32 v120, v114
	v_pack_b32_f16 v118, v129, v119
	v_add_f32_e32 v114, 1.0, v121
	v_rcp_f32_e32 v121, v114
	v_mov_b32_e32 v114, v115
	v_max_f32_e32 v115, 0xc1f00000, v127
	v_mul_f32_e32 v115, 0xbfb8aa3b, v115
	v_exp_f32_e32 v127, v115
	v_mov_b32_e32 v115, v116
	v_pk_mul_f32 v[114:115], v[114:115], v[120:121]
	v_cvt_f32_f16_e32 v116, v150
	v_cvt_pk_f16_f32 v114, v114, v115
	v_add_f32_e32 v115, 1.0, v127
	v_rcp_f32_e32 v115, v115
	v_alignbit_b32 v120, v114, v126, 16
	v_lshrrev_b32_e32 v121, 16, v114
	v_max_f32_e32 v114, 0xc1f00000, v116
	v_alignbit_b32 v119, v126, v119, 16
	v_fma_mixhi_f16 v121, v117, v115, 0
	v_mul_f32_e32 v114, 0xbfb8aa3b, v114
	v_cvt_f32_f16_sdwa v117, v150 dst_sel:DWORD dst_unused:UNUSED_PAD src0_sel:WORD_1
	v_exp_f32_e32 v116, v114
	global_store_dwordx4 v[208:209], v[118:121], off offset:256
	v_lshl_add_u64 v[114:115], v[192:193], 0, v[166:167]
	v_max_f32_e32 v117, 0xc1f00000, v117
	v_cvt_f32_f16_e32 v118, v151
	v_add_f32_e32 v116, 1.0, v116
	v_mul_f32_e32 v117, 0xbfb8aa3b, v117
	v_rcp_f32_e32 v116, v116
	v_max_f32_e32 v118, 0xc1f00000, v118
	v_exp_f32_e32 v117, v117
	v_mul_f32_e32 v118, 0xbfb8aa3b, v118
	v_exp_f32_e32 v118, v118
	v_fma_mixlo_f16 v119, v110, v116, 0
	v_add_f32_e32 v110, 1.0, v117
	v_rcp_f32_e32 v116, v110
	v_add_f32_e32 v110, 1.0, v118
	v_rcp_f32_e32 v117, v110
	v_cvt_f32_f16_sdwa v118, v151 dst_sel:DWORD dst_unused:UNUSED_PAD src0_sel:WORD_1
	v_mov_b32_e32 v110, v111
	v_mov_b32_e32 v111, v112
	v_cvt_f32_f16_e32 v112, v152
	v_pk_mul_f32 v[110:111], v[110:111], v[116:117]
	v_max_f32_e32 v116, 0xc1f00000, v118
	v_mul_f32_e32 v116, 0xbfb8aa3b, v116
	v_max_f32_e32 v112, 0xc1f00000, v112
	v_exp_f32_e32 v116, v116
	v_mul_f32_e32 v112, 0xbfb8aa3b, v112
	v_exp_f32_e32 v112, v112
	v_cvt_pk_f16_f32 v111, v110, v111
	v_add_f32_e32 v110, 1.0, v116
	v_rcp_f32_e32 v116, v110
	v_add_f32_e32 v110, 1.0, v112
	v_rcp_f32_e32 v117, v110
	v_pk_mov_b32 v[112:113], v[112:113], v[106:107] op_sel:[1,0]
	v_cvt_f32_f16_sdwa v106, v152 dst_sel:DWORD dst_unused:UNUSED_PAD src0_sel:WORD_1
	v_pack_b32_f16 v110, v119, v111
	v_pk_mul_f32 v[112:113], v[112:113], v[116:117]
	v_cvt_f32_f16_sdwa v117, v153 dst_sel:DWORD dst_unused:UNUSED_PAD src0_sel:WORD_1
	v_cvt_pk_f16_f32 v116, v112, v113
	v_cvt_f32_f16_e32 v112, v153
	v_max_f32_e32 v106, 0xc1f00000, v106
	v_mul_f32_e32 v106, 0xbfb8aa3b, v106
	v_exp_f32_e32 v106, v106
	v_max_f32_e32 v112, 0xc1f00000, v112
	v_mul_f32_e32 v112, 0xbfb8aa3b, v112
	v_exp_f32_e32 v113, v112
	v_add_f32_e32 v106, 1.0, v106
	v_rcp_f32_e32 v112, v106
	v_alignbit_b32 v111, v116, v111, 16
	v_add_f32_e32 v106, 1.0, v113
	v_rcp_f32_e32 v113, v106
	v_mov_b32_e32 v106, v107
	v_mov_b32_e32 v107, v108
	v_cvt_f32_f16_e32 v108, v146
	v_pk_mul_f32 v[106:107], v[106:107], v[112:113]
	global_store_dwordx4 v[208:209], v[134:137], off
	v_cvt_pk_f16_f32 v106, v106, v107
	v_max_f32_e32 v107, 0xc1f00000, v117
	v_mul_f32_e32 v107, 0xbfb8aa3b, v107
	v_exp_f32_e32 v107, v107
	v_alignbit_b32 v112, v106, v116, 16
	v_lshrrev_b32_e32 v113, 16, v106
	v_add_f32_e32 v106, 1.0, v107
	v_rcp_f32_e32 v106, v106
	v_max_f32_e32 v107, 0xc1f00000, v108
	v_mul_f32_e32 v107, 0xbfb8aa3b, v107
	v_exp_f32_e32 v107, v107
	v_fma_mixhi_f16 v113, v109, v106, 0
	v_cvt_f32_f16_sdwa v106, v146 dst_sel:DWORD dst_unused:UNUSED_PAD src0_sel:WORD_1
	v_cvt_f32_f16_e32 v108, v147
	v_add_f32_e32 v107, 1.0, v107
	v_rcp_f32_e32 v107, v107
	v_max_f32_e32 v106, 0xc1f00000, v106
	v_mul_f32_e32 v106, 0xbfb8aa3b, v106
	v_max_f32_e32 v108, 0xc1f00000, v108
	v_exp_f32_e32 v106, v106
	v_mul_f32_e32 v108, 0xbfb8aa3b, v108
	v_exp_f32_e32 v108, v108
	v_fma_mixlo_f16 v109, v102, v107, 0
	v_add_f32_e32 v102, 1.0, v106
	v_rcp_f32_e32 v106, v102
	v_add_f32_e32 v102, 1.0, v108
	v_rcp_f32_e32 v107, v102
	v_cvt_f32_f16_sdwa v108, v147 dst_sel:DWORD dst_unused:UNUSED_PAD src0_sel:WORD_1
	v_mov_b32_e32 v102, v103
	v_mov_b32_e32 v103, v104
	v_cvt_f32_f16_e32 v104, v148
	v_max_f32_e32 v108, 0xc1f00000, v108
	v_mul_f32_e32 v108, 0xbfb8aa3b, v108
	v_exp_f32_e32 v108, v108
	v_max_f32_e32 v104, 0xc1f00000, v104
	v_mul_f32_e32 v104, 0xbfb8aa3b, v104
	v_exp_f32_e32 v104, v104
	v_pk_mul_f32 v[102:103], v[102:103], v[106:107]
	v_add_f32_e32 v106, 1.0, v108
	v_rcp_f32_e32 v106, v106
	v_add_f32_e32 v104, 1.0, v104
	v_rcp_f32_e32 v107, v104
	v_pk_mov_b32 v[104:105], v[104:105], v[98:99] op_sel:[1,0]
	v_cvt_f32_f16_sdwa v98, v148 dst_sel:DWORD dst_unused:UNUSED_PAD src0_sel:WORD_1
	v_cvt_pk_f16_f32 v103, v102, v103
	v_pk_mul_f32 v[104:105], v[104:105], v[106:107]
	v_cvt_f32_f16_sdwa v107, v149 dst_sel:DWORD dst_unused:UNUSED_PAD src0_sel:WORD_1
	v_cvt_pk_f16_f32 v106, v104, v105
	v_cvt_f32_f16_e32 v104, v149
	v_max_f32_e32 v98, 0xc1f00000, v98
	v_mul_f32_e32 v98, 0xbfb8aa3b, v98
	v_exp_f32_e32 v98, v98
	v_max_f32_e32 v104, 0xc1f00000, v104
	v_mul_f32_e32 v104, 0xbfb8aa3b, v104
	v_exp_f32_e32 v105, v104
	v_add_f32_e32 v98, 1.0, v98
	v_rcp_f32_e32 v104, v98
	v_pack_b32_f16 v102, v109, v103
	v_add_f32_e32 v98, 1.0, v105
	v_rcp_f32_e32 v105, v98
	v_mov_b32_e32 v98, v99
	v_max_f32_e32 v99, 0xc1f00000, v107
	v_mul_f32_e32 v99, 0xbfb8aa3b, v99
	v_exp_f32_e32 v107, v99
	v_mov_b32_e32 v99, v100
	v_pk_mul_f32 v[98:99], v[98:99], v[104:105]
	v_cvt_f32_f16_e32 v100, v142
	v_cvt_pk_f16_f32 v98, v98, v99
	v_add_f32_e32 v99, 1.0, v107
	v_rcp_f32_e32 v99, v99
	v_alignbit_b32 v104, v98, v106, 16
	v_lshrrev_b32_e32 v105, 16, v98
	v_max_f32_e32 v98, 0xc1f00000, v100
	v_alignbit_b32 v103, v106, v103, 16
	v_fma_mixhi_f16 v105, v101, v99, 0
	v_mul_f32_e32 v98, 0xbfb8aa3b, v98
	v_cvt_f32_f16_sdwa v101, v142 dst_sel:DWORD dst_unused:UNUSED_PAD src0_sel:WORD_1
	v_exp_f32_e32 v100, v98
	global_store_dwordx4 v[114:115], v[102:105], off offset:256
	v_lshl_add_u64 v[98:99], v[192:193], 0, v[168:169]
	v_max_f32_e32 v101, 0xc1f00000, v101
	v_cvt_f32_f16_e32 v102, v143
	v_add_f32_e32 v100, 1.0, v100
	v_mul_f32_e32 v101, 0xbfb8aa3b, v101
	v_rcp_f32_e32 v100, v100
	v_max_f32_e32 v102, 0xc1f00000, v102
	v_exp_f32_e32 v101, v101
	v_mul_f32_e32 v102, 0xbfb8aa3b, v102
	v_exp_f32_e32 v102, v102
	v_fma_mixlo_f16 v103, v94, v100, 0
	v_add_f32_e32 v94, 1.0, v101
	v_rcp_f32_e32 v100, v94
	v_add_f32_e32 v94, 1.0, v102
	v_rcp_f32_e32 v101, v94
	v_cvt_f32_f16_sdwa v102, v143 dst_sel:DWORD dst_unused:UNUSED_PAD src0_sel:WORD_1
	v_mov_b32_e32 v94, v95
	v_mov_b32_e32 v95, v96
	v_cvt_f32_f16_e32 v96, v144
	v_pk_mul_f32 v[94:95], v[94:95], v[100:101]
	v_max_f32_e32 v100, 0xc1f00000, v102
	v_mul_f32_e32 v100, 0xbfb8aa3b, v100
	v_max_f32_e32 v96, 0xc1f00000, v96
	v_exp_f32_e32 v100, v100
	v_mul_f32_e32 v96, 0xbfb8aa3b, v96
	v_exp_f32_e32 v96, v96
	v_cvt_pk_f16_f32 v95, v94, v95
	v_add_f32_e32 v94, 1.0, v100
	v_rcp_f32_e32 v100, v94
	v_add_f32_e32 v94, 1.0, v96
	v_rcp_f32_e32 v101, v94
	v_pk_mov_b32 v[96:97], v[96:97], v[90:91] op_sel:[1,0]
	v_cvt_f32_f16_sdwa v90, v144 dst_sel:DWORD dst_unused:UNUSED_PAD src0_sel:WORD_1
	v_pack_b32_f16 v94, v103, v95
	v_pk_mul_f32 v[96:97], v[96:97], v[100:101]
	v_cvt_f32_f16_sdwa v101, v145 dst_sel:DWORD dst_unused:UNUSED_PAD src0_sel:WORD_1
	v_cvt_pk_f16_f32 v100, v96, v97
	v_cvt_f32_f16_e32 v96, v145
	v_max_f32_e32 v90, 0xc1f00000, v90
	v_mul_f32_e32 v90, 0xbfb8aa3b, v90
	v_exp_f32_e32 v90, v90
	v_max_f32_e32 v96, 0xc1f00000, v96
	v_mul_f32_e32 v96, 0xbfb8aa3b, v96
	v_exp_f32_e32 v97, v96
	v_add_f32_e32 v90, 1.0, v90
	v_rcp_f32_e32 v96, v90
	v_alignbit_b32 v95, v100, v95, 16
	v_add_f32_e32 v90, 1.0, v97
	v_rcp_f32_e32 v97, v90
	v_mov_b32_e32 v90, v91
	v_mov_b32_e32 v91, v92
	v_cvt_f32_f16_e32 v92, v138
	v_pk_mul_f32 v[90:91], v[90:91], v[96:97]
	global_store_dwordx4 v[114:115], v[110:113], off
	v_cvt_pk_f16_f32 v90, v90, v91
	v_max_f32_e32 v91, 0xc1f00000, v101
	v_mul_f32_e32 v91, 0xbfb8aa3b, v91
	v_exp_f32_e32 v91, v91
	v_alignbit_b32 v96, v90, v100, 16
	v_lshrrev_b32_e32 v97, 16, v90
	v_add_f32_e32 v90, 1.0, v91
	v_rcp_f32_e32 v90, v90
	v_max_f32_e32 v91, 0xc1f00000, v92
	v_mul_f32_e32 v91, 0xbfb8aa3b, v91
	v_exp_f32_e32 v91, v91
	v_fma_mixhi_f16 v97, v93, v90, 0
	v_cvt_f32_f16_sdwa v90, v138 dst_sel:DWORD dst_unused:UNUSED_PAD src0_sel:WORD_1
	v_cvt_f32_f16_e32 v92, v139
	v_add_f32_e32 v91, 1.0, v91
	v_rcp_f32_e32 v91, v91
	v_max_f32_e32 v90, 0xc1f00000, v90
	v_mul_f32_e32 v90, 0xbfb8aa3b, v90
	v_max_f32_e32 v92, 0xc1f00000, v92
	v_exp_f32_e32 v90, v90
	v_mul_f32_e32 v92, 0xbfb8aa3b, v92
	v_exp_f32_e32 v92, v92
	v_fma_mixlo_f16 v93, v86, v91, 0
	v_add_f32_e32 v86, 1.0, v90
	v_rcp_f32_e32 v90, v86
	v_add_f32_e32 v86, 1.0, v92
	v_rcp_f32_e32 v91, v86
	v_cvt_f32_f16_sdwa v92, v139 dst_sel:DWORD dst_unused:UNUSED_PAD src0_sel:WORD_1
	v_mov_b32_e32 v86, v87
	v_mov_b32_e32 v87, v88
	v_cvt_f32_f16_e32 v88, v140
	v_max_f32_e32 v92, 0xc1f00000, v92
	v_mul_f32_e32 v92, 0xbfb8aa3b, v92
	v_exp_f32_e32 v92, v92
	v_max_f32_e32 v88, 0xc1f00000, v88
	v_mul_f32_e32 v88, 0xbfb8aa3b, v88
	v_exp_f32_e32 v88, v88
	v_pk_mul_f32 v[86:87], v[86:87], v[90:91]
	v_add_f32_e32 v90, 1.0, v92
	v_rcp_f32_e32 v90, v90
	v_add_f32_e32 v88, 1.0, v88
	v_rcp_f32_e32 v91, v88
	v_pk_mov_b32 v[88:89], v[88:89], v[82:83] op_sel:[1,0]
	v_cvt_f32_f16_sdwa v82, v140 dst_sel:DWORD dst_unused:UNUSED_PAD src0_sel:WORD_1
	v_cvt_pk_f16_f32 v87, v86, v87
	v_pk_mul_f32 v[88:89], v[88:89], v[90:91]
	v_cvt_f32_f16_sdwa v91, v141 dst_sel:DWORD dst_unused:UNUSED_PAD src0_sel:WORD_1
	v_cvt_pk_f16_f32 v90, v88, v89
	v_cvt_f32_f16_e32 v88, v141
	v_max_f32_e32 v82, 0xc1f00000, v82
	v_mul_f32_e32 v82, 0xbfb8aa3b, v82
	v_exp_f32_e32 v82, v82
	v_max_f32_e32 v88, 0xc1f00000, v88
	v_mul_f32_e32 v88, 0xbfb8aa3b, v88
	v_exp_f32_e32 v89, v88
	v_add_f32_e32 v82, 1.0, v82
	v_rcp_f32_e32 v88, v82
	v_pack_b32_f16 v86, v93, v87
	v_add_f32_e32 v82, 1.0, v89
	v_rcp_f32_e32 v89, v82
	v_mov_b32_e32 v82, v83
	v_max_f32_e32 v83, 0xc1f00000, v91
	v_mul_f32_e32 v83, 0xbfb8aa3b, v83
	v_exp_f32_e32 v91, v83
	v_mov_b32_e32 v83, v84
	v_pk_mul_f32 v[82:83], v[82:83], v[88:89]
	v_cvt_f32_f16_e32 v84, v130
	v_cvt_pk_f16_f32 v82, v82, v83
	v_add_f32_e32 v83, 1.0, v91
	v_rcp_f32_e32 v83, v83
	v_alignbit_b32 v88, v82, v90, 16
	v_lshrrev_b32_e32 v89, 16, v82
	v_max_f32_e32 v82, 0xc1f00000, v84
	v_alignbit_b32 v87, v90, v87, 16
	v_fma_mixhi_f16 v89, v85, v83, 0
	v_mul_f32_e32 v82, 0xbfb8aa3b, v82
	v_cvt_f32_f16_sdwa v85, v130 dst_sel:DWORD dst_unused:UNUSED_PAD src0_sel:WORD_1
	v_exp_f32_e32 v84, v82
	global_store_dwordx4 v[98:99], v[86:89], off offset:256
	v_lshl_add_u64 v[82:83], v[192:193], 0, v[170:171]
	v_max_f32_e32 v85, 0xc1f00000, v85
	v_cvt_f32_f16_e32 v86, v131
	v_add_f32_e32 v84, 1.0, v84
	v_mul_f32_e32 v85, 0xbfb8aa3b, v85
	v_rcp_f32_e32 v84, v84
	v_max_f32_e32 v86, 0xc1f00000, v86
	v_exp_f32_e32 v85, v85
	v_mul_f32_e32 v86, 0xbfb8aa3b, v86
	v_exp_f32_e32 v86, v86
	v_fma_mixlo_f16 v87, v78, v84, 0
	v_add_f32_e32 v78, 1.0, v85
	v_rcp_f32_e32 v84, v78
	v_add_f32_e32 v78, 1.0, v86
	v_rcp_f32_e32 v85, v78
	v_cvt_f32_f16_sdwa v86, v131 dst_sel:DWORD dst_unused:UNUSED_PAD src0_sel:WORD_1
	v_mov_b32_e32 v78, v79
	v_mov_b32_e32 v79, v80
	v_cvt_f32_f16_e32 v80, v132
	v_pk_mul_f32 v[78:79], v[78:79], v[84:85]
	v_max_f32_e32 v84, 0xc1f00000, v86
	v_mul_f32_e32 v84, 0xbfb8aa3b, v84
	v_max_f32_e32 v80, 0xc1f00000, v80
	v_exp_f32_e32 v84, v84
	v_mul_f32_e32 v80, 0xbfb8aa3b, v80
	v_exp_f32_e32 v80, v80
	v_cvt_pk_f16_f32 v79, v78, v79
	v_add_f32_e32 v78, 1.0, v84
	v_rcp_f32_e32 v84, v78
	v_add_f32_e32 v78, 1.0, v80
	v_rcp_f32_e32 v85, v78
	v_pk_mov_b32 v[80:81], v[80:81], v[74:75] op_sel:[1,0]
	v_cvt_f32_f16_sdwa v74, v132 dst_sel:DWORD dst_unused:UNUSED_PAD src0_sel:WORD_1
	v_pack_b32_f16 v78, v87, v79
	v_pk_mul_f32 v[80:81], v[80:81], v[84:85]
	v_cvt_f32_f16_sdwa v85, v133 dst_sel:DWORD dst_unused:UNUSED_PAD src0_sel:WORD_1
	v_cvt_pk_f16_f32 v84, v80, v81
	v_cvt_f32_f16_e32 v80, v133
	v_max_f32_e32 v74, 0xc1f00000, v74
	v_mul_f32_e32 v74, 0xbfb8aa3b, v74
	v_exp_f32_e32 v74, v74
	v_max_f32_e32 v80, 0xc1f00000, v80
	v_mul_f32_e32 v80, 0xbfb8aa3b, v80
	v_exp_f32_e32 v81, v80
	v_add_f32_e32 v74, 1.0, v74
	v_rcp_f32_e32 v80, v74
	v_alignbit_b32 v79, v84, v79, 16
	v_add_f32_e32 v74, 1.0, v81
	v_rcp_f32_e32 v81, v74
	v_mov_b32_e32 v74, v75
	v_mov_b32_e32 v75, v76
	v_cvt_f32_f16_e32 v76, v122
	v_pk_mul_f32 v[74:75], v[74:75], v[80:81]
	global_store_dwordx4 v[98:99], v[94:97], off
	v_cvt_pk_f16_f32 v74, v74, v75
	v_max_f32_e32 v75, 0xc1f00000, v85
	v_mul_f32_e32 v75, 0xbfb8aa3b, v75
	v_exp_f32_e32 v75, v75
	v_alignbit_b32 v80, v74, v84, 16
	v_lshrrev_b32_e32 v81, 16, v74
	v_add_f32_e32 v74, 1.0, v75
	v_rcp_f32_e32 v74, v74
	v_max_f32_e32 v75, 0xc1f00000, v76
	v_mul_f32_e32 v75, 0xbfb8aa3b, v75
	v_exp_f32_e32 v75, v75
	v_fma_mixhi_f16 v81, v77, v74, 0
	v_cvt_f32_f16_sdwa v74, v122 dst_sel:DWORD dst_unused:UNUSED_PAD src0_sel:WORD_1
	v_cvt_f32_f16_e32 v76, v123
	v_add_f32_e32 v75, 1.0, v75
	v_rcp_f32_e32 v75, v75
	v_max_f32_e32 v74, 0xc1f00000, v74
	v_mul_f32_e32 v74, 0xbfb8aa3b, v74
	v_max_f32_e32 v76, 0xc1f00000, v76
	v_exp_f32_e32 v74, v74
	v_mul_f32_e32 v76, 0xbfb8aa3b, v76
	v_exp_f32_e32 v76, v76
	v_fma_mixlo_f16 v77, v70, v75, 0
	v_add_f32_e32 v70, 1.0, v74
	v_rcp_f32_e32 v74, v70
	v_add_f32_e32 v70, 1.0, v76
	v_rcp_f32_e32 v75, v70
	v_cvt_f32_f16_sdwa v76, v123 dst_sel:DWORD dst_unused:UNUSED_PAD src0_sel:WORD_1
	v_mov_b32_e32 v70, v71
	v_mov_b32_e32 v71, v72
	v_cvt_f32_f16_e32 v72, v124
	v_max_f32_e32 v76, 0xc1f00000, v76
	v_mul_f32_e32 v76, 0xbfb8aa3b, v76
	v_exp_f32_e32 v76, v76
	v_max_f32_e32 v72, 0xc1f00000, v72
	v_mul_f32_e32 v72, 0xbfb8aa3b, v72
	v_exp_f32_e32 v72, v72
	v_pk_mul_f32 v[70:71], v[70:71], v[74:75]
	v_add_f32_e32 v74, 1.0, v76
	v_rcp_f32_e32 v74, v74
	v_add_f32_e32 v72, 1.0, v72
	v_rcp_f32_e32 v75, v72
	v_pk_mov_b32 v[72:73], v[72:73], v[66:67] op_sel:[1,0]
	v_cvt_f32_f16_sdwa v66, v124 dst_sel:DWORD dst_unused:UNUSED_PAD src0_sel:WORD_1
	v_cvt_pk_f16_f32 v71, v70, v71
	v_pk_mul_f32 v[72:73], v[72:73], v[74:75]
	v_cvt_f32_f16_sdwa v75, v125 dst_sel:DWORD dst_unused:UNUSED_PAD src0_sel:WORD_1
	v_cvt_pk_f16_f32 v74, v72, v73
	v_cvt_f32_f16_e32 v72, v125
	v_max_f32_e32 v66, 0xc1f00000, v66
	v_mul_f32_e32 v66, 0xbfb8aa3b, v66
	v_exp_f32_e32 v66, v66
	v_max_f32_e32 v72, 0xc1f00000, v72
	v_mul_f32_e32 v72, 0xbfb8aa3b, v72
	v_exp_f32_e32 v73, v72
	v_add_f32_e32 v66, 1.0, v66
	v_rcp_f32_e32 v72, v66
	v_pack_b32_f16 v70, v77, v71
	v_add_f32_e32 v66, 1.0, v73
	v_rcp_f32_e32 v73, v66
	v_max_f32_e32 v66, 0xc1f00000, v75
	v_mul_f32_e32 v66, 0xbfb8aa3b, v66
	v_exp_f32_e32 v75, v66
	v_mov_b32_e32 v66, v67
	v_mov_b32_e32 v67, v68
	v_pk_mul_f32 v[66:67], v[66:67], v[72:73]
	v_add_f32_e32 v68, 1.0, v75
	v_rcp_f32_e32 v68, v68
	v_cvt_pk_f16_f32 v66, v66, v67
	v_lshrrev_b32_e32 v73, 16, v66
	v_alignbit_b32 v71, v74, v71, 16
	v_alignbit_b32 v72, v66, v74, 16
	v_fma_mixhi_f16 v73, v69, v68, 0
	global_store_dwordx4 v[82:83], v[78:81], off
	global_store_dwordx4 v[82:83], v[70:73], off offset:256
	v_lshl_add_u64 v[66:67], v[194:195], 0, v[172:173]
	v_lshl_add_u64 v[68:69], v[194:195], 0, v[174:175]
	v_lshl_add_u64 v[70:71], v[194:195], 0, v[176:177]
	v_lshl_add_u64 v[98:99], v[194:195], 0, v[178:179]
	global_load_dwordx4 v[90:93], v[66:67], off
	global_load_dwordx4 v[94:97], v[66:67], off offset:256
	global_load_dwordx4 v[86:89], v[68:69], off
	global_load_dwordx4 v[82:85], v[68:69], off offset:256
	global_load_dwordx4 v[78:81], v[70:71], off
	global_load_dwordx4 v[74:77], v[70:71], off offset:256
	s_nop 0
	global_load_dwordx4 v[70:73], v[98:99], off
	global_load_dwordx4 v[66:69], v[98:99], off offset:256
	s_waitcnt vmcnt(0)
	v_cvt_f32_f16_e32 v100, v90
	v_cvt_f32_f16_sdwa v90, v90 dst_sel:DWORD dst_unused:UNUSED_PAD src0_sel:WORD_1
	v_cvt_f32_f16_e32 v101, v91
	v_lshl_add_u64 v[98:99], v[192:193], 0, v[180:181]
	v_max_f32_e32 v100, 0xc1f00000, v100
	v_mul_f32_e32 v100, 0xbfb8aa3b, v100
	v_exp_f32_e32 v100, v100
	v_max_f32_e32 v90, 0xc1f00000, v90
	v_max_f32_e32 v101, 0xc1f00000, v101
	v_mul_f32_e32 v90, 0xbfb8aa3b, v90
	v_add_f32_e32 v100, 1.0, v100
	v_rcp_f32_e32 v100, v100
	v_exp_f32_e32 v90, v90
	v_mul_f32_e32 v101, 0xbfb8aa3b, v101
	v_exp_f32_e32 v101, v101
	v_fma_mixlo_f16 v102, v62, v100, 0
	v_add_f32_e32 v62, 1.0, v90
	v_rcp_f32_e32 v100, v62
	v_add_f32_e32 v62, 1.0, v101
	v_cvt_f32_f16_sdwa v90, v91 dst_sel:DWORD dst_unused:UNUSED_PAD src0_sel:WORD_1
	v_rcp_f32_e32 v101, v62
	v_mov_b32_e32 v62, v63
	v_mov_b32_e32 v63, v64
	v_cvt_f32_f16_e32 v64, v92
	v_max_f32_e32 v90, 0xc1f00000, v90
	v_mul_f32_e32 v90, 0xbfb8aa3b, v90
	v_exp_f32_e32 v90, v90
	v_max_f32_e32 v64, 0xc1f00000, v64
	v_mul_f32_e32 v64, 0xbfb8aa3b, v64
	v_exp_f32_e32 v64, v64
	v_pk_mul_f32 v[62:63], v[62:63], v[100:101]
	s_nop 0
	v_cvt_pk_f16_f32 v63, v62, v63
	v_add_f32_e32 v62, 1.0, v90
	v_rcp_f32_e32 v90, v62
	v_add_f32_e32 v62, 1.0, v64
	v_rcp_f32_e32 v91, v62
	v_pk_mov_b32 v[64:65], v[64:65], v[58:59] op_sel:[1,0]
	v_cvt_f32_f16_sdwa v58, v92 dst_sel:DWORD dst_unused:UNUSED_PAD src0_sel:WORD_1
	v_pack_b32_f16 v62, v102, v63
	v_pk_mul_f32 v[64:65], v[64:65], v[90:91]
	v_cvt_f32_f16_sdwa v91, v93 dst_sel:DWORD dst_unused:UNUSED_PAD src0_sel:WORD_1
	v_cvt_pk_f16_f32 v90, v64, v65
	v_cvt_f32_f16_e32 v64, v93
	v_max_f32_e32 v58, 0xc1f00000, v58
	v_mul_f32_e32 v58, 0xbfb8aa3b, v58
	v_exp_f32_e32 v58, v58
	v_max_f32_e32 v64, 0xc1f00000, v64
	v_mul_f32_e32 v64, 0xbfb8aa3b, v64
	v_exp_f32_e32 v65, v64
	v_add_f32_e32 v58, 1.0, v58
	v_rcp_f32_e32 v64, v58
	v_alignbit_b32 v63, v90, v63, 16
	v_add_f32_e32 v58, 1.0, v65
	v_rcp_f32_e32 v65, v58
	v_mov_b32_e32 v58, v59
	v_mov_b32_e32 v59, v60
	v_cvt_f32_f16_e32 v60, v94
	v_pk_mul_f32 v[58:59], v[58:59], v[64:65]
	s_nop 0
	v_cvt_pk_f16_f32 v58, v58, v59
	v_max_f32_e32 v59, 0xc1f00000, v91
	v_mul_f32_e32 v59, 0xbfb8aa3b, v59
	v_exp_f32_e32 v59, v59
	v_alignbit_b32 v64, v58, v90, 16
	v_lshrrev_b32_e32 v65, 16, v58
	v_add_f32_e32 v58, 1.0, v59
	v_rcp_f32_e32 v58, v58
	v_max_f32_e32 v59, 0xc1f00000, v60
	v_mul_f32_e32 v59, 0xbfb8aa3b, v59
	v_exp_f32_e32 v59, v59
	v_fma_mixhi_f16 v65, v61, v58, 0
	v_cvt_f32_f16_sdwa v58, v94 dst_sel:DWORD dst_unused:UNUSED_PAD src0_sel:WORD_1
	v_cvt_f32_f16_e32 v60, v95
	v_add_f32_e32 v59, 1.0, v59
	v_rcp_f32_e32 v59, v59
	v_max_f32_e32 v58, 0xc1f00000, v58
	v_mul_f32_e32 v58, 0xbfb8aa3b, v58
	v_max_f32_e32 v60, 0xc1f00000, v60
	v_exp_f32_e32 v58, v58
	v_mul_f32_e32 v60, 0xbfb8aa3b, v60
	v_exp_f32_e32 v60, v60
	v_fma_mixlo_f16 v61, v54, v59, 0
	v_add_f32_e32 v54, 1.0, v58
	v_rcp_f32_e32 v58, v54
	v_add_f32_e32 v54, 1.0, v60
	v_rcp_f32_e32 v59, v54
	v_cvt_f32_f16_sdwa v60, v95 dst_sel:DWORD dst_unused:UNUSED_PAD src0_sel:WORD_1
	v_mov_b32_e32 v54, v55
	v_mov_b32_e32 v55, v56
	v_cvt_f32_f16_e32 v56, v96
	v_max_f32_e32 v60, 0xc1f00000, v60
	v_mul_f32_e32 v60, 0xbfb8aa3b, v60
	v_exp_f32_e32 v60, v60
	v_max_f32_e32 v56, 0xc1f00000, v56
	v_mul_f32_e32 v56, 0xbfb8aa3b, v56
	v_exp_f32_e32 v56, v56
	v_pk_mul_f32 v[54:55], v[54:55], v[58:59]
	v_add_f32_e32 v58, 1.0, v60
	v_rcp_f32_e32 v58, v58
	v_add_f32_e32 v56, 1.0, v56
	v_rcp_f32_e32 v59, v56
	v_pk_mov_b32 v[56:57], v[56:57], v[50:51] op_sel:[1,0]
	v_cvt_f32_f16_sdwa v50, v96 dst_sel:DWORD dst_unused:UNUSED_PAD src0_sel:WORD_1
	v_cvt_pk_f16_f32 v55, v54, v55
	v_pk_mul_f32 v[56:57], v[56:57], v[58:59]
	v_cvt_f32_f16_sdwa v59, v97 dst_sel:DWORD dst_unused:UNUSED_PAD src0_sel:WORD_1
	v_cvt_pk_f16_f32 v58, v56, v57
	v_cvt_f32_f16_e32 v56, v97
	v_max_f32_e32 v50, 0xc1f00000, v50
	v_mul_f32_e32 v50, 0xbfb8aa3b, v50
	v_exp_f32_e32 v50, v50
	v_max_f32_e32 v56, 0xc1f00000, v56
	v_mul_f32_e32 v56, 0xbfb8aa3b, v56
	v_exp_f32_e32 v57, v56
	v_add_f32_e32 v50, 1.0, v50
	v_rcp_f32_e32 v56, v50
	v_pack_b32_f16 v54, v61, v55
	v_add_f32_e32 v50, 1.0, v57
	v_rcp_f32_e32 v57, v50
	v_mov_b32_e32 v50, v51
	v_max_f32_e32 v51, 0xc1f00000, v59
	v_mul_f32_e32 v51, 0xbfb8aa3b, v51
	v_exp_f32_e32 v59, v51
	v_mov_b32_e32 v51, v52
	v_pk_mul_f32 v[50:51], v[50:51], v[56:57]
	v_cvt_f32_f16_e32 v52, v86
	v_cvt_pk_f16_f32 v50, v50, v51
	v_add_f32_e32 v51, 1.0, v59
	v_rcp_f32_e32 v51, v51
	v_alignbit_b32 v56, v50, v58, 16
	v_lshrrev_b32_e32 v57, 16, v50
	v_max_f32_e32 v50, 0xc1f00000, v52
	v_alignbit_b32 v55, v58, v55, 16
	v_fma_mixhi_f16 v57, v53, v51, 0
	v_mul_f32_e32 v50, 0xbfb8aa3b, v50
	v_cvt_f32_f16_sdwa v53, v86 dst_sel:DWORD dst_unused:UNUSED_PAD src0_sel:WORD_1
	v_exp_f32_e32 v52, v50
	global_store_dwordx4 v[98:99], v[54:57], off offset:256
	v_lshl_add_u64 v[50:51], v[192:193], 0, v[182:183]
	v_max_f32_e32 v53, 0xc1f00000, v53
	v_cvt_f32_f16_e32 v54, v87
	v_add_f32_e32 v52, 1.0, v52
	v_mul_f32_e32 v53, 0xbfb8aa3b, v53
	v_rcp_f32_e32 v52, v52
	v_max_f32_e32 v54, 0xc1f00000, v54
	v_exp_f32_e32 v53, v53
	v_mul_f32_e32 v54, 0xbfb8aa3b, v54
	v_exp_f32_e32 v54, v54
	v_fma_mixlo_f16 v55, v46, v52, 0
	v_add_f32_e32 v46, 1.0, v53
	v_rcp_f32_e32 v52, v46
	v_add_f32_e32 v46, 1.0, v54
	v_rcp_f32_e32 v53, v46
	v_cvt_f32_f16_sdwa v54, v87 dst_sel:DWORD dst_unused:UNUSED_PAD src0_sel:WORD_1
	v_mov_b32_e32 v46, v47
	v_mov_b32_e32 v47, v48
	v_cvt_f32_f16_e32 v48, v88
	v_pk_mul_f32 v[46:47], v[46:47], v[52:53]
	v_max_f32_e32 v52, 0xc1f00000, v54
	v_mul_f32_e32 v52, 0xbfb8aa3b, v52
	v_max_f32_e32 v48, 0xc1f00000, v48
	v_exp_f32_e32 v52, v52
	v_mul_f32_e32 v48, 0xbfb8aa3b, v48
	v_exp_f32_e32 v48, v48
	v_cvt_pk_f16_f32 v47, v46, v47
	v_add_f32_e32 v46, 1.0, v52
	v_rcp_f32_e32 v52, v46
	v_add_f32_e32 v46, 1.0, v48
	v_rcp_f32_e32 v53, v46
	v_pk_mov_b32 v[48:49], v[48:49], v[42:43] op_sel:[1,0]
	v_cvt_f32_f16_sdwa v42, v88 dst_sel:DWORD dst_unused:UNUSED_PAD src0_sel:WORD_1
	v_pack_b32_f16 v46, v55, v47
	v_pk_mul_f32 v[48:49], v[48:49], v[52:53]
	v_cvt_f32_f16_sdwa v53, v89 dst_sel:DWORD dst_unused:UNUSED_PAD src0_sel:WORD_1
	v_cvt_pk_f16_f32 v52, v48, v49
	v_cvt_f32_f16_e32 v48, v89
	v_max_f32_e32 v42, 0xc1f00000, v42
	v_mul_f32_e32 v42, 0xbfb8aa3b, v42
	v_exp_f32_e32 v42, v42
	v_max_f32_e32 v48, 0xc1f00000, v48
	v_mul_f32_e32 v48, 0xbfb8aa3b, v48
	v_exp_f32_e32 v49, v48
	v_add_f32_e32 v42, 1.0, v42
	v_rcp_f32_e32 v48, v42
	v_alignbit_b32 v47, v52, v47, 16
	v_add_f32_e32 v42, 1.0, v49
	v_rcp_f32_e32 v49, v42
	v_mov_b32_e32 v42, v43
	v_mov_b32_e32 v43, v44
	v_cvt_f32_f16_e32 v44, v82
	v_pk_mul_f32 v[42:43], v[42:43], v[48:49]
	global_store_dwordx4 v[98:99], v[62:65], off
	v_cvt_pk_f16_f32 v42, v42, v43
	v_max_f32_e32 v43, 0xc1f00000, v53
	v_mul_f32_e32 v43, 0xbfb8aa3b, v43
	v_exp_f32_e32 v43, v43
	v_alignbit_b32 v48, v42, v52, 16
	v_lshrrev_b32_e32 v49, 16, v42
	v_add_f32_e32 v42, 1.0, v43
	v_rcp_f32_e32 v42, v42
	v_max_f32_e32 v43, 0xc1f00000, v44
	v_mul_f32_e32 v43, 0xbfb8aa3b, v43
	v_exp_f32_e32 v43, v43
	v_fma_mixhi_f16 v49, v45, v42, 0
	v_cvt_f32_f16_sdwa v42, v82 dst_sel:DWORD dst_unused:UNUSED_PAD src0_sel:WORD_1
	v_cvt_f32_f16_e32 v44, v83
	v_add_f32_e32 v43, 1.0, v43
	v_rcp_f32_e32 v43, v43
	v_max_f32_e32 v42, 0xc1f00000, v42
	v_mul_f32_e32 v42, 0xbfb8aa3b, v42
	v_max_f32_e32 v44, 0xc1f00000, v44
	v_exp_f32_e32 v42, v42
	v_mul_f32_e32 v44, 0xbfb8aa3b, v44
	v_exp_f32_e32 v44, v44
	v_fma_mixlo_f16 v45, v38, v43, 0
	v_add_f32_e32 v38, 1.0, v42
	v_rcp_f32_e32 v42, v38
	v_add_f32_e32 v38, 1.0, v44
	v_rcp_f32_e32 v43, v38
	v_cvt_f32_f16_sdwa v44, v83 dst_sel:DWORD dst_unused:UNUSED_PAD src0_sel:WORD_1
	v_mov_b32_e32 v38, v39
	v_mov_b32_e32 v39, v40
	v_cvt_f32_f16_e32 v40, v84
	v_max_f32_e32 v44, 0xc1f00000, v44
	v_mul_f32_e32 v44, 0xbfb8aa3b, v44
	v_exp_f32_e32 v44, v44
	v_max_f32_e32 v40, 0xc1f00000, v40
	v_mul_f32_e32 v40, 0xbfb8aa3b, v40
	v_exp_f32_e32 v40, v40
	v_pk_mul_f32 v[38:39], v[38:39], v[42:43]
	v_add_f32_e32 v42, 1.0, v44
	v_rcp_f32_e32 v42, v42
	v_add_f32_e32 v40, 1.0, v40
	v_rcp_f32_e32 v43, v40
	v_pk_mov_b32 v[40:41], v[40:41], v[34:35] op_sel:[1,0]
	v_cvt_f32_f16_sdwa v34, v84 dst_sel:DWORD dst_unused:UNUSED_PAD src0_sel:WORD_1
	v_cvt_pk_f16_f32 v39, v38, v39
	v_pk_mul_f32 v[40:41], v[40:41], v[42:43]
	v_cvt_f32_f16_sdwa v43, v85 dst_sel:DWORD dst_unused:UNUSED_PAD src0_sel:WORD_1
	v_cvt_pk_f16_f32 v42, v40, v41
	v_cvt_f32_f16_e32 v40, v85
	v_max_f32_e32 v34, 0xc1f00000, v34
	v_mul_f32_e32 v34, 0xbfb8aa3b, v34
	v_exp_f32_e32 v34, v34
	v_max_f32_e32 v40, 0xc1f00000, v40
	v_mul_f32_e32 v40, 0xbfb8aa3b, v40
	v_exp_f32_e32 v41, v40
	v_add_f32_e32 v34, 1.0, v34
	v_rcp_f32_e32 v40, v34
	v_pack_b32_f16 v38, v45, v39
	v_add_f32_e32 v34, 1.0, v41
	v_rcp_f32_e32 v41, v34
	v_mov_b32_e32 v34, v35
	v_max_f32_e32 v35, 0xc1f00000, v43
	v_mul_f32_e32 v35, 0xbfb8aa3b, v35
	v_exp_f32_e32 v43, v35
	v_mov_b32_e32 v35, v36
	v_pk_mul_f32 v[34:35], v[34:35], v[40:41]
	v_cvt_f32_f16_e32 v36, v78
	v_cvt_pk_f16_f32 v34, v34, v35
	v_add_f32_e32 v35, 1.0, v43
	v_rcp_f32_e32 v35, v35
	v_alignbit_b32 v40, v34, v42, 16
	v_lshrrev_b32_e32 v41, 16, v34
	v_max_f32_e32 v34, 0xc1f00000, v36
	v_alignbit_b32 v39, v42, v39, 16
	v_fma_mixhi_f16 v41, v37, v35, 0
	v_mul_f32_e32 v34, 0xbfb8aa3b, v34
	v_cvt_f32_f16_sdwa v37, v78 dst_sel:DWORD dst_unused:UNUSED_PAD src0_sel:WORD_1
	v_exp_f32_e32 v36, v34
	global_store_dwordx4 v[50:51], v[38:41], off offset:256
	v_lshl_add_u64 v[34:35], v[192:193], 0, v[184:185]
	v_max_f32_e32 v37, 0xc1f00000, v37
	v_cvt_f32_f16_e32 v38, v79
	v_add_f32_e32 v36, 1.0, v36
	v_mul_f32_e32 v37, 0xbfb8aa3b, v37
	v_rcp_f32_e32 v36, v36
	v_max_f32_e32 v38, 0xc1f00000, v38
	v_exp_f32_e32 v37, v37
	v_mul_f32_e32 v38, 0xbfb8aa3b, v38
	v_exp_f32_e32 v38, v38
	v_fma_mixlo_f16 v39, v28, v36, 0
	v_add_f32_e32 v28, 1.0, v37
	v_rcp_f32_e32 v36, v28
	v_add_f32_e32 v28, 1.0, v38
	v_rcp_f32_e32 v37, v28
	v_cvt_f32_f16_sdwa v38, v79 dst_sel:DWORD dst_unused:UNUSED_PAD src0_sel:WORD_1
	v_mov_b32_e32 v28, v29
	v_mov_b32_e32 v29, v30
	v_cvt_f32_f16_e32 v30, v80
	v_pk_mul_f32 v[28:29], v[28:29], v[36:37]
	v_max_f32_e32 v36, 0xc1f00000, v38
	v_mul_f32_e32 v36, 0xbfb8aa3b, v36
	v_max_f32_e32 v30, 0xc1f00000, v30
	v_exp_f32_e32 v36, v36
	v_mul_f32_e32 v30, 0xbfb8aa3b, v30
	v_exp_f32_e32 v30, v30
	v_cvt_pk_f16_f32 v29, v28, v29
	v_add_f32_e32 v28, 1.0, v36
	v_rcp_f32_e32 v36, v28
	v_add_f32_e32 v28, 1.0, v30
	v_rcp_f32_e32 v37, v28
	v_pk_mov_b32 v[30:31], v[30:31], v[24:25] op_sel:[1,0]
	v_cvt_f32_f16_sdwa v24, v80 dst_sel:DWORD dst_unused:UNUSED_PAD src0_sel:WORD_1
	v_pack_b32_f16 v28, v39, v29
	v_pk_mul_f32 v[30:31], v[30:31], v[36:37]
	v_cvt_f32_f16_sdwa v37, v81 dst_sel:DWORD dst_unused:UNUSED_PAD src0_sel:WORD_1
	v_cvt_pk_f16_f32 v36, v30, v31
	v_cvt_f32_f16_e32 v30, v81
	v_max_f32_e32 v24, 0xc1f00000, v24
	v_mul_f32_e32 v24, 0xbfb8aa3b, v24
	v_exp_f32_e32 v24, v24
	v_max_f32_e32 v30, 0xc1f00000, v30
	v_mul_f32_e32 v30, 0xbfb8aa3b, v30
	v_exp_f32_e32 v31, v30
	v_add_f32_e32 v24, 1.0, v24
	v_rcp_f32_e32 v30, v24
	v_alignbit_b32 v29, v36, v29, 16
	v_add_f32_e32 v24, 1.0, v31
	v_rcp_f32_e32 v31, v24
	v_mov_b32_e32 v24, v25
	v_mov_b32_e32 v25, v26
	v_cvt_f32_f16_e32 v26, v74
	v_pk_mul_f32 v[24:25], v[24:25], v[30:31]
	global_store_dwordx4 v[50:51], v[46:49], off
	v_cvt_pk_f16_f32 v24, v24, v25
	v_max_f32_e32 v25, 0xc1f00000, v37
	v_mul_f32_e32 v25, 0xbfb8aa3b, v25
	v_exp_f32_e32 v25, v25
	v_alignbit_b32 v30, v24, v36, 16
	v_lshrrev_b32_e32 v31, 16, v24
	v_add_f32_e32 v24, 1.0, v25
	v_rcp_f32_e32 v24, v24
	v_max_f32_e32 v25, 0xc1f00000, v26
	v_mul_f32_e32 v25, 0xbfb8aa3b, v25
	v_exp_f32_e32 v25, v25
	v_fma_mixhi_f16 v31, v27, v24, 0
	v_cvt_f32_f16_sdwa v24, v74 dst_sel:DWORD dst_unused:UNUSED_PAD src0_sel:WORD_1
	v_cvt_f32_f16_e32 v26, v75
	v_add_f32_e32 v25, 1.0, v25
	v_rcp_f32_e32 v25, v25
	v_max_f32_e32 v24, 0xc1f00000, v24
	v_mul_f32_e32 v24, 0xbfb8aa3b, v24
	v_max_f32_e32 v26, 0xc1f00000, v26
	v_exp_f32_e32 v24, v24
	v_mul_f32_e32 v26, 0xbfb8aa3b, v26
	v_exp_f32_e32 v26, v26
	v_fma_mixlo_f16 v27, v20, v25, 0
	v_add_f32_e32 v20, 1.0, v24
	v_rcp_f32_e32 v24, v20
	v_add_f32_e32 v20, 1.0, v26
	v_rcp_f32_e32 v25, v20
	v_cvt_f32_f16_sdwa v26, v75 dst_sel:DWORD dst_unused:UNUSED_PAD src0_sel:WORD_1
	v_mov_b32_e32 v20, v21
	v_mov_b32_e32 v21, v22
	v_cvt_f32_f16_e32 v22, v76
	v_max_f32_e32 v26, 0xc1f00000, v26
	v_mul_f32_e32 v26, 0xbfb8aa3b, v26
	v_exp_f32_e32 v26, v26
	v_max_f32_e32 v22, 0xc1f00000, v22
	v_mul_f32_e32 v22, 0xbfb8aa3b, v22
	v_exp_f32_e32 v22, v22
	v_pk_mul_f32 v[20:21], v[20:21], v[24:25]
	v_add_f32_e32 v24, 1.0, v26
	v_rcp_f32_e32 v24, v24
	v_add_f32_e32 v22, 1.0, v22
	v_rcp_f32_e32 v25, v22
	v_pk_mov_b32 v[22:23], v[22:23], v[16:17] op_sel:[1,0]
	v_cvt_f32_f16_sdwa v16, v76 dst_sel:DWORD dst_unused:UNUSED_PAD src0_sel:WORD_1
	v_cvt_pk_f16_f32 v21, v20, v21
	v_pk_mul_f32 v[22:23], v[22:23], v[24:25]
	v_cvt_f32_f16_sdwa v25, v77 dst_sel:DWORD dst_unused:UNUSED_PAD src0_sel:WORD_1
	v_cvt_pk_f16_f32 v24, v22, v23
	v_cvt_f32_f16_e32 v22, v77
	v_max_f32_e32 v16, 0xc1f00000, v16
	v_mul_f32_e32 v16, 0xbfb8aa3b, v16
	v_exp_f32_e32 v16, v16
	v_max_f32_e32 v22, 0xc1f00000, v22
	v_mul_f32_e32 v22, 0xbfb8aa3b, v22
	v_exp_f32_e32 v23, v22
	v_add_f32_e32 v16, 1.0, v16
	v_rcp_f32_e32 v22, v16
	v_pack_b32_f16 v20, v27, v21
	v_add_f32_e32 v16, 1.0, v23
	v_rcp_f32_e32 v23, v16
	v_mov_b32_e32 v16, v17
	v_max_f32_e32 v17, 0xc1f00000, v25
	v_mul_f32_e32 v17, 0xbfb8aa3b, v17
	v_exp_f32_e32 v25, v17
	v_mov_b32_e32 v17, v18
	v_pk_mul_f32 v[16:17], v[16:17], v[22:23]
	v_cvt_f32_f16_e32 v18, v70
	v_cvt_pk_f16_f32 v16, v16, v17
	v_add_f32_e32 v17, 1.0, v25
	v_rcp_f32_e32 v17, v17
	v_alignbit_b32 v22, v16, v24, 16
	v_lshrrev_b32_e32 v23, 16, v16
	v_max_f32_e32 v16, 0xc1f00000, v18
	v_alignbit_b32 v21, v24, v21, 16
	v_fma_mixhi_f16 v23, v19, v17, 0
	v_mul_f32_e32 v16, 0xbfb8aa3b, v16
	v_cvt_f32_f16_sdwa v19, v70 dst_sel:DWORD dst_unused:UNUSED_PAD src0_sel:WORD_1
	v_exp_f32_e32 v18, v16
	global_store_dwordx4 v[34:35], v[20:23], off offset:256
	v_lshl_add_u64 v[16:17], v[192:193], 0, v[186:187]
	v_max_f32_e32 v19, 0xc1f00000, v19
	v_cvt_f32_f16_e32 v20, v71
	v_add_f32_e32 v18, 1.0, v18
	v_mul_f32_e32 v19, 0xbfb8aa3b, v19
	v_rcp_f32_e32 v18, v18
	v_max_f32_e32 v20, 0xc1f00000, v20
	v_exp_f32_e32 v19, v19
	v_mul_f32_e32 v20, 0xbfb8aa3b, v20
	v_exp_f32_e32 v20, v20
	v_fma_mixlo_f16 v21, v12, v18, 0
	v_add_f32_e32 v12, 1.0, v19
	v_rcp_f32_e32 v18, v12
	v_add_f32_e32 v12, 1.0, v20
	v_rcp_f32_e32 v19, v12
	v_cvt_f32_f16_sdwa v20, v71 dst_sel:DWORD dst_unused:UNUSED_PAD src0_sel:WORD_1
	v_mov_b32_e32 v12, v13
	v_mov_b32_e32 v13, v14
	v_cvt_f32_f16_e32 v14, v72
	v_pk_mul_f32 v[12:13], v[12:13], v[18:19]
	v_max_f32_e32 v18, 0xc1f00000, v20
	v_mul_f32_e32 v18, 0xbfb8aa3b, v18
	v_max_f32_e32 v14, 0xc1f00000, v14
	v_exp_f32_e32 v18, v18
	v_mul_f32_e32 v14, 0xbfb8aa3b, v14
	v_exp_f32_e32 v14, v14
	v_cvt_pk_f16_f32 v13, v12, v13
	v_add_f32_e32 v12, 1.0, v18
	v_rcp_f32_e32 v18, v12
	v_add_f32_e32 v12, 1.0, v14
	v_rcp_f32_e32 v19, v12
	v_pk_mov_b32 v[14:15], v[14:15], v[8:9] op_sel:[1,0]
	v_cvt_f32_f16_sdwa v8, v72 dst_sel:DWORD dst_unused:UNUSED_PAD src0_sel:WORD_1
	v_pack_b32_f16 v12, v21, v13
	v_pk_mul_f32 v[14:15], v[14:15], v[18:19]
	v_cvt_f32_f16_sdwa v19, v73 dst_sel:DWORD dst_unused:UNUSED_PAD src0_sel:WORD_1
	v_cvt_pk_f16_f32 v18, v14, v15
	v_cvt_f32_f16_e32 v14, v73
	v_max_f32_e32 v8, 0xc1f00000, v8
	v_mul_f32_e32 v8, 0xbfb8aa3b, v8
	v_exp_f32_e32 v8, v8
	v_max_f32_e32 v14, 0xc1f00000, v14
	v_mul_f32_e32 v14, 0xbfb8aa3b, v14
	v_exp_f32_e32 v15, v14
	v_add_f32_e32 v8, 1.0, v8
	v_rcp_f32_e32 v14, v8
	v_alignbit_b32 v13, v18, v13, 16
	v_add_f32_e32 v8, 1.0, v15
	v_rcp_f32_e32 v15, v8
	v_mov_b32_e32 v8, v9
	v_mov_b32_e32 v9, v10
	v_cvt_f32_f16_e32 v10, v66
	v_pk_mul_f32 v[8:9], v[8:9], v[14:15]
	global_store_dwordx4 v[34:35], v[28:31], off
	v_cvt_pk_f16_f32 v8, v8, v9
	v_max_f32_e32 v9, 0xc1f00000, v19
	v_mul_f32_e32 v9, 0xbfb8aa3b, v9
	v_exp_f32_e32 v9, v9
	v_alignbit_b32 v14, v8, v18, 16
	v_lshrrev_b32_e32 v15, 16, v8
	v_add_f32_e32 v8, 1.0, v9
	v_rcp_f32_e32 v8, v8
	v_max_f32_e32 v9, 0xc1f00000, v10
	v_mul_f32_e32 v9, 0xbfb8aa3b, v9
	v_exp_f32_e32 v9, v9
	v_fma_mixhi_f16 v15, v11, v8, 0
	v_cvt_f32_f16_sdwa v8, v66 dst_sel:DWORD dst_unused:UNUSED_PAD src0_sel:WORD_1
	v_cvt_f32_f16_e32 v10, v67
	v_add_f32_e32 v9, 1.0, v9
	v_rcp_f32_e32 v9, v9
	v_max_f32_e32 v8, 0xc1f00000, v8
	v_mul_f32_e32 v8, 0xbfb8aa3b, v8
	v_max_f32_e32 v10, 0xc1f00000, v10
	v_exp_f32_e32 v8, v8
	v_mul_f32_e32 v10, 0xbfb8aa3b, v10
	v_exp_f32_e32 v10, v10
	v_fma_mixlo_f16 v11, v4, v9, 0
	v_add_f32_e32 v4, 1.0, v8
	v_rcp_f32_e32 v8, v4
	v_add_f32_e32 v4, 1.0, v10
	v_rcp_f32_e32 v9, v4
	v_cvt_f32_f16_sdwa v10, v67 dst_sel:DWORD dst_unused:UNUSED_PAD src0_sel:WORD_1
	v_mov_b32_e32 v4, v5
	v_mov_b32_e32 v5, v6
	v_cvt_f32_f16_e32 v6, v68
	v_max_f32_e32 v10, 0xc1f00000, v10
	v_mul_f32_e32 v10, 0xbfb8aa3b, v10
	v_exp_f32_e32 v10, v10
	v_max_f32_e32 v6, 0xc1f00000, v6
	v_mul_f32_e32 v6, 0xbfb8aa3b, v6
	v_exp_f32_e32 v6, v6
	v_pk_mul_f32 v[4:5], v[4:5], v[8:9]
	v_add_f32_e32 v8, 1.0, v10
	v_rcp_f32_e32 v8, v8
	v_add_f32_e32 v6, 1.0, v6
	v_rcp_f32_e32 v9, v6
	v_pk_mov_b32 v[6:7], v[6:7], v[0:1] op_sel:[1,0]
	v_cvt_f32_f16_sdwa v0, v68 dst_sel:DWORD dst_unused:UNUSED_PAD src0_sel:WORD_1
	v_cvt_pk_f16_f32 v5, v4, v5
	v_pk_mul_f32 v[6:7], v[6:7], v[8:9]
	v_cvt_f32_f16_sdwa v9, v69 dst_sel:DWORD dst_unused:UNUSED_PAD src0_sel:WORD_1
	v_cvt_pk_f16_f32 v8, v6, v7
	v_cvt_f32_f16_e32 v6, v69
	v_max_f32_e32 v0, 0xc1f00000, v0
	v_mul_f32_e32 v0, 0xbfb8aa3b, v0
	v_exp_f32_e32 v0, v0
	v_max_f32_e32 v6, 0xc1f00000, v6
	v_mul_f32_e32 v6, 0xbfb8aa3b, v6
	v_exp_f32_e32 v7, v6
	v_add_f32_e32 v0, 1.0, v0
	v_rcp_f32_e32 v6, v0
	v_pack_b32_f16 v4, v11, v5
	v_add_f32_e32 v0, 1.0, v7
	v_rcp_f32_e32 v7, v0
	v_max_f32_e32 v0, 0xc1f00000, v9
	v_mul_f32_e32 v0, 0xbfb8aa3b, v0
	v_exp_f32_e32 v9, v0
	v_mov_b32_e32 v0, v1
	v_mov_b32_e32 v1, v2
	v_pk_mul_f32 v[0:1], v[0:1], v[6:7]
	v_add_f32_e32 v2, 1.0, v9
	v_rcp_f32_e32 v2, v2
	v_cvt_pk_f16_f32 v0, v0, v1
	v_lshrrev_b32_e32 v7, 16, v0
	v_alignbit_b32 v5, v8, v5, 16
	v_alignbit_b32 v6, v0, v8, 16
	v_fma_mixhi_f16 v7, v3, v2, 0
	global_store_dwordx4 v[16:17], v[12:15], off
	global_store_dwordx4 v[16:17], v[4:7], off offset:256
	s_and_b64 vcc, exec, s[4:5]
	s_mov_b32 s31, s30
	s_mov_b32 s34, s29
	s_mov_b64 s[12:13], s[0:1]
	s_mov_b64 s[10:11], s[2:3]
	s_cbranch_vccz .LBB0_955
	s_waitcnt vmcnt(0)
	s_cmpk_gt_u32 s19, 0xff
	s_cbranch_scc1 .LBB0_962
	s_barrier

.LBB0_1117:
	s_add_i32 s41, s22, 2
	s_add_u32 s20, s14, 0x100
	s_addc_u32 s21, s15, 0
	s_add_i32 s42, 0, 0x10000
	s_waitcnt vmcnt(0)
	v_add_u32_e32 v102, s42, v230
	ds_read_b128 v[78:81], v102
	ds_read_b128 v[94:97], v102 offset:2048
	ds_read_b128 v[86:89], v102 offset:1024
	ds_read_b128 v[102:105], v102 offset:3072
	s_cmp_eq_u32 s38, s22
	s_cselect_b32 s22, s18, s39
	s_cselect_b32 s25, s17, s21
	s_cselect_b32 s24, s16, s20
	s_cselect_b32 s23, s19, s40
	v_lshl_add_u64 v[178:179], s[14:15], 0, v[200:201]
	s_add_i32 m0, s28, 0xc000
	ds_read_b128 v[122:125], v232
	ds_read_b128 v[130:133], v232 offset:2048
	ds_read_b128 v[154:157], v232 offset:4096
	ds_read_b128 v[170:173], v232 offset:6144
	ds_read_b128 v[126:129], v232 offset:1024
	ds_read_b128 v[134:137], v232 offset:3072
	ds_read_b128 v[158:161], v232 offset:5120
	ds_read_b128 v[174:177], v232 offset:7168
	global_load_lds_dwordx4 v[178:179], off
	v_lshl_add_u64 v[178:179], s[14:15], 0, v[202:203]
	s_add_i32 m0, s28, 0xe000
	s_nop 0
	global_load_lds_dwordx4 v[178:179], off
	s_waitcnt lgkmcnt(8)
	s_barrier
	s_waitcnt lgkmcnt(7)
	s_setprio 1
	v_mfma_f32_16x16x32_f16 v[166:169], v[78:81], v[122:125], v[166:169]
	v_mfma_f32_16x16x32_f16 v[162:165], v[94:97], v[122:125], v[162:165]
	s_waitcnt lgkmcnt(6)
	v_mfma_f32_16x16x32_f16 v[150:153], v[78:81], v[130:133], v[150:153]
	v_mfma_f32_16x16x32_f16 v[142:145], v[94:97], v[130:133], v[142:145]
	s_waitcnt lgkmcnt(5)
	v_mfma_f32_16x16x32_f16 v[110:113], v[78:81], v[154:157], v[110:113]
	v_mfma_f32_16x16x32_f16 v[106:109], v[94:97], v[154:157], v[106:109]
	s_waitcnt lgkmcnt(4)
	v_mfma_f32_16x16x32_f16 v[82:85], v[78:81], v[170:173], v[82:85]
	v_mfma_f32_16x16x32_f16 v[74:77], v[94:97], v[170:173], v[74:77]
	s_waitcnt lgkmcnt(3)
	v_mfma_f32_16x16x32_f16 v[166:169], v[86:89], v[126:129], v[166:169]
	v_mfma_f32_16x16x32_f16 v[162:165], v[102:105], v[126:129], v[162:165]
	s_waitcnt lgkmcnt(2)
	v_mfma_f32_16x16x32_f16 v[150:153], v[86:89], v[134:137], v[150:153]
	v_mfma_f32_16x16x32_f16 v[142:145], v[102:105], v[134:137], v[142:145]
	s_waitcnt lgkmcnt(1)
	v_mfma_f32_16x16x32_f16 v[110:113], v[86:89], v[158:161], v[110:113]
	v_mfma_f32_16x16x32_f16 v[106:109], v[102:105], v[158:161], v[106:109]
	s_waitcnt lgkmcnt(0)
	v_mfma_f32_16x16x32_f16 v[82:85], v[86:89], v[174:177], v[82:85]
	v_mfma_f32_16x16x32_f16 v[74:77], v[102:105], v[174:177], v[74:77]
	s_setprio 0
	s_barrier
	s_add_i32 s43, 0, 0x14000
	s_add_i32 s14, s42, s13
	v_add_u32_e32 v190, s43, v230
	v_lshl_add_u64 v[204:205], s[22:23], 0, v[32:33]
	s_mov_b32 m0, s14
	ds_read_b128 v[178:181], v190
	ds_read_b128 v[186:189], v190 offset:2048
	ds_read_b128 v[182:185], v190 offset:1024
	ds_read_b128 v[190:193], v190 offset:3072
	global_load_lds_dwordx4 v[204:205], off
	v_lshl_add_u64 v[206:207], s[22:23], 0, v[198:199]
	s_add_i32 m0, s14, 0x2000
	s_nop 0
	global_load_lds_dwordx4 v[206:207], off
	s_barrier
	s_waitcnt lgkmcnt(3)
	s_setprio 1
	v_mfma_f32_16x16x32_f16 v[146:149], v[178:181], v[122:125], v[146:149]
	v_mfma_f32_16x16x32_f16 v[118:121], v[178:181], v[130:133], v[118:121]
	s_waitcnt lgkmcnt(2)
	v_mfma_f32_16x16x32_f16 v[114:117], v[186:189], v[130:133], v[114:117]
	v_mfma_f32_16x16x32_f16 v[98:101], v[178:181], v[154:157], v[98:101]
	v_mfma_f32_16x16x32_f16 v[90:93], v[186:189], v[154:157], v[90:93]
	v_mfma_f32_16x16x32_f16 v[70:73], v[178:181], v[170:173], v[70:73]
	s_waitcnt lgkmcnt(1)
	v_mfma_f32_16x16x32_f16 v[66:69], v[186:189], v[170:173], v[66:69]
	v_mfma_f32_16x16x32_f16 v[146:149], v[182:185], v[126:129], v[146:149]
	v_mfma_f32_16x16x32_f16 v[122:125], v[186:189], v[122:125], v[138:141]
	v_mfma_f32_16x16x32_f16 v[118:121], v[182:185], v[134:137], v[118:121]
	s_waitcnt lgkmcnt(0)
	v_mfma_f32_16x16x32_f16 v[114:117], v[190:193], v[134:137], v[114:117]
	v_mfma_f32_16x16x32_f16 v[98:101], v[182:185], v[158:161], v[98:101]
	v_mfma_f32_16x16x32_f16 v[90:93], v[190:193], v[158:161], v[90:93]
	v_mfma_f32_16x16x32_f16 v[70:73], v[182:185], v[174:177], v[70:73]
	v_mfma_f32_16x16x32_f16 v[66:69], v[190:193], v[174:177], v[66:69]
	v_mfma_f32_16x16x32_f16 v[122:125], v[190:193], v[126:129], v[122:125]
	s_setprio 0
	s_mov_b32 m0, s28
	v_lshl_add_u64 v[208:209], s[24:25], 0, v[32:33]
	s_barrier
	ds_read_b128 v[126:129], v232 offset:16384
	ds_read_b128 v[134:137], v232 offset:18432
	ds_read_b128 v[154:157], v232 offset:20480
	ds_read_b128 v[170:173], v232 offset:22528
	ds_read_b128 v[130:133], v232 offset:17408
	ds_read_b128 v[138:141], v232 offset:19456
	ds_read_b128 v[158:161], v232 offset:21504
	ds_read_b128 v[174:177], v232 offset:23552
	global_load_lds_dwordx4 v[208:209], off
	v_lshl_add_u64 v[210:211], s[24:25], 0, v[198:199]
	s_mov_b32 m0, s29
	s_nop 0
	global_load_lds_dwordx4 v[210:211], off
	s_barrier
	s_waitcnt lgkmcnt(7)
	s_setprio 1
	v_mfma_f32_16x16x32_f16 v[62:65], v[78:81], v[126:129], v[62:65]
	v_mfma_f32_16x16x32_f16 v[58:61], v[94:97], v[126:129], v[58:61]
	s_waitcnt lgkmcnt(6)
	v_mfma_f32_16x16x32_f16 v[46:49], v[78:81], v[134:137], v[46:49]
	v_mfma_f32_16x16x32_f16 v[42:45], v[94:97], v[134:137], v[42:45]
	s_waitcnt lgkmcnt(5)
	v_mfma_f32_16x16x32_f16 v[28:31], v[78:81], v[154:157], v[28:31]
	v_mfma_f32_16x16x32_f16 v[24:27], v[94:97], v[154:157], v[24:27]
	s_waitcnt lgkmcnt(4)
	v_mfma_f32_16x16x32_f16 v[12:15], v[78:81], v[170:173], v[12:15]
	v_mfma_f32_16x16x32_f16 v[8:11], v[94:97], v[170:173], v[8:11]
	s_waitcnt lgkmcnt(3)
	v_mfma_f32_16x16x32_f16 v[62:65], v[86:89], v[130:133], v[62:65]
	v_mfma_f32_16x16x32_f16 v[58:61], v[102:105], v[130:133], v[58:61]
	s_waitcnt lgkmcnt(2)
	v_mfma_f32_16x16x32_f16 v[46:49], v[86:89], v[138:141], v[46:49]
	v_mfma_f32_16x16x32_f16 v[42:45], v[102:105], v[138:141], v[42:45]
	s_waitcnt lgkmcnt(1)
	v_mfma_f32_16x16x32_f16 v[28:31], v[86:89], v[158:161], v[28:31]
	v_mfma_f32_16x16x32_f16 v[24:27], v[102:105], v[158:161], v[24:27]
	s_waitcnt lgkmcnt(0)
	v_mfma_f32_16x16x32_f16 v[12:15], v[86:89], v[174:177], v[12:15]
	v_mfma_f32_16x16x32_f16 v[8:11], v[102:105], v[174:177], v[8:11]
	s_setprio 0
	s_barrier
	s_add_u32 s14, s22, 0x40000
	s_addc_u32 s15, s23, 0
	s_add_i32 s42, s43, s13
	v_lshl_add_u64 v[78:79], s[14:15], 0, v[32:33]
	s_mov_b32 m0, s42
	s_nop 0
	global_load_lds_dwordx4 v[78:79], off
	v_lshl_add_u64 v[78:79], s[14:15], 0, v[198:199]
	s_add_i32 m0, s42, 0x2000
	s_nop 0
	global_load_lds_dwordx4 v[78:79], off
	s_waitcnt vmcnt(6)
	s_barrier
	s_setprio 1
	v_mfma_f32_16x16x32_f16 v[54:57], v[178:181], v[126:129], v[54:57]
	v_mfma_f32_16x16x32_f16 v[50:53], v[186:189], v[126:129], v[50:53]
	v_mfma_f32_16x16x32_f16 v[38:41], v[178:181], v[134:137], v[38:41]
	v_mfma_f32_16x16x32_f16 v[34:37], v[186:189], v[134:137], v[34:37]
	v_mfma_f32_16x16x32_f16 v[20:23], v[178:181], v[154:157], v[20:23]
	v_mfma_f32_16x16x32_f16 v[16:19], v[186:189], v[154:157], v[16:19]
	v_mfma_f32_16x16x32_f16 v[4:7], v[178:181], v[170:173], v[4:7]
	v_mfma_f32_16x16x32_f16 v[0:3], v[186:189], v[170:173], v[0:3]
	v_mfma_f32_16x16x32_f16 v[54:57], v[182:185], v[130:133], v[54:57]
	v_mfma_f32_16x16x32_f16 v[50:53], v[190:193], v[130:133], v[50:53]
	v_mfma_f32_16x16x32_f16 v[38:41], v[182:185], v[138:141], v[38:41]
	v_mfma_f32_16x16x32_f16 v[34:37], v[190:193], v[138:141], v[34:37]
	v_mfma_f32_16x16x32_f16 v[20:23], v[182:185], v[158:161], v[20:23]
	v_mfma_f32_16x16x32_f16 v[16:19], v[190:193], v[158:161], v[16:19]
	v_mfma_f32_16x16x32_f16 v[4:7], v[182:185], v[174:177], v[4:7]
	v_mfma_f32_16x16x32_f16 v[0:3], v[190:193], v[174:177], v[0:3]
	s_setprio 0
	s_add_i32 s42, 0, 0x18000
	v_add_u32_e32 v102, s42, v230
	s_barrier
	ds_read_b128 v[78:81], v102
	ds_read_b128 v[86:89], v102 offset:1024
	ds_read_b128 v[94:97], v102 offset:2048
	ds_read_b128 v[102:105], v102 offset:3072
	s_add_u32 s14, s24, 0x40000
	s_addc_u32 s15, s25, 0
	s_mov_b32 m0, s30
	v_lshl_add_u64 v[138:139], s[14:15], 0, v[32:33]
	ds_read_b128 v[126:129], v232 offset:32768
	ds_read_b128 v[130:133], v232 offset:33792
	ds_read_b128 v[134:137], v232 offset:34816
	ds_read_b128 v[154:157], v232 offset:35840
	ds_read_b128 v[158:161], v232 offset:36864
	ds_read_b128 v[174:177], v232 offset:38912
	ds_read_b128 v[170:173], v232 offset:37888
	ds_read_b128 v[178:181], v232 offset:39936
	global_load_lds_dwordx4 v[138:139], off
	v_lshl_add_u64 v[138:139], s[14:15], 0, v[198:199]
	s_mov_b32 m0, s31
	s_nop 0
	global_load_lds_dwordx4 v[138:139], off
	s_waitcnt lgkmcnt(8)
	s_barrier
	s_waitcnt lgkmcnt(6)
	s_setprio 1
	v_mfma_f32_16x16x32_f16 v[138:141], v[78:81], v[126:129], v[166:169]
	v_mfma_f32_16x16x32_f16 v[166:169], v[86:89], v[130:133], v[138:141]
	v_mfma_f32_16x16x32_f16 v[138:141], v[94:97], v[126:129], v[162:165]
	v_mfma_f32_16x16x32_f16 v[162:165], v[102:105], v[130:133], v[138:141]
	s_waitcnt lgkmcnt(4)
	v_mfma_f32_16x16x32_f16 v[138:141], v[78:81], v[134:137], v[150:153]
	v_mfma_f32_16x16x32_f16 v[150:153], v[86:89], v[154:157], v[138:141]
	s_waitcnt lgkmcnt(3)
	v_mfma_f32_16x16x32_f16 v[138:141], v[94:97], v[134:137], v[142:145]
	v_mfma_f32_16x16x32_f16 v[110:113], v[78:81], v[158:161], v[110:113]
	s_waitcnt lgkmcnt(2)
	v_mfma_f32_16x16x32_f16 v[106:109], v[94:97], v[158:161], v[106:109]
	v_mfma_f32_16x16x32_f16 v[82:85], v[78:81], v[174:177], v[82:85]
	v_mfma_f32_16x16x32_f16 v[74:77], v[94:97], v[174:177], v[74:77]
	v_mfma_f32_16x16x32_f16 v[142:145], v[102:105], v[154:157], v[138:141]
	s_waitcnt lgkmcnt(1)
	v_mfma_f32_16x16x32_f16 v[110:113], v[86:89], v[170:173], v[110:113]
	v_mfma_f32_16x16x32_f16 v[106:109], v[102:105], v[170:173], v[106:109]
	s_waitcnt lgkmcnt(0)
	v_mfma_f32_16x16x32_f16 v[82:85], v[86:89], v[178:181], v[82:85]
	v_mfma_f32_16x16x32_f16 v[74:77], v[102:105], v[178:181], v[74:77]
	s_setprio 0
	s_barrier
	s_add_i32 s24, 0, 0x1c000
	v_add_u32_e32 v138, s24, v230
	s_add_i32 s14, s42, s13
	ds_read_b128 v[182:185], v138
	ds_read_b128 v[190:193], v138 offset:2048
	ds_read_b128 v[186:189], v138 offset:1024
	ds_read_b128 v[194:197], v138 offset:3072
	v_lshl_add_u64 v[138:139], v[204:205], 0, s[84:85]
	s_mov_b32 m0, s14
	s_nop 0
	global_load_lds_dwordx4 v[138:139], off
	v_lshl_add_u64 v[138:139], v[206:207], 0, s[84:85]
	s_add_i32 m0, s14, 0x2000
	s_nop 0
	global_load_lds_dwordx4 v[138:139], off
	s_barrier
	s_waitcnt lgkmcnt(2)
	s_setprio 1
	v_mfma_f32_16x16x32_f16 v[138:141], v[182:185], v[126:129], v[146:149]
	v_mfma_f32_16x16x32_f16 v[122:125], v[190:193], v[126:129], v[122:125]
	v_mfma_f32_16x16x32_f16 v[118:121], v[182:185], v[134:137], v[118:121]
	v_mfma_f32_16x16x32_f16 v[114:117], v[190:193], v[134:137], v[114:117]
	v_mfma_f32_16x16x32_f16 v[98:101], v[182:185], v[158:161], v[98:101]
	v_mfma_f32_16x16x32_f16 v[90:93], v[190:193], v[158:161], v[90:93]
	v_mfma_f32_16x16x32_f16 v[70:73], v[182:185], v[174:177], v[70:73]
	v_mfma_f32_16x16x32_f16 v[66:69], v[190:193], v[174:177], v[66:69]
	s_waitcnt lgkmcnt(0)
	v_mfma_f32_16x16x32_f16 v[146:149], v[186:189], v[130:133], v[138:141]
	v_mfma_f32_16x16x32_f16 v[138:141], v[194:197], v[130:133], v[122:125]
	v_mfma_f32_16x16x32_f16 v[118:121], v[186:189], v[154:157], v[118:121]
	v_mfma_f32_16x16x32_f16 v[114:117], v[194:197], v[154:157], v[114:117]
	v_mfma_f32_16x16x32_f16 v[98:101], v[186:189], v[170:173], v[98:101]
	v_mfma_f32_16x16x32_f16 v[90:93], v[194:197], v[170:173], v[90:93]
	v_mfma_f32_16x16x32_f16 v[70:73], v[186:189], v[178:181], v[70:73]
	v_mfma_f32_16x16x32_f16 v[66:69], v[194:197], v[178:181], v[66:69]
	s_setprio 0
	s_mov_b32 m0, s34
	v_lshl_add_u64 v[178:179], v[208:209], 0, s[84:85]
	s_barrier
	ds_read_b128 v[122:125], v232 offset:49152
	ds_read_b128 v[130:133], v232 offset:51200
	ds_read_b128 v[154:157], v232 offset:53248
	ds_read_b128 v[170:173], v232 offset:55296
	ds_read_b128 v[126:129], v232 offset:50176
	ds_read_b128 v[134:137], v232 offset:52224
	ds_read_b128 v[158:161], v232 offset:54272
	ds_read_b128 v[174:177], v232 offset:56320
	global_load_lds_dwordx4 v[178:179], off
	v_lshl_add_u64 v[178:179], v[210:211], 0, s[84:85]
	s_mov_b32 m0, s35
	s_nop 0
	global_load_lds_dwordx4 v[178:179], off
	s_barrier
	s_waitcnt lgkmcnt(7)
	s_setprio 1
	v_mfma_f32_16x16x32_f16 v[62:65], v[78:81], v[122:125], v[62:65]
	v_mfma_f32_16x16x32_f16 v[58:61], v[94:97], v[122:125], v[58:61]
	s_waitcnt lgkmcnt(6)
	v_mfma_f32_16x16x32_f16 v[46:49], v[78:81], v[130:133], v[46:49]
	v_mfma_f32_16x16x32_f16 v[42:45], v[94:97], v[130:133], v[42:45]
	s_waitcnt lgkmcnt(5)
	v_mfma_f32_16x16x32_f16 v[28:31], v[78:81], v[154:157], v[28:31]
	v_mfma_f32_16x16x32_f16 v[24:27], v[94:97], v[154:157], v[24:27]
	s_waitcnt lgkmcnt(4)
	v_mfma_f32_16x16x32_f16 v[12:15], v[78:81], v[170:173], v[12:15]
	v_mfma_f32_16x16x32_f16 v[8:11], v[94:97], v[170:173], v[8:11]
	s_waitcnt lgkmcnt(3)
	v_mfma_f32_16x16x32_f16 v[62:65], v[86:89], v[126:129], v[62:65]
	v_mfma_f32_16x16x32_f16 v[58:61], v[102:105], v[126:129], v[58:61]
	s_waitcnt lgkmcnt(2)
	v_mfma_f32_16x16x32_f16 v[46:49], v[86:89], v[134:137], v[46:49]
	v_mfma_f32_16x16x32_f16 v[42:45], v[102:105], v[134:137], v[42:45]
	s_waitcnt lgkmcnt(1)
	v_mfma_f32_16x16x32_f16 v[28:31], v[86:89], v[158:161], v[28:31]
	v_mfma_f32_16x16x32_f16 v[24:27], v[102:105], v[158:161], v[24:27]
	s_waitcnt lgkmcnt(0)
	v_mfma_f32_16x16x32_f16 v[12:15], v[86:89], v[174:177], v[12:15]
	v_mfma_f32_16x16x32_f16 v[8:11], v[102:105], v[174:177], v[8:11]
	s_setprio 0
	s_barrier
	s_add_u32 s14, s22, 0x40080
	s_addc_u32 s15, s23, 0
	s_add_i32 s22, s24, s13
	v_lshl_add_u64 v[78:79], s[14:15], 0, v[32:33]
	s_mov_b32 m0, s22
	s_nop 0
	global_load_lds_dwordx4 v[78:79], off
	v_lshl_add_u64 v[78:79], s[14:15], 0, v[198:199]
	s_add_i32 m0, s22, 0x2000
	s_nop 0
	global_load_lds_dwordx4 v[78:79], off
	s_waitcnt vmcnt(6)
	s_barrier
	s_setprio 1
	v_mfma_f32_16x16x32_f16 v[54:57], v[182:185], v[122:125], v[54:57]
	v_mfma_f32_16x16x32_f16 v[50:53], v[190:193], v[122:125], v[50:53]
	v_mfma_f32_16x16x32_f16 v[38:41], v[182:185], v[130:133], v[38:41]
	v_mfma_f32_16x16x32_f16 v[34:37], v[190:193], v[130:133], v[34:37]
	v_mfma_f32_16x16x32_f16 v[20:23], v[182:185], v[154:157], v[20:23]
	v_mfma_f32_16x16x32_f16 v[16:19], v[190:193], v[154:157], v[16:19]
	v_mfma_f32_16x16x32_f16 v[4:7], v[182:185], v[170:173], v[4:7]
	v_mfma_f32_16x16x32_f16 v[0:3], v[190:193], v[170:173], v[0:3]
	v_mfma_f32_16x16x32_f16 v[54:57], v[186:189], v[126:129], v[54:57]
	v_mfma_f32_16x16x32_f16 v[50:53], v[194:197], v[126:129], v[50:53]
	v_mfma_f32_16x16x32_f16 v[38:41], v[186:189], v[134:137], v[38:41]
	v_mfma_f32_16x16x32_f16 v[34:37], v[194:197], v[134:137], v[34:37]
	v_mfma_f32_16x16x32_f16 v[20:23], v[186:189], v[158:161], v[20:23]
	v_mfma_f32_16x16x32_f16 v[16:19], v[194:197], v[158:161], v[16:19]
	v_mfma_f32_16x16x32_f16 v[4:7], v[186:189], v[174:177], v[4:7]
	v_mfma_f32_16x16x32_f16 v[0:3], v[194:197], v[174:177], v[0:3]
	s_setprio 0
	s_add_u32 s39, s39, 0x100
	s_addc_u32 s40, s40, 0
	s_cmp_ge_u32 s41, s37
	s_mov_b64 s[14:15], s[20:21]
	s_mov_b32 s22, s41
	s_barrier
	s_cbranch_scc0 .LBB0_1117
	v_lshl_or_b32 v124, s12, 8, v231
	s_cmp_eq_u32 s10, 0
	s_movk_i32 s12, 0x5000
	s_cselect_b32 s12, 0xe000, s12
	v_readlane_b32 s14, v252, 51
	s_add_u32 s14, s14, s12
	v_readlane_b32 s12, v252, 52
	s_addc_u32 s15, s12, 0
	v_ashrrev_i32_e32 v125, 31, v124
	v_lshl_add_u64 v[86:87], v[124:125], 2, s[14:15]
	global_load_dwordx4 v[94:97], v[86:87], off offset:16
	global_load_dwordx4 v[102:105], v[86:87], off
	global_load_dwordx4 v[78:81], v[86:87], off offset:528
	s_nop 0
	global_load_dwordx4 v[86:89], v[86:87], off offset:512
	v_lshl_add_u32 v130, s10, 8, v229
	v_or_b32_e32 v128, 16, v130
	v_or_b32_e32 v126, 32, v130
	v_or_b32_e32 v122, 48, v130
	s_cmp_eq_u32 s11, 0
	v_ashrrev_i32_e32 v131, 31, v130
	v_ashrrev_i32_e32 v129, 31, v128
	v_ashrrev_i32_e32 v127, 31, v126
	v_ashrrev_i32_e32 v123, 31, v122
	s_cbranch_scc1 .LBB0_1120
	s_add_i32 s96, s11, -1
	s_lshl_b64 s[10:11], s[96:97], 20
	v_readlane_b32 s14, v252, 11
	v_readlane_b32 s15, v252, 12
	s_add_u32 s10, s14, s10
	s_addc_u32 s11, s15, s11
	v_lshlrev_b64 v[132:133], 2, v[124:125]
	v_lshrrev_b32_e32 v134, 5, v220
	v_mul_u32_u24_e32 v134, 48, v134
	s_nop 0
	v_sub_co_u32_e32 v132, vcc, v132, v134
	s_nop 1
	v_subbrev_co_u32_e32 v133, vcc, 0, v133, vcc
	v_lshl_add_u64 v[132:133], s[10:11], 0, v[132:133]
	s_mov_b64 s[10:11], 0x80000
	v_lshlrev_b64 v[204:205], 12, v[130:131]
	v_lshl_add_u64 v[204:205], v[204:205], 0, v[132:133]
	v_lshl_add_u64 v[212:213], v[204:205], 0, s[10:11]
	v_lshlrev_b64 v[206:207], 12, v[128:129]
	v_lshl_add_u64 v[206:207], v[206:207], 0, v[132:133]
	v_lshl_add_u64 v[214:215], v[206:207], 0, s[10:11]
	v_lshlrev_b64 v[208:209], 12, v[126:127]
	v_lshl_add_u64 v[208:209], v[208:209], 0, v[132:133]
	v_lshl_add_u64 v[216:217], v[208:209], 0, s[10:11]
	v_lshlrev_b64 v[210:211], 12, v[122:123]
	v_lshl_add_u64 v[210:211], v[210:211], 0, v[132:133]
	v_lshl_add_u64 v[218:219], v[210:211], 0, s[10:11]
	s_waitcnt vmcnt(0)
	v_pk_mul_f32 v[172:173], v[166:167], v[102:103]
	v_pk_mul_f32 v[174:175], v[168:169], v[104:105]
	v_pk_mul_f32 v[176:177], v[162:163], v[94:95]
	v_pk_mul_f32 v[178:179], v[164:165], v[96:97]
	s_nop 1
	v_permlane32_swap_b32_e32 v172, v176
	v_permlane32_swap_b32_e32 v173, v177
	v_permlane32_swap_b32_e32 v174, v178
	v_permlane32_swap_b32_e32 v175, v179
	s_nop 0
	global_store_dwordx4 v[204:205], v[172:175], off
	global_store_dwordx4 v[204:205], v[176:179], off offset:64
	v_pk_mul_f32 v[180:181], v[146:147], v[86:87]
	v_pk_mul_f32 v[182:183], v[148:149], v[88:89]
	v_pk_mul_f32 v[184:185], v[138:139], v[78:79]
	v_pk_mul_f32 v[186:187], v[140:141], v[80:81]
	s_nop 1
	v_permlane32_swap_b32_e32 v180, v184
	v_permlane32_swap_b32_e32 v181, v185
	v_permlane32_swap_b32_e32 v182, v186
	v_permlane32_swap_b32_e32 v183, v187
	s_nop 0
	global_store_dwordx4 v[204:205], v[180:183], off offset:512
	global_store_dwordx4 v[204:205], v[184:187], off offset:576
	v_pk_mul_f32 v[188:189], v[150:151], v[102:103]
	v_pk_mul_f32 v[190:191], v[152:153], v[104:105]
	v_pk_mul_f32 v[192:193], v[142:143], v[94:95]
	v_pk_mul_f32 v[194:195], v[144:145], v[96:97]
	s_nop 1
	v_permlane32_swap_b32_e32 v188, v192
	v_permlane32_swap_b32_e32 v189, v193
	v_permlane32_swap_b32_e32 v190, v194
	v_permlane32_swap_b32_e32 v191, v195
	s_nop 0
	global_store_dwordx4 v[206:207], v[188:191], off
	global_store_dwordx4 v[206:207], v[192:195], off offset:64
	v_pk_mul_f32 v[154:155], v[118:119], v[86:87]
	v_pk_mul_f32 v[156:157], v[120:121], v[88:89]
	v_pk_mul_f32 v[158:159], v[114:115], v[78:79]
	v_pk_mul_f32 v[160:161], v[116:117], v[80:81]
	s_nop 1
	v_permlane32_swap_b32_e32 v154, v158
	v_permlane32_swap_b32_e32 v155, v159
	v_permlane32_swap_b32_e32 v156, v160
	v_permlane32_swap_b32_e32 v157, v161
	s_nop 0
	global_store_dwordx4 v[206:207], v[154:157], off offset:512
	global_store_dwordx4 v[206:207], v[158:161], off offset:576
	v_pk_mul_f32 v[172:173], v[110:111], v[102:103]
	v_pk_mul_f32 v[174:175], v[112:113], v[104:105]
	v_pk_mul_f32 v[176:177], v[106:107], v[94:95]
	v_pk_mul_f32 v[178:179], v[108:109], v[96:97]
	s_nop 1
	v_permlane32_swap_b32_e32 v172, v176
	v_permlane32_swap_b32_e32 v173, v177
	v_permlane32_swap_b32_e32 v174, v178
	v_permlane32_swap_b32_e32 v175, v179
	s_nop 0
	global_store_dwordx4 v[208:209], v[172:175], off
	global_store_dwordx4 v[208:209], v[176:179], off offset:64
	v_pk_mul_f32 v[180:181], v[98:99], v[86:87]
	v_pk_mul_f32 v[182:183], v[100:101], v[88:89]
	v_pk_mul_f32 v[184:185], v[90:91], v[78:79]
	v_pk_mul_f32 v[186:187], v[92:93], v[80:81]
	s_nop 1
	v_permlane32_swap_b32_e32 v180, v184
	v_permlane32_swap_b32_e32 v181, v185
	v_permlane32_swap_b32_e32 v182, v186
	v_permlane32_swap_b32_e32 v183, v187
	s_nop 0
	global_store_dwordx4 v[208:209], v[180:183], off offset:512
	global_store_dwordx4 v[208:209], v[184:187], off offset:576
	v_pk_mul_f32 v[188:189], v[82:83], v[102:103]
	v_pk_mul_f32 v[190:191], v[84:85], v[104:105]
	v_pk_mul_f32 v[192:193], v[74:75], v[94:95]
	v_pk_mul_f32 v[194:195], v[76:77], v[96:97]
	s_nop 1
	v_permlane32_swap_b32_e32 v188, v192
	v_permlane32_swap_b32_e32 v189, v193
	v_permlane32_swap_b32_e32 v190, v194
	v_permlane32_swap_b32_e32 v191, v195
	s_nop 0
	global_store_dwordx4 v[210:211], v[188:191], off
	global_store_dwordx4 v[210:211], v[192:195], off offset:64
	v_pk_mul_f32 v[154:155], v[70:71], v[86:87]
	v_pk_mul_f32 v[156:157], v[72:73], v[88:89]
	v_pk_mul_f32 v[158:159], v[66:67], v[78:79]
	v_pk_mul_f32 v[160:161], v[68:69], v[80:81]
	s_nop 1
	v_permlane32_swap_b32_e32 v154, v158
	v_permlane32_swap_b32_e32 v155, v159
	v_permlane32_swap_b32_e32 v156, v160
	v_permlane32_swap_b32_e32 v157, v161
	s_nop 0
	global_store_dwordx4 v[210:211], v[154:157], off offset:512
	global_store_dwordx4 v[210:211], v[158:161], off offset:576
	v_pk_mul_f32 v[172:173], v[62:63], v[102:103]
	v_pk_mul_f32 v[174:175], v[64:65], v[104:105]
	v_pk_mul_f32 v[176:177], v[58:59], v[94:95]
	v_pk_mul_f32 v[178:179], v[60:61], v[96:97]
	s_nop 1
	v_permlane32_swap_b32_e32 v172, v176
	v_permlane32_swap_b32_e32 v173, v177
	v_permlane32_swap_b32_e32 v174, v178
	v_permlane32_swap_b32_e32 v175, v179
	s_nop 0
	global_store_dwordx4 v[212:213], v[172:175], off
	global_store_dwordx4 v[212:213], v[176:179], off offset:64
	v_pk_mul_f32 v[180:181], v[54:55], v[86:87]
	v_pk_mul_f32 v[182:183], v[56:57], v[88:89]
	v_pk_mul_f32 v[184:185], v[50:51], v[78:79]
	v_pk_mul_f32 v[186:187], v[52:53], v[80:81]
	s_nop 1
	v_permlane32_swap_b32_e32 v180, v184
	v_permlane32_swap_b32_e32 v181, v185
	v_permlane32_swap_b32_e32 v182, v186
	v_permlane32_swap_b32_e32 v183, v187
	s_nop 0
	global_store_dwordx4 v[212:213], v[180:183], off offset:512
	global_store_dwordx4 v[212:213], v[184:187], off offset:576
	v_pk_mul_f32 v[188:189], v[46:47], v[102:103]
	v_pk_mul_f32 v[190:191], v[48:49], v[104:105]
	v_pk_mul_f32 v[192:193], v[42:43], v[94:95]
	v_pk_mul_f32 v[194:195], v[44:45], v[96:97]
	s_nop 1
	v_permlane32_swap_b32_e32 v188, v192
	v_permlane32_swap_b32_e32 v189, v193
	v_permlane32_swap_b32_e32 v190, v194
	v_permlane32_swap_b32_e32 v191, v195
	s_nop 0
	global_store_dwordx4 v[214:215], v[188:191], off
	global_store_dwordx4 v[214:215], v[192:195], off offset:64
	v_pk_mul_f32 v[154:155], v[38:39], v[86:87]
	v_pk_mul_f32 v[156:157], v[40:41], v[88:89]
	v_pk_mul_f32 v[158:159], v[34:35], v[78:79]
	v_pk_mul_f32 v[160:161], v[36:37], v[80:81]
	s_nop 1
	v_permlane32_swap_b32_e32 v154, v158
	v_permlane32_swap_b32_e32 v155, v159
	v_permlane32_swap_b32_e32 v156, v160
	v_permlane32_swap_b32_e32 v157, v161
	s_nop 0
	global_store_dwordx4 v[214:215], v[154:157], off offset:512
	global_store_dwordx4 v[214:215], v[158:161], off offset:576
	v_pk_mul_f32 v[172:173], v[28:29], v[102:103]
	v_pk_mul_f32 v[174:175], v[30:31], v[104:105]
	v_pk_mul_f32 v[176:177], v[24:25], v[94:95]
	v_pk_mul_f32 v[178:179], v[26:27], v[96:97]
	s_nop 1
	v_permlane32_swap_b32_e32 v172, v176
	v_permlane32_swap_b32_e32 v173, v177
	v_permlane32_swap_b32_e32 v174, v178
	v_permlane32_swap_b32_e32 v175, v179
	s_nop 0
	global_store_dwordx4 v[216:217], v[172:175], off
	global_store_dwordx4 v[216:217], v[176:179], off offset:64
	v_pk_mul_f32 v[180:181], v[20:21], v[86:87]
	v_pk_mul_f32 v[182:183], v[22:23], v[88:89]
	v_pk_mul_f32 v[184:185], v[16:17], v[78:79]
	v_pk_mul_f32 v[186:187], v[18:19], v[80:81]
	s_nop 1
	v_permlane32_swap_b32_e32 v180, v184
	v_permlane32_swap_b32_e32 v181, v185
	v_permlane32_swap_b32_e32 v182, v186
	v_permlane32_swap_b32_e32 v183, v187
	s_nop 0
	global_store_dwordx4 v[216:217], v[180:183], off offset:512
	global_store_dwordx4 v[216:217], v[184:187], off offset:576
	v_pk_mul_f32 v[188:189], v[12:13], v[102:103]
	v_pk_mul_f32 v[190:191], v[14:15], v[104:105]
	v_pk_mul_f32 v[192:193], v[8:9], v[94:95]
	v_pk_mul_f32 v[194:195], v[10:11], v[96:97]
	s_nop 1
	v_permlane32_swap_b32_e32 v188, v192
	v_permlane32_swap_b32_e32 v189, v193
	v_permlane32_swap_b32_e32 v190, v194
	v_permlane32_swap_b32_e32 v191, v195
	s_nop 0
	global_store_dwordx4 v[218:219], v[188:191], off
	global_store_dwordx4 v[218:219], v[192:195], off offset:64
	v_pk_mul_f32 v[154:155], v[4:5], v[86:87]
	v_pk_mul_f32 v[156:157], v[6:7], v[88:89]
	v_pk_mul_f32 v[158:159], v[0:1], v[78:79]
	v_pk_mul_f32 v[160:161], v[2:3], v[80:81]
	s_nop 1
	v_permlane32_swap_b32_e32 v154, v158
	v_permlane32_swap_b32_e32 v155, v159
	v_permlane32_swap_b32_e32 v156, v160
	v_permlane32_swap_b32_e32 v157, v161
	s_nop 0
	global_store_dwordx4 v[218:219], v[154:157], off offset:512
	global_store_dwordx4 v[218:219], v[158:161], off offset:576
	s_cbranch_execnz .LBB0_1104
	s_branch .LBB0_1103

.LBB0_1276:
	s_add_u32 s16, s14, 0x100
	s_addc_u32 s17, s15, 0
	s_add_i32 s39, 0, 0x10000
	v_add_u32_e32 v152, s39, v137
	ds_read_b128 v[140:143], v152
	ds_read_b128 v[148:151], v152 offset:2048
	ds_read_b128 v[144:147], v152 offset:1024
	ds_read_b128 v[152:155], v152 offset:3072
	s_cmp_eq_u32 s38, 12
	s_cselect_b32 s21, s11, s17
	s_cselect_b32 s20, s10, s16
	s_cselect_b32 s19, s13, s37
	s_cselect_b32 s18, s12, s3
	v_lshl_add_u64 v[188:189], s[14:15], 0, v[132:133]
	s_add_i32 m0, s9, 0xc000
	ds_read_b128 v[156:159], v139
	ds_read_b128 v[164:167], v139 offset:2048
	ds_read_b128 v[172:175], v139 offset:4096
	ds_read_b128 v[180:183], v139 offset:6144
	ds_read_b128 v[160:163], v139 offset:1024
	ds_read_b128 v[168:171], v139 offset:3072
	ds_read_b128 v[176:179], v139 offset:5120
	ds_read_b128 v[184:187], v139 offset:7168
	global_load_lds_dwordx4 v[188:189], off
	v_lshl_add_u64 v[188:189], s[14:15], 0, v[134:135]
	s_add_i32 m0, s9, 0xe000
	s_nop 0
	global_load_lds_dwordx4 v[188:189], off
	s_waitcnt lgkmcnt(8)
	s_barrier
	s_waitcnt lgkmcnt(7)
	s_setprio 1
	v_mfma_f32_16x16x32_f16 v[126:129], v[140:143], v[156:159], v[126:129]
	v_mfma_f32_16x16x32_f16 v[122:125], v[148:151], v[156:159], v[122:125]
	s_waitcnt lgkmcnt(6)
	v_mfma_f32_16x16x32_f16 v[110:113], v[140:143], v[164:167], v[110:113]
	v_mfma_f32_16x16x32_f16 v[106:109], v[148:151], v[164:167], v[106:109]
	s_waitcnt lgkmcnt(5)
	v_mfma_f32_16x16x32_f16 v[94:97], v[140:143], v[172:175], v[94:97]
	v_mfma_f32_16x16x32_f16 v[90:93], v[148:151], v[172:175], v[90:93]
	s_waitcnt lgkmcnt(4)
	v_mfma_f32_16x16x32_f16 v[78:81], v[140:143], v[180:183], v[78:81]
	v_mfma_f32_16x16x32_f16 v[74:77], v[148:151], v[180:183], v[74:77]
	s_waitcnt lgkmcnt(3)
	v_mfma_f32_16x16x32_f16 v[126:129], v[144:147], v[160:163], v[126:129]
	v_mfma_f32_16x16x32_f16 v[122:125], v[152:155], v[160:163], v[122:125]
	s_waitcnt lgkmcnt(2)
	v_mfma_f32_16x16x32_f16 v[110:113], v[144:147], v[168:171], v[110:113]
	v_mfma_f32_16x16x32_f16 v[106:109], v[152:155], v[168:171], v[106:109]
	s_waitcnt lgkmcnt(1)
	v_mfma_f32_16x16x32_f16 v[94:97], v[144:147], v[176:179], v[94:97]
	v_mfma_f32_16x16x32_f16 v[90:93], v[152:155], v[176:179], v[90:93]
	s_waitcnt lgkmcnt(0)
	v_mfma_f32_16x16x32_f16 v[78:81], v[144:147], v[184:187], v[78:81]
	v_mfma_f32_16x16x32_f16 v[74:77], v[152:155], v[184:187], v[74:77]
	s_setprio 0
	s_barrier
	s_add_i32 s40, 0, 0x14000
	s_add_i32 s14, s39, s26
	v_add_u32_e32 v200, s40, v137
	v_lshl_add_u64 v[204:205], s[18:19], 0, v[32:33]
	s_mov_b32 m0, s14
	ds_read_b128 v[188:191], v200
	ds_read_b128 v[196:199], v200 offset:2048
	ds_read_b128 v[192:195], v200 offset:1024
	ds_read_b128 v[200:203], v200 offset:3072
	global_load_lds_dwordx4 v[204:205], off
	v_lshl_add_u64 v[206:207], s[18:19], 0, v[130:131]
	s_add_i32 m0, s14, 0x2000
	s_nop 0
	global_load_lds_dwordx4 v[206:207], off
	s_barrier
	s_waitcnt lgkmcnt(2)
	s_setprio 1
	v_mfma_f32_16x16x32_f16 v[118:121], v[188:191], v[156:159], v[118:121]
	v_mfma_f32_16x16x32_f16 v[114:117], v[196:199], v[156:159], v[114:117]
	v_mfma_f32_16x16x32_f16 v[102:105], v[188:191], v[164:167], v[102:105]
	v_mfma_f32_16x16x32_f16 v[98:101], v[196:199], v[164:167], v[98:101]
	v_mfma_f32_16x16x32_f16 v[86:89], v[188:191], v[172:175], v[86:89]
	v_mfma_f32_16x16x32_f16 v[82:85], v[196:199], v[172:175], v[82:85]
	v_mfma_f32_16x16x32_f16 v[70:73], v[188:191], v[180:183], v[70:73]
	v_mfma_f32_16x16x32_f16 v[66:69], v[196:199], v[180:183], v[66:69]
	s_waitcnt lgkmcnt(0)
	v_mfma_f32_16x16x32_f16 v[118:121], v[192:195], v[160:163], v[118:121]
	v_mfma_f32_16x16x32_f16 v[114:117], v[200:203], v[160:163], v[114:117]
	v_mfma_f32_16x16x32_f16 v[102:105], v[192:195], v[168:171], v[102:105]
	v_mfma_f32_16x16x32_f16 v[98:101], v[200:203], v[168:171], v[98:101]
	v_mfma_f32_16x16x32_f16 v[86:89], v[192:195], v[176:179], v[86:89]
	v_mfma_f32_16x16x32_f16 v[82:85], v[200:203], v[176:179], v[82:85]
	v_mfma_f32_16x16x32_f16 v[70:73], v[192:195], v[184:187], v[70:73]
	v_mfma_f32_16x16x32_f16 v[66:69], v[200:203], v[184:187], v[66:69]
	s_setprio 0
	s_mov_b32 m0, s9
	v_lshl_add_u64 v[208:209], s[20:21], 0, v[32:33]
	s_barrier
	ds_read_b128 v[156:159], v139 offset:16384
	ds_read_b128 v[164:167], v139 offset:18432
	ds_read_b128 v[172:175], v139 offset:20480
	ds_read_b128 v[180:183], v139 offset:22528
	ds_read_b128 v[160:163], v139 offset:17408
	ds_read_b128 v[168:171], v139 offset:19456
	ds_read_b128 v[176:179], v139 offset:21504
	ds_read_b128 v[184:187], v139 offset:23552
	global_load_lds_dwordx4 v[208:209], off
	v_lshl_add_u64 v[210:211], s[20:21], 0, v[130:131]
	s_mov_b32 m0, s27
	s_nop 0
	global_load_lds_dwordx4 v[210:211], off
	s_barrier
	s_waitcnt lgkmcnt(7)
	s_setprio 1
	v_mfma_f32_16x16x32_f16 v[62:65], v[140:143], v[156:159], v[62:65]
	v_mfma_f32_16x16x32_f16 v[58:61], v[148:151], v[156:159], v[58:61]
	s_waitcnt lgkmcnt(6)
	v_mfma_f32_16x16x32_f16 v[46:49], v[140:143], v[164:167], v[46:49]
	v_mfma_f32_16x16x32_f16 v[42:45], v[148:151], v[164:167], v[42:45]
	s_waitcnt lgkmcnt(5)
	v_mfma_f32_16x16x32_f16 v[28:31], v[140:143], v[172:175], v[28:31]
	v_mfma_f32_16x16x32_f16 v[24:27], v[148:151], v[172:175], v[24:27]
	s_waitcnt lgkmcnt(4)
	v_mfma_f32_16x16x32_f16 v[12:15], v[140:143], v[180:183], v[12:15]
	v_mfma_f32_16x16x32_f16 v[8:11], v[148:151], v[180:183], v[8:11]
	s_waitcnt lgkmcnt(3)
	v_mfma_f32_16x16x32_f16 v[62:65], v[144:147], v[160:163], v[62:65]
	v_mfma_f32_16x16x32_f16 v[58:61], v[152:155], v[160:163], v[58:61]
	s_waitcnt lgkmcnt(2)
	v_mfma_f32_16x16x32_f16 v[46:49], v[144:147], v[168:171], v[46:49]
	v_mfma_f32_16x16x32_f16 v[42:45], v[152:155], v[168:171], v[42:45]
	s_waitcnt lgkmcnt(1)
	v_mfma_f32_16x16x32_f16 v[28:31], v[144:147], v[176:179], v[28:31]
	v_mfma_f32_16x16x32_f16 v[24:27], v[152:155], v[176:179], v[24:27]
	s_waitcnt lgkmcnt(0)
	v_mfma_f32_16x16x32_f16 v[12:15], v[144:147], v[184:187], v[12:15]
	v_mfma_f32_16x16x32_f16 v[8:11], v[152:155], v[184:187], v[8:11]
	s_setprio 0
	s_barrier
	s_add_u32 s14, s18, 0x40000
	s_addc_u32 s15, s19, 0
	s_add_i32 s39, s40, s26
	v_lshl_add_u64 v[140:141], s[14:15], 0, v[32:33]
	s_mov_b32 m0, s39
	s_nop 0
	global_load_lds_dwordx4 v[140:141], off
	v_lshl_add_u64 v[140:141], s[14:15], 0, v[130:131]
	s_add_i32 m0, s39, 0x2000
	s_nop 0
	global_load_lds_dwordx4 v[140:141], off
	s_waitcnt vmcnt(6)
	s_barrier
	s_setprio 1
	v_mfma_f32_16x16x32_f16 v[54:57], v[188:191], v[156:159], v[54:57]
	v_mfma_f32_16x16x32_f16 v[50:53], v[196:199], v[156:159], v[50:53]
	v_mfma_f32_16x16x32_f16 v[38:41], v[188:191], v[164:167], v[38:41]
	v_mfma_f32_16x16x32_f16 v[34:37], v[196:199], v[164:167], v[34:37]
	v_mfma_f32_16x16x32_f16 v[20:23], v[188:191], v[172:175], v[20:23]
	v_mfma_f32_16x16x32_f16 v[16:19], v[196:199], v[172:175], v[16:19]
	v_mfma_f32_16x16x32_f16 v[4:7], v[188:191], v[180:183], v[4:7]
	v_mfma_f32_16x16x32_f16 v[0:3], v[196:199], v[180:183], v[0:3]
	v_mfma_f32_16x16x32_f16 v[54:57], v[192:195], v[160:163], v[54:57]
	v_mfma_f32_16x16x32_f16 v[50:53], v[200:203], v[160:163], v[50:53]
	v_mfma_f32_16x16x32_f16 v[38:41], v[192:195], v[168:171], v[38:41]
	v_mfma_f32_16x16x32_f16 v[34:37], v[200:203], v[168:171], v[34:37]
	v_mfma_f32_16x16x32_f16 v[20:23], v[192:195], v[176:179], v[20:23]
	v_mfma_f32_16x16x32_f16 v[16:19], v[200:203], v[176:179], v[16:19]
	v_mfma_f32_16x16x32_f16 v[4:7], v[192:195], v[184:187], v[4:7]
	v_mfma_f32_16x16x32_f16 v[0:3], v[200:203], v[184:187], v[0:3]
	s_setprio 0
	s_add_i32 s39, 0, 0x18000
	v_add_u32_e32 v152, s39, v137
	s_barrier
	ds_read_b128 v[140:143], v152
	ds_read_b128 v[148:151], v152 offset:2048
	ds_read_b128 v[144:147], v152 offset:1024
	ds_read_b128 v[152:155], v152 offset:3072
	s_add_u32 s14, s20, 0x40000
	s_addc_u32 s15, s21, 0
	s_mov_b32 m0, s28
	v_lshl_add_u64 v[188:189], s[14:15], 0, v[32:33]
	ds_read_b128 v[156:159], v139 offset:32768
	ds_read_b128 v[164:167], v139 offset:34816
	ds_read_b128 v[172:175], v139 offset:36864
	ds_read_b128 v[180:183], v139 offset:38912
	ds_read_b128 v[160:163], v139 offset:33792
	ds_read_b128 v[168:171], v139 offset:35840
	ds_read_b128 v[176:179], v139 offset:37888
	ds_read_b128 v[184:187], v139 offset:39936
	global_load_lds_dwordx4 v[188:189], off
	v_lshl_add_u64 v[188:189], s[14:15], 0, v[130:131]
	s_mov_b32 m0, s29
	s_nop 0
	global_load_lds_dwordx4 v[188:189], off
	s_waitcnt lgkmcnt(8)
	s_barrier
	s_waitcnt lgkmcnt(7)
	s_setprio 1
	v_mfma_f32_16x16x32_f16 v[126:129], v[140:143], v[156:159], v[126:129]
	v_mfma_f32_16x16x32_f16 v[122:125], v[148:151], v[156:159], v[122:125]
	s_waitcnt lgkmcnt(6)
	v_mfma_f32_16x16x32_f16 v[110:113], v[140:143], v[164:167], v[110:113]
	v_mfma_f32_16x16x32_f16 v[106:109], v[148:151], v[164:167], v[106:109]
	s_waitcnt lgkmcnt(5)
	v_mfma_f32_16x16x32_f16 v[94:97], v[140:143], v[172:175], v[94:97]
	v_mfma_f32_16x16x32_f16 v[90:93], v[148:151], v[172:175], v[90:93]
	s_waitcnt lgkmcnt(4)
	v_mfma_f32_16x16x32_f16 v[78:81], v[140:143], v[180:183], v[78:81]
	v_mfma_f32_16x16x32_f16 v[74:77], v[148:151], v[180:183], v[74:77]
	s_waitcnt lgkmcnt(3)
	v_mfma_f32_16x16x32_f16 v[126:129], v[144:147], v[160:163], v[126:129]
	v_mfma_f32_16x16x32_f16 v[122:125], v[152:155], v[160:163], v[122:125]
	s_waitcnt lgkmcnt(2)
	v_mfma_f32_16x16x32_f16 v[110:113], v[144:147], v[168:171], v[110:113]
	v_mfma_f32_16x16x32_f16 v[106:109], v[152:155], v[168:171], v[106:109]
	s_waitcnt lgkmcnt(1)
	v_mfma_f32_16x16x32_f16 v[94:97], v[144:147], v[176:179], v[94:97]
	v_mfma_f32_16x16x32_f16 v[90:93], v[152:155], v[176:179], v[90:93]
	s_waitcnt lgkmcnt(0)
	v_mfma_f32_16x16x32_f16 v[78:81], v[144:147], v[184:187], v[78:81]
	v_mfma_f32_16x16x32_f16 v[74:77], v[152:155], v[184:187], v[74:77]
	s_setprio 0
	s_barrier
	s_add_i32 s20, 0, 0x1c000
	s_add_i32 s14, s39, s26
	v_add_u32_e32 v200, s20, v137
	v_lshl_add_u64 v[204:205], v[204:205], 0, s[84:85]
	s_mov_b32 m0, s14
	ds_read_b128 v[188:191], v200
	ds_read_b128 v[196:199], v200 offset:2048
	ds_read_b128 v[192:195], v200 offset:1024
	ds_read_b128 v[200:203], v200 offset:3072
	global_load_lds_dwordx4 v[204:205], off
	v_lshl_add_u64 v[204:205], v[206:207], 0, s[84:85]
	s_add_i32 m0, s14, 0x2000
	s_nop 0
	global_load_lds_dwordx4 v[204:205], off
	s_barrier
	s_waitcnt lgkmcnt(2)
	s_setprio 1
	v_mfma_f32_16x16x32_f16 v[118:121], v[188:191], v[156:159], v[118:121]
	v_mfma_f32_16x16x32_f16 v[114:117], v[196:199], v[156:159], v[114:117]
	v_mfma_f32_16x16x32_f16 v[102:105], v[188:191], v[164:167], v[102:105]
	v_mfma_f32_16x16x32_f16 v[98:101], v[196:199], v[164:167], v[98:101]
	v_mfma_f32_16x16x32_f16 v[86:89], v[188:191], v[172:175], v[86:89]
	v_mfma_f32_16x16x32_f16 v[82:85], v[196:199], v[172:175], v[82:85]
	v_mfma_f32_16x16x32_f16 v[70:73], v[188:191], v[180:183], v[70:73]
	v_mfma_f32_16x16x32_f16 v[66:69], v[196:199], v[180:183], v[66:69]
	s_waitcnt lgkmcnt(0)
	v_mfma_f32_16x16x32_f16 v[118:121], v[192:195], v[160:163], v[118:121]
	v_mfma_f32_16x16x32_f16 v[114:117], v[200:203], v[160:163], v[114:117]
	v_mfma_f32_16x16x32_f16 v[102:105], v[192:195], v[168:171], v[102:105]
	v_mfma_f32_16x16x32_f16 v[98:101], v[200:203], v[168:171], v[98:101]
	v_mfma_f32_16x16x32_f16 v[86:89], v[192:195], v[176:179], v[86:89]
	v_mfma_f32_16x16x32_f16 v[82:85], v[200:203], v[176:179], v[82:85]
	v_mfma_f32_16x16x32_f16 v[70:73], v[192:195], v[184:187], v[70:73]
	v_mfma_f32_16x16x32_f16 v[66:69], v[200:203], v[184:187], v[66:69]
	s_setprio 0
	s_mov_b32 m0, s30
	v_lshl_add_u64 v[204:205], v[208:209], 0, s[84:85]
	s_barrier
	ds_read_b128 v[156:159], v139 offset:49152
	ds_read_b128 v[164:167], v139 offset:51200
	ds_read_b128 v[172:175], v139 offset:53248
	ds_read_b128 v[180:183], v139 offset:55296
	ds_read_b128 v[160:163], v139 offset:50176
	ds_read_b128 v[168:171], v139 offset:52224
	ds_read_b128 v[176:179], v139 offset:54272
	ds_read_b128 v[184:187], v139 offset:56320
	global_load_lds_dwordx4 v[204:205], off
	v_lshl_add_u64 v[204:205], v[210:211], 0, s[84:85]
	s_mov_b32 m0, s31
	s_nop 0
	global_load_lds_dwordx4 v[204:205], off
	s_barrier
	s_waitcnt lgkmcnt(7)
	s_setprio 1
	v_mfma_f32_16x16x32_f16 v[62:65], v[140:143], v[156:159], v[62:65]
	v_mfma_f32_16x16x32_f16 v[58:61], v[148:151], v[156:159], v[58:61]
	s_waitcnt lgkmcnt(6)
	v_mfma_f32_16x16x32_f16 v[46:49], v[140:143], v[164:167], v[46:49]
	v_mfma_f32_16x16x32_f16 v[42:45], v[148:151], v[164:167], v[42:45]
	s_waitcnt lgkmcnt(5)
	v_mfma_f32_16x16x32_f16 v[28:31], v[140:143], v[172:175], v[28:31]
	v_mfma_f32_16x16x32_f16 v[24:27], v[148:151], v[172:175], v[24:27]
	s_waitcnt lgkmcnt(4)
	v_mfma_f32_16x16x32_f16 v[12:15], v[140:143], v[180:183], v[12:15]
	v_mfma_f32_16x16x32_f16 v[8:11], v[148:151], v[180:183], v[8:11]
	s_waitcnt lgkmcnt(3)
	v_mfma_f32_16x16x32_f16 v[62:65], v[144:147], v[160:163], v[62:65]
	v_mfma_f32_16x16x32_f16 v[58:61], v[152:155], v[160:163], v[58:61]
	s_waitcnt lgkmcnt(2)
	v_mfma_f32_16x16x32_f16 v[46:49], v[144:147], v[168:171], v[46:49]
	v_mfma_f32_16x16x32_f16 v[42:45], v[152:155], v[168:171], v[42:45]
	s_waitcnt lgkmcnt(1)
	v_mfma_f32_16x16x32_f16 v[28:31], v[144:147], v[176:179], v[28:31]
	v_mfma_f32_16x16x32_f16 v[24:27], v[152:155], v[176:179], v[24:27]
	s_waitcnt lgkmcnt(0)
	v_mfma_f32_16x16x32_f16 v[12:15], v[144:147], v[184:187], v[12:15]
	v_mfma_f32_16x16x32_f16 v[8:11], v[152:155], v[184:187], v[8:11]
	s_setprio 0
	s_barrier
	s_add_u32 s14, s18, 0x40080
	s_addc_u32 s15, s19, 0
	s_add_i32 s18, s20, s26
	v_lshl_add_u64 v[140:141], s[14:15], 0, v[32:33]
	s_mov_b32 m0, s18
	s_nop 0
	global_load_lds_dwordx4 v[140:141], off
	v_lshl_add_u64 v[140:141], s[14:15], 0, v[130:131]
	s_add_i32 m0, s18, 0x2000
	s_nop 0
	global_load_lds_dwordx4 v[140:141], off
	s_waitcnt vmcnt(6)
	s_barrier
	s_setprio 1
	v_mfma_f32_16x16x32_f16 v[54:57], v[188:191], v[156:159], v[54:57]
	v_mfma_f32_16x16x32_f16 v[50:53], v[196:199], v[156:159], v[50:53]
	v_mfma_f32_16x16x32_f16 v[38:41], v[188:191], v[164:167], v[38:41]
	v_mfma_f32_16x16x32_f16 v[34:37], v[196:199], v[164:167], v[34:37]
	v_mfma_f32_16x16x32_f16 v[20:23], v[188:191], v[172:175], v[20:23]
	v_mfma_f32_16x16x32_f16 v[16:19], v[196:199], v[172:175], v[16:19]
	v_mfma_f32_16x16x32_f16 v[4:7], v[188:191], v[180:183], v[4:7]
	v_mfma_f32_16x16x32_f16 v[0:3], v[196:199], v[180:183], v[0:3]
	v_mfma_f32_16x16x32_f16 v[54:57], v[192:195], v[160:163], v[54:57]
	v_mfma_f32_16x16x32_f16 v[50:53], v[200:203], v[160:163], v[50:53]
	v_mfma_f32_16x16x32_f16 v[38:41], v[192:195], v[168:171], v[38:41]
	v_mfma_f32_16x16x32_f16 v[34:37], v[200:203], v[168:171], v[34:37]
	v_mfma_f32_16x16x32_f16 v[20:23], v[192:195], v[176:179], v[20:23]
	v_mfma_f32_16x16x32_f16 v[16:19], v[200:203], v[176:179], v[16:19]
	v_mfma_f32_16x16x32_f16 v[4:7], v[192:195], v[184:187], v[4:7]
	v_mfma_f32_16x16x32_f16 v[0:3], v[200:203], v[184:187], v[0:3]
	s_setprio 0
	s_add_i32 s38, s38, 2
	s_add_u32 s3, s3, 0x100
	s_addc_u32 s37, s37, 0
	s_cmp_gt_u32 s38, 13
	s_mov_b64 s[14:15], s[16:17]
	s_barrier
	s_cbranch_scc0 .LBB0_1276
	v_mul_f32_e32 v144, 0xbfb8aa3b, v127
	v_mul_f32_e32 v141, 0xbfb8aa3b, v126
	v_exp_f32_e32 v145, v144
	v_mul_f32_e32 v144, 0xbfb8aa3b, v128
	v_exp_f32_e32 v141, v141
	v_exp_f32_e32 v146, v144
	v_mul_f32_e32 v144, 0xbfb8aa3b, v129
	v_exp_f32_e32 v147, v144
	v_mul_f32_e32 v144, 0xbfb8aa3b, v122
	v_exp_f32_e32 v148, v144
	v_mul_f32_e32 v144, 0xbfb8aa3b, v123
	v_exp_f32_e32 v149, v144
	v_mul_f32_e32 v144, 0xbfb8aa3b, v124
	v_exp_f32_e32 v150, v144
	v_mul_f32_e32 v144, 0xbfb8aa3b, v125
	v_add_f32_e32 v141, 1.0, v141
	v_exp_f32_e32 v151, v144
	v_rcp_f32_e32 v144, v141
	v_add_f32_e32 v141, 1.0, v145
	v_rcp_f32_e32 v145, v141
	v_add_f32_e32 v141, 1.0, v146
	v_rcp_f32_e32 v146, v141
	v_add_f32_e32 v141, 1.0, v147
	v_rcp_f32_e32 v147, v141
	v_add_f32_e32 v141, 1.0, v148
	v_rcp_f32_e32 v148, v141
	v_add_f32_e32 v141, 1.0, v149
	v_rcp_f32_e32 v149, v141
	v_add_f32_e32 v141, 1.0, v150
	v_rcp_f32_e32 v150, v141
	v_add_f32_e32 v141, 1.0, v151
	v_pk_mul_f32 v[126:127], v[126:127], v[144:145]
	v_rcp_f32_e32 v151, v141
	v_pk_mul_f32 v[118:119], v[126:127], v[118:119]
	v_pk_mul_f32 v[126:127], v[128:129], v[146:147]
	v_cvt_pk_f16_f32 v118, v118, v119
	v_pk_mul_f32 v[120:121], v[126:127], v[120:121]
	v_lshl_or_b32 v142, s36, 7, v138
	v_cvt_pk_f16_f32 v119, v120, v121
	v_pk_mul_f32 v[120:121], v[122:123], v[148:149]
	v_lshl_add_u32 v140, s8, 8, v136
	v_pk_mul_f32 v[114:115], v[120:121], v[114:115]
	v_ashrrev_i32_e32 v143, 31, v142
	v_cvt_pk_f16_f32 v120, v114, v115
	v_pk_mul_f32 v[114:115], v[124:125], v[150:151]
	s_movk_i32 s3, 0x1600
	v_pk_mul_f32 v[114:115], v[114:115], v[116:117]
	v_lshlrev_b64 v[116:117], 1, v[142:143]
	v_cvt_pk_f16_f32 v121, v114, v115
	v_mov_b64_e32 v[114:115], s[92:93]
	v_mad_i64_i32 v[122:123], s[10:11], v140, s3, v[114:115]
	v_lshl_add_u64 v[122:123], v[122:123], 0, v[116:117]
	global_store_dwordx4 v[122:123], v[118:121], off
	v_mul_f32_e32 v122, 0xbfb8aa3b, v106
	v_mul_f32_e32 v123, 0xbfb8aa3b, v107
	v_mul_f32_e32 v118, 0xbfb8aa3b, v110
	v_mul_f32_e32 v119, 0xbfb8aa3b, v111
	v_exp_f32_e32 v118, v118
	v_exp_f32_e32 v119, v119
	v_mul_f32_e32 v120, 0xbfb8aa3b, v112
	v_mul_f32_e32 v121, 0xbfb8aa3b, v113
	v_exp_f32_e32 v120, v120
	v_exp_f32_e32 v121, v121
	v_exp_f32_e32 v122, v122
	v_exp_f32_e32 v123, v123
	v_mul_f32_e32 v124, 0xbfb8aa3b, v108
	v_mul_f32_e32 v125, 0xbfb8aa3b, v109
	v_add_f32_e32 v118, 1.0, v118
	v_add_f32_e32 v119, 1.0, v119
	v_exp_f32_e32 v124, v124
	v_exp_f32_e32 v125, v125
	v_rcp_f32_e32 v118, v118
	v_rcp_f32_e32 v119, v119
	v_add_f32_e32 v120, 1.0, v120
	v_add_f32_e32 v121, 1.0, v121
	v_rcp_f32_e32 v120, v120
	v_rcp_f32_e32 v121, v121
	v_add_f32_e32 v122, 1.0, v122
	v_add_f32_e32 v123, 1.0, v123
	v_rcp_f32_e32 v122, v122
	v_rcp_f32_e32 v123, v123
	v_add_f32_e32 v124, 1.0, v124
	v_add_f32_e32 v125, 1.0, v125
	v_pk_mul_f32 v[110:111], v[110:111], v[118:119]
	v_rcp_f32_e32 v124, v124
	v_rcp_f32_e32 v125, v125
	v_pk_mul_f32 v[102:103], v[110:111], v[102:103]
	v_pk_mul_f32 v[110:111], v[112:113], v[120:121]
	v_cvt_pk_f16_f32 v102, v102, v103
	v_pk_mul_f32 v[104:105], v[110:111], v[104:105]
	s_and_b64 vcc, exec, s[0:1]
	v_cvt_pk_f16_f32 v103, v104, v105
	v_pk_mul_f32 v[104:105], v[106:107], v[122:123]
	s_mov_b32 s36, s35
	v_pk_mul_f32 v[98:99], v[104:105], v[98:99]
	s_mov_b32 s8, s2
	v_cvt_pk_f16_f32 v104, v98, v99
	v_pk_mul_f32 v[98:99], v[108:109], v[124:125]
	s_mov_b64 s[16:17], s[6:7]
	v_pk_mul_f32 v[98:99], v[98:99], v[100:101]
	v_mul_f32_e32 v100, 0xbfb8aa3b, v96
	v_cvt_pk_f16_f32 v105, v98, v99
	v_or_b32_e32 v98, 16, v140
	v_mad_i64_i32 v[98:99], s[10:11], v98, s3, v[114:115]
	v_lshl_add_u64 v[98:99], v[98:99], 0, v[116:117]
	global_store_dwordx4 v[98:99], v[102:105], off
	v_mul_f32_e32 v98, 0xbfb8aa3b, v94
	v_mul_f32_e32 v99, 0xbfb8aa3b, v95
	v_exp_f32_e32 v98, v98
	v_exp_f32_e32 v99, v99
	v_mul_f32_e32 v101, 0xbfb8aa3b, v97
	v_exp_f32_e32 v100, v100
	v_exp_f32_e32 v101, v101
	v_mul_f32_e32 v102, 0xbfb8aa3b, v90
	v_mul_f32_e32 v103, 0xbfb8aa3b, v91
	v_exp_f32_e32 v102, v102
	v_exp_f32_e32 v103, v103
	v_mul_f32_e32 v104, 0xbfb8aa3b, v92
	v_mul_f32_e32 v105, 0xbfb8aa3b, v93
	v_add_f32_e32 v98, 1.0, v98
	v_add_f32_e32 v99, 1.0, v99
	v_exp_f32_e32 v104, v104
	v_exp_f32_e32 v105, v105
	v_rcp_f32_e32 v98, v98
	v_rcp_f32_e32 v99, v99
	v_add_f32_e32 v100, 1.0, v100
	v_add_f32_e32 v101, 1.0, v101
	v_rcp_f32_e32 v100, v100
	v_rcp_f32_e32 v101, v101
	v_add_f32_e32 v102, 1.0, v102
	v_add_f32_e32 v103, 1.0, v103
	v_rcp_f32_e32 v102, v102
	v_rcp_f32_e32 v103, v103
	v_add_f32_e32 v104, 1.0, v104
	v_add_f32_e32 v105, 1.0, v105
	v_pk_mul_f32 v[94:95], v[94:95], v[98:99]
	v_rcp_f32_e32 v104, v104
	v_rcp_f32_e32 v105, v105
	v_pk_mul_f32 v[86:87], v[94:95], v[86:87]
	v_pk_mul_f32 v[94:95], v[96:97], v[100:101]
	v_cvt_pk_f16_f32 v86, v86, v87
	v_pk_mul_f32 v[88:89], v[94:95], v[88:89]
	s_mov_b64 s[14:15], s[4:5]
	v_cvt_pk_f16_f32 v87, v88, v89
	v_pk_mul_f32 v[88:89], v[90:91], v[102:103]
	s_nop 0
	v_pk_mul_f32 v[82:83], v[88:89], v[82:83]
	s_nop 0
	v_cvt_pk_f16_f32 v88, v82, v83
	v_pk_mul_f32 v[82:83], v[92:93], v[104:105]
	s_nop 0
	v_pk_mul_f32 v[82:83], v[82:83], v[84:85]
	v_mul_f32_e32 v84, 0xbfb8aa3b, v80
	v_cvt_pk_f16_f32 v89, v82, v83
	v_or_b32_e32 v82, 32, v140
	v_mad_i64_i32 v[82:83], s[10:11], v82, s3, v[114:115]
	v_lshl_add_u64 v[82:83], v[82:83], 0, v[116:117]
	global_store_dwordx4 v[82:83], v[86:89], off
	v_mul_f32_e32 v82, 0xbfb8aa3b, v78
	v_mul_f32_e32 v83, 0xbfb8aa3b, v79
	v_exp_f32_e32 v82, v82
	v_exp_f32_e32 v83, v83
	v_mul_f32_e32 v85, 0xbfb8aa3b, v81
	v_exp_f32_e32 v84, v84
	v_exp_f32_e32 v85, v85
	v_mul_f32_e32 v86, 0xbfb8aa3b, v74
	v_mul_f32_e32 v87, 0xbfb8aa3b, v75
	v_exp_f32_e32 v86, v86
	v_exp_f32_e32 v87, v87
	v_mul_f32_e32 v88, 0xbfb8aa3b, v76
	v_mul_f32_e32 v89, 0xbfb8aa3b, v77
	v_add_f32_e32 v82, 1.0, v82
	v_add_f32_e32 v83, 1.0, v83
	v_exp_f32_e32 v88, v88
	v_exp_f32_e32 v89, v89
	v_rcp_f32_e32 v82, v82
	v_rcp_f32_e32 v83, v83
	v_add_f32_e32 v84, 1.0, v84
	v_add_f32_e32 v85, 1.0, v85
	v_rcp_f32_e32 v84, v84
	v_rcp_f32_e32 v85, v85
	v_add_f32_e32 v86, 1.0, v86
	v_add_f32_e32 v87, 1.0, v87
	v_rcp_f32_e32 v86, v86
	v_rcp_f32_e32 v87, v87
	v_add_f32_e32 v88, 1.0, v88
	v_add_f32_e32 v89, 1.0, v89
	v_pk_mul_f32 v[78:79], v[78:79], v[82:83]
	v_rcp_f32_e32 v88, v88
	v_rcp_f32_e32 v89, v89
	v_pk_mul_f32 v[70:71], v[78:79], v[70:71]
	v_pk_mul_f32 v[78:79], v[80:81], v[84:85]
	v_cvt_pk_f16_f32 v70, v70, v71
	v_pk_mul_f32 v[72:73], v[78:79], v[72:73]
	s_nop 0
	v_cvt_pk_f16_f32 v71, v72, v73
	v_pk_mul_f32 v[72:73], v[74:75], v[86:87]
	v_add_u32_e32 v74, 0x80, v140
	v_pk_mul_f32 v[66:67], v[72:73], v[66:67]
	s_nop 0
	v_cvt_pk_f16_f32 v72, v66, v67
	v_pk_mul_f32 v[66:67], v[76:77], v[88:89]
	s_nop 0
	v_pk_mul_f32 v[66:67], v[66:67], v[68:69]
	v_mul_f32_e32 v68, 0xbfb8aa3b, v64
	v_cvt_pk_f16_f32 v73, v66, v67
	v_or_b32_e32 v66, 48, v140
	v_mad_i64_i32 v[66:67], s[10:11], v66, s3, v[114:115]
	v_lshl_add_u64 v[66:67], v[66:67], 0, v[116:117]
	global_store_dwordx4 v[66:67], v[70:73], off
	v_mul_f32_e32 v66, 0xbfb8aa3b, v62
	v_mul_f32_e32 v67, 0xbfb8aa3b, v63
	v_exp_f32_e32 v66, v66
	v_exp_f32_e32 v67, v67
	v_mul_f32_e32 v69, 0xbfb8aa3b, v65
	v_exp_f32_e32 v68, v68
	v_exp_f32_e32 v69, v69
	v_mul_f32_e32 v70, 0xbfb8aa3b, v58
	v_mul_f32_e32 v71, 0xbfb8aa3b, v59
	v_exp_f32_e32 v70, v70
	v_exp_f32_e32 v71, v71
	v_mul_f32_e32 v72, 0xbfb8aa3b, v60
	v_mul_f32_e32 v73, 0xbfb8aa3b, v61
	v_add_f32_e32 v66, 1.0, v66
	v_add_f32_e32 v67, 1.0, v67
	v_exp_f32_e32 v72, v72
	v_exp_f32_e32 v73, v73
	v_rcp_f32_e32 v66, v66
	v_rcp_f32_e32 v67, v67
	v_add_f32_e32 v68, 1.0, v68
	v_add_f32_e32 v69, 1.0, v69
	v_rcp_f32_e32 v68, v68
	v_rcp_f32_e32 v69, v69
	v_add_f32_e32 v70, 1.0, v70
	v_add_f32_e32 v71, 1.0, v71
	v_rcp_f32_e32 v70, v70
	v_rcp_f32_e32 v71, v71
	v_add_f32_e32 v72, 1.0, v72
	v_add_f32_e32 v73, 1.0, v73
	v_pk_mul_f32 v[62:63], v[62:63], v[66:67]
	v_rcp_f32_e32 v72, v72
	v_rcp_f32_e32 v73, v73
	v_pk_mul_f32 v[54:55], v[62:63], v[54:55]
	v_pk_mul_f32 v[62:63], v[64:65], v[68:69]
	v_cvt_pk_f16_f32 v54, v54, v55
	v_pk_mul_f32 v[56:57], v[62:63], v[56:57]
	s_nop 0
	v_cvt_pk_f16_f32 v55, v56, v57
	v_pk_mul_f32 v[56:57], v[58:59], v[70:71]
	s_nop 0
	v_pk_mul_f32 v[50:51], v[56:57], v[50:51]
	s_nop 0
	v_cvt_pk_f16_f32 v56, v50, v51
	v_pk_mul_f32 v[50:51], v[60:61], v[72:73]
	s_nop 0
	v_pk_mul_f32 v[50:51], v[50:51], v[52:53]
	v_mul_f32_e32 v52, 0xbfb8aa3b, v48
	v_cvt_pk_f16_f32 v57, v50, v51
	v_mad_i64_i32 v[50:51], s[10:11], v74, s3, v[114:115]
	v_lshl_add_u64 v[50:51], v[50:51], 0, v[116:117]
	global_store_dwordx4 v[50:51], v[54:57], off
	v_mul_f32_e32 v50, 0xbfb8aa3b, v46
	v_mul_f32_e32 v51, 0xbfb8aa3b, v47
	v_exp_f32_e32 v50, v50
	v_exp_f32_e32 v51, v51
	v_mul_f32_e32 v53, 0xbfb8aa3b, v49
	v_exp_f32_e32 v52, v52
	v_exp_f32_e32 v53, v53
	v_mul_f32_e32 v54, 0xbfb8aa3b, v42
	v_mul_f32_e32 v55, 0xbfb8aa3b, v43
	v_exp_f32_e32 v54, v54
	v_exp_f32_e32 v55, v55
	v_mul_f32_e32 v56, 0xbfb8aa3b, v44
	v_mul_f32_e32 v57, 0xbfb8aa3b, v45
	v_add_f32_e32 v50, 1.0, v50
	v_add_f32_e32 v51, 1.0, v51
	v_exp_f32_e32 v56, v56
	v_exp_f32_e32 v57, v57
	v_rcp_f32_e32 v50, v50
	v_rcp_f32_e32 v51, v51
	v_add_f32_e32 v52, 1.0, v52
	v_add_f32_e32 v53, 1.0, v53
	v_rcp_f32_e32 v52, v52
	v_rcp_f32_e32 v53, v53
	v_add_f32_e32 v54, 1.0, v54
	v_add_f32_e32 v55, 1.0, v55
	v_rcp_f32_e32 v54, v54
	v_rcp_f32_e32 v55, v55
	v_add_f32_e32 v56, 1.0, v56
	v_add_f32_e32 v57, 1.0, v57
	v_pk_mul_f32 v[46:47], v[46:47], v[50:51]
	v_rcp_f32_e32 v56, v56
	v_rcp_f32_e32 v57, v57
	v_pk_mul_f32 v[38:39], v[46:47], v[38:39]
	v_pk_mul_f32 v[46:47], v[48:49], v[52:53]
	v_cvt_pk_f16_f32 v38, v38, v39
	v_pk_mul_f32 v[40:41], v[46:47], v[40:41]
	s_nop 0
	v_cvt_pk_f16_f32 v39, v40, v41
	v_pk_mul_f32 v[40:41], v[42:43], v[54:55]
	s_nop 0
	v_pk_mul_f32 v[34:35], v[40:41], v[34:35]
	s_nop 0
	v_cvt_pk_f16_f32 v40, v34, v35
	v_pk_mul_f32 v[34:35], v[44:45], v[56:57]
	s_nop 0
	v_pk_mul_f32 v[34:35], v[34:35], v[36:37]
	v_mul_f32_e32 v36, 0xbfb8aa3b, v30
	v_cvt_pk_f16_f32 v41, v34, v35
	v_add_u32_e32 v34, 0x90, v140
	v_mad_i64_i32 v[34:35], s[10:11], v34, s3, v[114:115]
	v_lshl_add_u64 v[34:35], v[34:35], 0, v[116:117]
	global_store_dwordx4 v[34:35], v[38:41], off
	v_mul_f32_e32 v34, 0xbfb8aa3b, v28
	v_mul_f32_e32 v35, 0xbfb8aa3b, v29
	v_exp_f32_e32 v34, v34
	v_exp_f32_e32 v35, v35
	v_mul_f32_e32 v37, 0xbfb8aa3b, v31
	v_exp_f32_e32 v36, v36
	v_exp_f32_e32 v37, v37
	v_mul_f32_e32 v38, 0xbfb8aa3b, v24
	v_mul_f32_e32 v39, 0xbfb8aa3b, v25
	v_exp_f32_e32 v38, v38
	v_exp_f32_e32 v39, v39
	v_mul_f32_e32 v40, 0xbfb8aa3b, v26
	v_mul_f32_e32 v41, 0xbfb8aa3b, v27
	v_add_f32_e32 v34, 1.0, v34
	v_add_f32_e32 v35, 1.0, v35
	v_exp_f32_e32 v40, v40
	v_exp_f32_e32 v41, v41
	v_rcp_f32_e32 v34, v34
	v_rcp_f32_e32 v35, v35
	v_add_f32_e32 v36, 1.0, v36
	v_add_f32_e32 v37, 1.0, v37
	v_rcp_f32_e32 v36, v36
	v_rcp_f32_e32 v37, v37
	v_add_f32_e32 v38, 1.0, v38
	v_add_f32_e32 v39, 1.0, v39
	v_rcp_f32_e32 v38, v38
	v_rcp_f32_e32 v39, v39
	v_add_f32_e32 v40, 1.0, v40
	v_add_f32_e32 v41, 1.0, v41
	v_pk_mul_f32 v[28:29], v[28:29], v[34:35]
	v_rcp_f32_e32 v40, v40
	v_rcp_f32_e32 v41, v41
	v_pk_mul_f32 v[20:21], v[28:29], v[20:21]
	v_pk_mul_f32 v[28:29], v[30:31], v[36:37]
	v_cvt_pk_f16_f32 v20, v20, v21
	v_pk_mul_f32 v[22:23], v[28:29], v[22:23]
	s_nop 0
	v_cvt_pk_f16_f32 v21, v22, v23
	v_pk_mul_f32 v[22:23], v[24:25], v[38:39]
	s_nop 0
	v_pk_mul_f32 v[16:17], v[22:23], v[16:17]
	s_nop 0
	v_cvt_pk_f16_f32 v22, v16, v17
	v_pk_mul_f32 v[16:17], v[26:27], v[40:41]
	s_nop 0
	v_pk_mul_f32 v[16:17], v[16:17], v[18:19]
	v_mul_f32_e32 v18, 0xbfb8aa3b, v14
	v_cvt_pk_f16_f32 v23, v16, v17
	v_add_u32_e32 v16, 0xa0, v140
	v_mad_i64_i32 v[16:17], s[10:11], v16, s3, v[114:115]
	v_lshl_add_u64 v[16:17], v[16:17], 0, v[116:117]
	global_store_dwordx4 v[16:17], v[20:23], off
	v_mul_f32_e32 v16, 0xbfb8aa3b, v12
	v_mul_f32_e32 v17, 0xbfb8aa3b, v13
	v_exp_f32_e32 v16, v16
	v_exp_f32_e32 v17, v17
	v_mul_f32_e32 v19, 0xbfb8aa3b, v15
	v_exp_f32_e32 v18, v18
	v_exp_f32_e32 v19, v19
	v_mul_f32_e32 v20, 0xbfb8aa3b, v8
	v_mul_f32_e32 v21, 0xbfb8aa3b, v9
	v_exp_f32_e32 v20, v20
	v_exp_f32_e32 v21, v21
	v_mul_f32_e32 v22, 0xbfb8aa3b, v10
	v_mul_f32_e32 v23, 0xbfb8aa3b, v11
	v_add_f32_e32 v16, 1.0, v16
	v_add_f32_e32 v17, 1.0, v17
	v_exp_f32_e32 v22, v22
	v_exp_f32_e32 v23, v23
	v_rcp_f32_e32 v16, v16
	v_rcp_f32_e32 v17, v17
	v_add_f32_e32 v18, 1.0, v18
	v_add_f32_e32 v19, 1.0, v19
	v_rcp_f32_e32 v18, v18
	v_rcp_f32_e32 v19, v19
	v_add_f32_e32 v20, 1.0, v20
	v_add_f32_e32 v21, 1.0, v21
	v_rcp_f32_e32 v20, v20
	v_rcp_f32_e32 v21, v21
	v_add_f32_e32 v22, 1.0, v22
	v_add_f32_e32 v23, 1.0, v23
	v_pk_mul_f32 v[12:13], v[12:13], v[16:17]
	v_rcp_f32_e32 v22, v22
	v_rcp_f32_e32 v23, v23
	v_pk_mul_f32 v[4:5], v[12:13], v[4:5]
	v_pk_mul_f32 v[12:13], v[14:15], v[18:19]
	v_cvt_pk_f16_f32 v4, v4, v5
	v_pk_mul_f32 v[6:7], v[12:13], v[6:7]
	s_nop 0
	v_cvt_pk_f16_f32 v5, v6, v7
	v_pk_mul_f32 v[6:7], v[8:9], v[20:21]
	s_nop 0
	v_pk_mul_f32 v[0:1], v[6:7], v[0:1]
	s_nop 0
	v_cvt_pk_f16_f32 v6, v0, v1
	v_pk_mul_f32 v[0:1], v[10:11], v[22:23]
	s_nop 0
	v_pk_mul_f32 v[0:1], v[0:1], v[2:3]
	s_nop 0
	v_cvt_pk_f16_f32 v7, v0, v1
	v_add_u32_e32 v0, 0xb0, v140
	v_mad_i64_i32 v[0:1], s[10:11], v0, s3, v[114:115]
	v_lshl_add_u64 v[0:1], v[0:1], 0, v[116:117]
	global_store_dwordx4 v[0:1], v[4:7], off
	s_cmp_lg_u32 s34, 1
	s_cbranch_scc1 .Lups_skip
	s_and_b32 s0, s91, 63
	s_cmp_gt_u32 s0, 5
	s_cbranch_scc1 .Lups_skip
	s_cmp_gt_u32 s91, 196
	s_cbranch_scc1 .Lups_skip
	s_waitcnt vmcnt(0)
	s_barrier
	v_readlane_b32 s0, v251, 36
	s_cmp_lg_u32 s0, 0
	s_cbranch_scc1 .Lups_skip
	buffer_wbl2 sc1
	s_waitcnt vmcnt(0)
	v_readlane_b32 s2, v255, 45
	v_readlane_b32 s3, v254, 25
	s_lshl_b32 s2, s2, 1
	s_cmp_eq_u32 s3, 0
	s_cselect_b32 s3, 1, 0
	s_add_i32 s2, s2, s3
	s_lshl_b32 s2, s2, 2
	s_add_i32 s2, s2, 14016
	v_readlane_b32 s0, v251, 32
	v_readlane_b32 s1, v251, 33
	s_add_u32 s0, s0, s2
	s_addc_u32 s1, s1, 0
	s_mov_b64 s[2:3], exec
	s_mov_b64 exec, 1
	global_atomic_add v33, v248, s[0:1]
	s_mov_b64 exec, s[2:3]

.LBB0_1365:
	s_add_i32 s46, s14, 2
	s_add_u32 s12, s10, 0x100
	s_addc_u32 s13, s11, 0
	s_add_i32 s47, 0, 0x10000
	v_add_u32_e32 v134, s47, v230
	ds_read_b128 v[106:109], v134
	ds_read_b128 v[114:117], v134 offset:2048
	ds_read_b128 v[110:113], v134 offset:1024
	ds_read_b128 v[134:137], v134 offset:3072
	s_cmp_eq_u32 s43, s14
	s_cselect_b32 s14, s8, s44
	s_cselect_b32 s17, s7, s13
	s_cselect_b32 s16, s6, s12
	s_cselect_b32 s15, s9, s45
	v_lshl_add_u64 v[178:179], s[10:11], 0, v[184:185]
	s_add_i32 m0, s24, 0xc000
	ds_read_b128 v[138:141], v232
	ds_read_b128 v[154:157], v232 offset:2048
	ds_read_b128 v[162:165], v232 offset:4096
	ds_read_b128 v[170:173], v232 offset:6144
	ds_read_b128 v[150:153], v232 offset:1024
	ds_read_b128 v[158:161], v232 offset:3072
	ds_read_b128 v[166:169], v232 offset:5120
	ds_read_b128 v[174:177], v232 offset:7168
	global_load_lds_dwordx4 v[178:179], off
	v_lshl_add_u64 v[178:179], s[10:11], 0, v[186:187]
	s_add_i32 m0, s24, 0xe000
	s_nop 0
	global_load_lds_dwordx4 v[178:179], off
	s_waitcnt lgkmcnt(8)
	s_barrier
	s_waitcnt lgkmcnt(7)
	s_setprio 1
	v_mfma_f32_16x16x32_f16 v[146:149], v[106:109], v[138:141], v[146:149]
	v_mfma_f32_16x16x32_f16 v[142:145], v[114:117], v[138:141], v[142:145]
	s_waitcnt lgkmcnt(6)
	v_mfma_f32_16x16x32_f16 v[130:133], v[106:109], v[154:157], v[130:133]
	v_mfma_f32_16x16x32_f16 v[122:125], v[114:117], v[154:157], v[122:125]
	s_waitcnt lgkmcnt(5)
	v_mfma_f32_16x16x32_f16 v[94:97], v[106:109], v[162:165], v[94:97]
	v_mfma_f32_16x16x32_f16 v[90:93], v[114:117], v[162:165], v[90:93]
	s_waitcnt lgkmcnt(4)
	v_mfma_f32_16x16x32_f16 v[78:81], v[106:109], v[170:173], v[78:81]
	v_mfma_f32_16x16x32_f16 v[74:77], v[114:117], v[170:173], v[74:77]
	s_waitcnt lgkmcnt(3)
	v_mfma_f32_16x16x32_f16 v[146:149], v[110:113], v[150:153], v[146:149]
	v_mfma_f32_16x16x32_f16 v[142:145], v[134:137], v[150:153], v[142:145]
	s_waitcnt lgkmcnt(2)
	v_mfma_f32_16x16x32_f16 v[130:133], v[110:113], v[158:161], v[130:133]
	v_mfma_f32_16x16x32_f16 v[122:125], v[134:137], v[158:161], v[122:125]
	s_waitcnt lgkmcnt(1)
	v_mfma_f32_16x16x32_f16 v[94:97], v[110:113], v[166:169], v[94:97]
	v_mfma_f32_16x16x32_f16 v[90:93], v[134:137], v[166:169], v[90:93]
	s_waitcnt lgkmcnt(0)
	v_mfma_f32_16x16x32_f16 v[78:81], v[110:113], v[174:177], v[78:81]
	v_mfma_f32_16x16x32_f16 v[74:77], v[134:137], v[174:177], v[74:77]
	s_setprio 0
	s_barrier
	s_add_i32 s48, 0, 0x14000
	s_add_i32 s10, s47, s23
	v_add_u32_e32 v196, s48, v230
	v_lshl_add_u64 v[200:201], s[14:15], 0, v[32:33]
	s_mov_b32 m0, s10
	ds_read_b128 v[178:181], v196
	ds_read_b128 v[192:195], v196 offset:2048
	ds_read_b128 v[188:191], v196 offset:1024
	ds_read_b128 v[196:199], v196 offset:3072
	global_load_lds_dwordx4 v[200:201], off
	v_lshl_add_u64 v[202:203], s[14:15], 0, v[182:183]
	s_add_i32 m0, s10, 0x2000
	s_nop 0
	global_load_lds_dwordx4 v[202:203], off
	s_barrier
	s_waitcnt lgkmcnt(2)
	s_setprio 1
	v_mfma_f32_16x16x32_f16 v[126:129], v[178:181], v[138:141], v[126:129]
	v_mfma_f32_16x16x32_f16 v[118:121], v[192:195], v[138:141], v[118:121]
	v_mfma_f32_16x16x32_f16 v[102:105], v[178:181], v[154:157], v[102:105]
	v_mfma_f32_16x16x32_f16 v[98:101], v[192:195], v[154:157], v[98:101]
	v_mfma_f32_16x16x32_f16 v[86:89], v[178:181], v[162:165], v[86:89]
	v_mfma_f32_16x16x32_f16 v[82:85], v[192:195], v[162:165], v[82:85]
	v_mfma_f32_16x16x32_f16 v[70:73], v[178:181], v[170:173], v[70:73]
	v_mfma_f32_16x16x32_f16 v[66:69], v[192:195], v[170:173], v[66:69]
	s_waitcnt lgkmcnt(0)
	v_mfma_f32_16x16x32_f16 v[126:129], v[188:191], v[150:153], v[126:129]
	v_mfma_f32_16x16x32_f16 v[118:121], v[196:199], v[150:153], v[118:121]
	v_mfma_f32_16x16x32_f16 v[102:105], v[188:191], v[158:161], v[102:105]
	v_mfma_f32_16x16x32_f16 v[98:101], v[196:199], v[158:161], v[98:101]
	v_mfma_f32_16x16x32_f16 v[86:89], v[188:191], v[166:169], v[86:89]
	v_mfma_f32_16x16x32_f16 v[82:85], v[196:199], v[166:169], v[82:85]
	v_mfma_f32_16x16x32_f16 v[70:73], v[188:191], v[174:177], v[70:73]
	v_mfma_f32_16x16x32_f16 v[66:69], v[196:199], v[174:177], v[66:69]
	s_setprio 0
	s_mov_b32 m0, s24
	v_lshl_add_u64 v[204:205], s[16:17], 0, v[32:33]
	s_barrier
	ds_read_b128 v[138:141], v232 offset:16384
	ds_read_b128 v[154:157], v232 offset:18432
	ds_read_b128 v[162:165], v232 offset:20480
	ds_read_b128 v[170:173], v232 offset:22528
	ds_read_b128 v[150:153], v232 offset:17408
	ds_read_b128 v[158:161], v232 offset:19456
	ds_read_b128 v[166:169], v232 offset:21504
	ds_read_b128 v[174:177], v232 offset:23552
	global_load_lds_dwordx4 v[204:205], off
	v_lshl_add_u64 v[206:207], s[16:17], 0, v[182:183]
	s_mov_b32 m0, s25
	s_nop 0
	global_load_lds_dwordx4 v[206:207], off
	s_barrier
	s_waitcnt lgkmcnt(7)
	s_setprio 1
	v_mfma_f32_16x16x32_f16 v[62:65], v[106:109], v[138:141], v[62:65]
	v_mfma_f32_16x16x32_f16 v[58:61], v[114:117], v[138:141], v[58:61]
	s_waitcnt lgkmcnt(6)
	v_mfma_f32_16x16x32_f16 v[46:49], v[106:109], v[154:157], v[46:49]
	v_mfma_f32_16x16x32_f16 v[42:45], v[114:117], v[154:157], v[42:45]
	s_waitcnt lgkmcnt(5)
	v_mfma_f32_16x16x32_f16 v[28:31], v[106:109], v[162:165], v[28:31]
	v_mfma_f32_16x16x32_f16 v[24:27], v[114:117], v[162:165], v[24:27]
	s_waitcnt lgkmcnt(4)
	v_mfma_f32_16x16x32_f16 v[12:15], v[106:109], v[170:173], v[12:15]
	v_mfma_f32_16x16x32_f16 v[8:11], v[114:117], v[170:173], v[8:11]
	s_waitcnt lgkmcnt(3)
	v_mfma_f32_16x16x32_f16 v[62:65], v[110:113], v[150:153], v[62:65]
	v_mfma_f32_16x16x32_f16 v[58:61], v[134:137], v[150:153], v[58:61]
	s_waitcnt lgkmcnt(2)
	v_mfma_f32_16x16x32_f16 v[46:49], v[110:113], v[158:161], v[46:49]
	v_mfma_f32_16x16x32_f16 v[42:45], v[134:137], v[158:161], v[42:45]
	s_waitcnt lgkmcnt(1)
	v_mfma_f32_16x16x32_f16 v[28:31], v[110:113], v[166:169], v[28:31]
	v_mfma_f32_16x16x32_f16 v[24:27], v[134:137], v[166:169], v[24:27]
	s_waitcnt lgkmcnt(0)
	v_mfma_f32_16x16x32_f16 v[12:15], v[110:113], v[174:177], v[12:15]
	v_mfma_f32_16x16x32_f16 v[8:11], v[134:137], v[174:177], v[8:11]
	s_setprio 0
	s_barrier
	s_add_u32 s10, s14, 0xb0000
	s_addc_u32 s11, s15, 0
	s_add_i32 s47, s48, s23
	v_lshl_add_u64 v[106:107], s[10:11], 0, v[32:33]
	s_mov_b32 m0, s47
	s_nop 0
	global_load_lds_dwordx4 v[106:107], off
	v_lshl_add_u64 v[106:107], s[10:11], 0, v[182:183]
	s_add_i32 m0, s47, 0x2000
	s_nop 0
	global_load_lds_dwordx4 v[106:107], off
	s_waitcnt vmcnt(6)
	s_barrier
	s_setprio 1
	v_mfma_f32_16x16x32_f16 v[54:57], v[178:181], v[138:141], v[54:57]
	v_mfma_f32_16x16x32_f16 v[50:53], v[192:195], v[138:141], v[50:53]
	v_mfma_f32_16x16x32_f16 v[38:41], v[178:181], v[154:157], v[38:41]
	v_mfma_f32_16x16x32_f16 v[34:37], v[192:195], v[154:157], v[34:37]
	v_mfma_f32_16x16x32_f16 v[20:23], v[178:181], v[162:165], v[20:23]
	v_mfma_f32_16x16x32_f16 v[16:19], v[192:195], v[162:165], v[16:19]
	v_mfma_f32_16x16x32_f16 v[4:7], v[178:181], v[170:173], v[4:7]
	v_mfma_f32_16x16x32_f16 v[0:3], v[192:195], v[170:173], v[0:3]
	v_mfma_f32_16x16x32_f16 v[54:57], v[188:191], v[150:153], v[54:57]
	v_mfma_f32_16x16x32_f16 v[50:53], v[196:199], v[150:153], v[50:53]
	v_mfma_f32_16x16x32_f16 v[38:41], v[188:191], v[158:161], v[38:41]
	v_mfma_f32_16x16x32_f16 v[34:37], v[196:199], v[158:161], v[34:37]
	v_mfma_f32_16x16x32_f16 v[20:23], v[188:191], v[166:169], v[20:23]
	v_mfma_f32_16x16x32_f16 v[16:19], v[196:199], v[166:169], v[16:19]
	v_mfma_f32_16x16x32_f16 v[4:7], v[188:191], v[174:177], v[4:7]
	v_mfma_f32_16x16x32_f16 v[0:3], v[196:199], v[174:177], v[0:3]
	s_setprio 0
	s_add_i32 s47, 0, 0x18000
	v_add_u32_e32 v134, s47, v230
	s_barrier
	ds_read_b128 v[106:109], v134
	ds_read_b128 v[114:117], v134 offset:2048
	ds_read_b128 v[110:113], v134 offset:1024
	ds_read_b128 v[134:137], v134 offset:3072
	s_add_u32 s10, s16, 0xb0000
	s_addc_u32 s11, s17, 0
	s_mov_b32 m0, s26
	v_lshl_add_u64 v[178:179], s[10:11], 0, v[32:33]
	ds_read_b128 v[138:141], v232 offset:32768
	ds_read_b128 v[154:157], v232 offset:34816
	ds_read_b128 v[162:165], v232 offset:36864
	ds_read_b128 v[170:173], v232 offset:38912
	ds_read_b128 v[150:153], v232 offset:33792
	ds_read_b128 v[158:161], v232 offset:35840
	ds_read_b128 v[166:169], v232 offset:37888
	ds_read_b128 v[174:177], v232 offset:39936
	global_load_lds_dwordx4 v[178:179], off
	v_lshl_add_u64 v[178:179], s[10:11], 0, v[182:183]
	s_mov_b32 m0, s27
	s_nop 0
	global_load_lds_dwordx4 v[178:179], off
	s_waitcnt lgkmcnt(8)
	s_barrier
	s_waitcnt lgkmcnt(7)
	s_setprio 1
	v_mfma_f32_16x16x32_f16 v[146:149], v[106:109], v[138:141], v[146:149]
	v_mfma_f32_16x16x32_f16 v[142:145], v[114:117], v[138:141], v[142:145]
	s_waitcnt lgkmcnt(6)
	v_mfma_f32_16x16x32_f16 v[130:133], v[106:109], v[154:157], v[130:133]
	v_mfma_f32_16x16x32_f16 v[122:125], v[114:117], v[154:157], v[122:125]
	s_waitcnt lgkmcnt(5)
	v_mfma_f32_16x16x32_f16 v[94:97], v[106:109], v[162:165], v[94:97]
	v_mfma_f32_16x16x32_f16 v[90:93], v[114:117], v[162:165], v[90:93]
	s_waitcnt lgkmcnt(4)
	v_mfma_f32_16x16x32_f16 v[78:81], v[106:109], v[170:173], v[78:81]
	v_mfma_f32_16x16x32_f16 v[74:77], v[114:117], v[170:173], v[74:77]
	s_waitcnt lgkmcnt(3)
	v_mfma_f32_16x16x32_f16 v[146:149], v[110:113], v[150:153], v[146:149]
	v_mfma_f32_16x16x32_f16 v[142:145], v[134:137], v[150:153], v[142:145]
	s_waitcnt lgkmcnt(2)
	v_mfma_f32_16x16x32_f16 v[130:133], v[110:113], v[158:161], v[130:133]
	v_mfma_f32_16x16x32_f16 v[122:125], v[134:137], v[158:161], v[122:125]
	s_waitcnt lgkmcnt(1)
	v_mfma_f32_16x16x32_f16 v[94:97], v[110:113], v[166:169], v[94:97]
	v_mfma_f32_16x16x32_f16 v[90:93], v[134:137], v[166:169], v[90:93]
	s_waitcnt lgkmcnt(0)
	v_mfma_f32_16x16x32_f16 v[78:81], v[110:113], v[174:177], v[78:81]
	v_mfma_f32_16x16x32_f16 v[74:77], v[134:137], v[174:177], v[74:77]
	s_setprio 0
	s_barrier
	s_add_i32 s16, 0, 0x1c000
	s_add_i32 s10, s47, s23
	v_add_u32_e32 v196, s16, v230
	v_lshl_add_u64 v[200:201], v[200:201], 0, s[84:85]
	s_mov_b32 m0, s10
	ds_read_b128 v[178:181], v196
	ds_read_b128 v[192:195], v196 offset:2048
	ds_read_b128 v[188:191], v196 offset:1024
	ds_read_b128 v[196:199], v196 offset:3072
	global_load_lds_dwordx4 v[200:201], off
	v_lshl_add_u64 v[200:201], v[202:203], 0, s[84:85]
	s_add_i32 m0, s10, 0x2000
	s_nop 0
	global_load_lds_dwordx4 v[200:201], off
	s_barrier
	s_waitcnt lgkmcnt(2)
	s_setprio 1
	v_mfma_f32_16x16x32_f16 v[126:129], v[178:181], v[138:141], v[126:129]
	v_mfma_f32_16x16x32_f16 v[118:121], v[192:195], v[138:141], v[118:121]
	v_mfma_f32_16x16x32_f16 v[102:105], v[178:181], v[154:157], v[102:105]
	v_mfma_f32_16x16x32_f16 v[98:101], v[192:195], v[154:157], v[98:101]
	v_mfma_f32_16x16x32_f16 v[86:89], v[178:181], v[162:165], v[86:89]
	v_mfma_f32_16x16x32_f16 v[82:85], v[192:195], v[162:165], v[82:85]
	v_mfma_f32_16x16x32_f16 v[70:73], v[178:181], v[170:173], v[70:73]
	v_mfma_f32_16x16x32_f16 v[66:69], v[192:195], v[170:173], v[66:69]
	s_waitcnt lgkmcnt(0)
	v_mfma_f32_16x16x32_f16 v[126:129], v[188:191], v[150:153], v[126:129]
	v_mfma_f32_16x16x32_f16 v[118:121], v[196:199], v[150:153], v[118:121]
	v_mfma_f32_16x16x32_f16 v[102:105], v[188:191], v[158:161], v[102:105]
	v_mfma_f32_16x16x32_f16 v[98:101], v[196:199], v[158:161], v[98:101]
	v_mfma_f32_16x16x32_f16 v[86:89], v[188:191], v[166:169], v[86:89]
	v_mfma_f32_16x16x32_f16 v[82:85], v[196:199], v[166:169], v[82:85]
	v_mfma_f32_16x16x32_f16 v[70:73], v[188:191], v[174:177], v[70:73]
	v_mfma_f32_16x16x32_f16 v[66:69], v[196:199], v[174:177], v[66:69]
	s_setprio 0
	s_mov_b32 m0, s29
	v_lshl_add_u64 v[200:201], v[204:205], 0, s[84:85]
	s_barrier
	ds_read_b128 v[138:141], v232 offset:49152
	ds_read_b128 v[154:157], v232 offset:51200
	ds_read_b128 v[162:165], v232 offset:53248
	ds_read_b128 v[170:173], v232 offset:55296
	ds_read_b128 v[150:153], v232 offset:50176
	ds_read_b128 v[158:161], v232 offset:52224
	ds_read_b128 v[166:169], v232 offset:54272
	ds_read_b128 v[174:177], v232 offset:56320
	global_load_lds_dwordx4 v[200:201], off
	v_lshl_add_u64 v[200:201], v[206:207], 0, s[84:85]
	s_mov_b32 m0, s30
	s_nop 0
	global_load_lds_dwordx4 v[200:201], off
	s_barrier
	s_waitcnt lgkmcnt(7)
	s_setprio 1
	v_mfma_f32_16x16x32_f16 v[62:65], v[106:109], v[138:141], v[62:65]
	v_mfma_f32_16x16x32_f16 v[58:61], v[114:117], v[138:141], v[58:61]
	s_waitcnt lgkmcnt(6)
	v_mfma_f32_16x16x32_f16 v[46:49], v[106:109], v[154:157], v[46:49]
	v_mfma_f32_16x16x32_f16 v[42:45], v[114:117], v[154:157], v[42:45]
	s_waitcnt lgkmcnt(5)
	v_mfma_f32_16x16x32_f16 v[28:31], v[106:109], v[162:165], v[28:31]
	v_mfma_f32_16x16x32_f16 v[24:27], v[114:117], v[162:165], v[24:27]
	s_waitcnt lgkmcnt(4)
	v_mfma_f32_16x16x32_f16 v[12:15], v[106:109], v[170:173], v[12:15]
	v_mfma_f32_16x16x32_f16 v[8:11], v[114:117], v[170:173], v[8:11]
	s_waitcnt lgkmcnt(3)
	v_mfma_f32_16x16x32_f16 v[62:65], v[110:113], v[150:153], v[62:65]
	v_mfma_f32_16x16x32_f16 v[58:61], v[134:137], v[150:153], v[58:61]
	s_waitcnt lgkmcnt(2)
	v_mfma_f32_16x16x32_f16 v[46:49], v[110:113], v[158:161], v[46:49]
	v_mfma_f32_16x16x32_f16 v[42:45], v[134:137], v[158:161], v[42:45]
	s_waitcnt lgkmcnt(1)
	v_mfma_f32_16x16x32_f16 v[28:31], v[110:113], v[166:169], v[28:31]
	v_mfma_f32_16x16x32_f16 v[24:27], v[134:137], v[166:169], v[24:27]
	s_waitcnt lgkmcnt(0)
	v_mfma_f32_16x16x32_f16 v[12:15], v[110:113], v[174:177], v[12:15]
	v_mfma_f32_16x16x32_f16 v[8:11], v[134:137], v[174:177], v[8:11]
	s_setprio 0
	s_barrier
	s_add_u32 s10, s14, 0xb0080
	s_addc_u32 s11, s15, 0
	s_add_i32 s14, s16, s23
	v_lshl_add_u64 v[106:107], s[10:11], 0, v[32:33]
	s_mov_b32 m0, s14
	s_nop 0
	global_load_lds_dwordx4 v[106:107], off
	v_lshl_add_u64 v[106:107], s[10:11], 0, v[182:183]
	s_add_i32 m0, s14, 0x2000
	s_nop 0
	global_load_lds_dwordx4 v[106:107], off
	s_waitcnt vmcnt(6)
	s_barrier
	s_setprio 1
	v_mfma_f32_16x16x32_f16 v[54:57], v[178:181], v[138:141], v[54:57]
	v_mfma_f32_16x16x32_f16 v[50:53], v[192:195], v[138:141], v[50:53]
	v_mfma_f32_16x16x32_f16 v[38:41], v[178:181], v[154:157], v[38:41]
	v_mfma_f32_16x16x32_f16 v[34:37], v[192:195], v[154:157], v[34:37]
	v_mfma_f32_16x16x32_f16 v[20:23], v[178:181], v[162:165], v[20:23]
	v_mfma_f32_16x16x32_f16 v[16:19], v[192:195], v[162:165], v[16:19]
	v_mfma_f32_16x16x32_f16 v[4:7], v[178:181], v[170:173], v[4:7]
	v_mfma_f32_16x16x32_f16 v[0:3], v[192:195], v[170:173], v[0:3]
	v_mfma_f32_16x16x32_f16 v[54:57], v[188:191], v[150:153], v[54:57]
	v_mfma_f32_16x16x32_f16 v[50:53], v[196:199], v[150:153], v[50:53]
	v_mfma_f32_16x16x32_f16 v[38:41], v[188:191], v[158:161], v[38:41]
	v_mfma_f32_16x16x32_f16 v[34:37], v[196:199], v[158:161], v[34:37]
	v_mfma_f32_16x16x32_f16 v[20:23], v[188:191], v[166:169], v[20:23]
	v_mfma_f32_16x16x32_f16 v[16:19], v[196:199], v[166:169], v[16:19]
	v_mfma_f32_16x16x32_f16 v[4:7], v[188:191], v[174:177], v[4:7]
	v_mfma_f32_16x16x32_f16 v[0:3], v[196:199], v[174:177], v[0:3]
	s_setprio 0
	s_add_u32 s44, s44, 0x100
	s_addc_u32 s45, s45, 0
	s_cmp_ge_u32 s46, s42
	s_mov_b64 s[10:11], s[12:13]
	s_mov_b32 s14, s46
	s_barrier
	s_cbranch_scc0 .LBB0_1365
	s_cmp_eq_u32 s40, 0
	s_cselect_b32 s6, 0x9000, 0
	v_lshl_or_b32 v106, s41, 8, v231
	s_add_u32 s6, s31, s6
	s_addc_u32 s7, s34, 0
	v_ashrrev_i32_e32 v107, 31, v106
	v_lshl_add_u64 v[116:117], v[106:107], 2, s[6:7]
	global_load_dwordx4 v[108:111], v[116:117], off offset:16
	global_load_dwordx4 v[112:115], v[116:117], off
	s_cmp_eq_u32 s39, 0
	s_waitcnt vmcnt(0)
	v_pk_mul_f32 v[194:195], v[110:111], 0.5 op_sel_hi:[1,0]
	v_pk_mul_f32 v[198:199], v[114:115], 0.5 op_sel_hi:[1,0]
	v_pk_mul_f32 v[202:203], v[112:113], 0.5 op_sel_hi:[1,0]
	v_pk_mul_f32 v[200:201], v[108:109], 0.5 op_sel_hi:[1,0]
	global_load_dwordx4 v[108:111], v[116:117], off offset:528
	global_load_dwordx4 v[112:115], v[116:117], off offset:512
	s_waitcnt vmcnt(0)
	v_pk_mul_f32 v[188:189], v[110:111], 0.5 op_sel_hi:[1,0]
	v_pk_mul_f32 v[196:197], v[112:113], 0.5 op_sel_hi:[1,0]
	v_lshl_add_u32 v112, s40, 8, v229
	v_pk_mul_f32 v[190:191], v[114:115], 0.5 op_sel_hi:[1,0]
	v_pk_mul_f32 v[192:193], v[108:109], 0.5 op_sel_hi:[1,0]
	v_or_b32_e32 v114, 16, v112
	v_or_b32_e32 v110, 32, v112
	v_or_b32_e32 v108, 48, v112
	v_ashrrev_i32_e32 v113, 31, v112
	v_ashrrev_i32_e32 v115, 31, v114
	v_ashrrev_i32_e32 v111, 31, v110
	v_ashrrev_i32_e32 v109, 31, v108
	s_cbranch_scc1 .LBB0_1368
	s_add_i32 s96, s39, -1
	s_lshl_b64 s[6:7], s[96:97], 20
	v_readlane_b32 s8, v252, 11
	v_readlane_b32 s9, v252, 12
	s_add_u32 s6, s8, s6
	s_addc_u32 s7, s9, s7
	v_lshlrev_b64 v[138:139], 2, v[106:107]
	v_lshrrev_b32_e32 v150, 5, v220
	v_mul_u32_u24_e32 v150, 48, v150
	s_nop 0
	v_sub_co_u32_e32 v138, vcc, v138, v150
	s_nop 1
	v_subbrev_co_u32_e32 v139, vcc, 0, v139, vcc
	v_lshl_add_u64 v[138:139], s[6:7], 0, v[138:139]
	s_mov_b64 s[6:7], 0x80000
	v_lshlrev_b64 v[204:205], 12, v[112:113]
	v_lshl_add_u64 v[204:205], v[204:205], 0, v[138:139]
	v_lshl_add_u64 v[212:213], v[204:205], 0, s[6:7]
	v_lshlrev_b64 v[206:207], 12, v[114:115]
	v_lshl_add_u64 v[206:207], v[206:207], 0, v[138:139]
	v_lshl_add_u64 v[214:215], v[206:207], 0, s[6:7]
	v_lshlrev_b64 v[208:209], 12, v[110:111]
	v_lshl_add_u64 v[208:209], v[208:209], 0, v[138:139]
	v_lshl_add_u64 v[216:217], v[208:209], 0, s[6:7]
	v_lshlrev_b64 v[210:211], 12, v[108:109]
	v_lshl_add_u64 v[210:211], v[210:211], 0, v[138:139]
	v_lshl_add_u64 v[218:219], v[210:211], 0, s[6:7]
	s_waitcnt vmcnt(0)
	v_pk_mul_f32 v[152:153], v[146:147], v[202:203]
	v_pk_mul_f32 v[154:155], v[148:149], v[198:199]
	v_pk_mul_f32 v[156:157], v[142:143], v[200:201]
	v_pk_mul_f32 v[158:159], v[144:145], v[194:195]
	s_nop 1
	v_permlane32_swap_b32_e32 v152, v156
	v_permlane32_swap_b32_e32 v153, v157
	v_permlane32_swap_b32_e32 v154, v158
	v_permlane32_swap_b32_e32 v155, v159
	s_nop 0
	global_store_dwordx4 v[204:205], v[152:155], off
	global_store_dwordx4 v[204:205], v[156:159], off offset:64
	v_pk_mul_f32 v[160:161], v[126:127], v[196:197]
	v_pk_mul_f32 v[162:163], v[128:129], v[190:191]
	v_pk_mul_f32 v[164:165], v[118:119], v[192:193]
	v_pk_mul_f32 v[166:167], v[120:121], v[188:189]
	s_nop 1
	v_permlane32_swap_b32_e32 v160, v164
	v_permlane32_swap_b32_e32 v161, v165
	v_permlane32_swap_b32_e32 v162, v166
	v_permlane32_swap_b32_e32 v163, v167
	s_nop 0
	global_store_dwordx4 v[204:205], v[160:163], off offset:512
	global_store_dwordx4 v[204:205], v[164:167], off offset:576
	v_pk_mul_f32 v[168:169], v[130:131], v[202:203]
	v_pk_mul_f32 v[170:171], v[132:133], v[198:199]
	v_pk_mul_f32 v[172:173], v[122:123], v[200:201]
	v_pk_mul_f32 v[174:175], v[124:125], v[194:195]
	s_nop 1
	v_permlane32_swap_b32_e32 v168, v172
	v_permlane32_swap_b32_e32 v169, v173
	v_permlane32_swap_b32_e32 v170, v174
	v_permlane32_swap_b32_e32 v171, v175
	s_nop 0
	global_store_dwordx4 v[206:207], v[168:171], off
	global_store_dwordx4 v[206:207], v[172:175], off offset:64
	v_pk_mul_f32 v[176:177], v[102:103], v[196:197]
	v_pk_mul_f32 v[178:179], v[104:105], v[190:191]
	v_pk_mul_f32 v[180:181], v[98:99], v[192:193]
	v_pk_mul_f32 v[182:183], v[100:101], v[188:189]
	s_nop 1
	v_permlane32_swap_b32_e32 v176, v180
	v_permlane32_swap_b32_e32 v177, v181
	v_permlane32_swap_b32_e32 v178, v182
	v_permlane32_swap_b32_e32 v179, v183
	s_nop 0
	global_store_dwordx4 v[206:207], v[176:179], off offset:512
	global_store_dwordx4 v[206:207], v[180:183], off offset:576
	v_pk_mul_f32 v[152:153], v[94:95], v[202:203]
	v_pk_mul_f32 v[154:155], v[96:97], v[198:199]
	v_pk_mul_f32 v[156:157], v[90:91], v[200:201]
	v_pk_mul_f32 v[158:159], v[92:93], v[194:195]
	s_nop 1
	v_permlane32_swap_b32_e32 v152, v156
	v_permlane32_swap_b32_e32 v153, v157
	v_permlane32_swap_b32_e32 v154, v158
	v_permlane32_swap_b32_e32 v155, v159
	s_nop 0
	global_store_dwordx4 v[208:209], v[152:155], off
	global_store_dwordx4 v[208:209], v[156:159], off offset:64
	v_pk_mul_f32 v[160:161], v[86:87], v[196:197]
	v_pk_mul_f32 v[162:163], v[88:89], v[190:191]
	v_pk_mul_f32 v[164:165], v[82:83], v[192:193]
	v_pk_mul_f32 v[166:167], v[84:85], v[188:189]
	s_nop 1
	v_permlane32_swap_b32_e32 v160, v164
	v_permlane32_swap_b32_e32 v161, v165
	v_permlane32_swap_b32_e32 v162, v166
	v_permlane32_swap_b32_e32 v163, v167
	s_nop 0
	global_store_dwordx4 v[208:209], v[160:163], off offset:512
	global_store_dwordx4 v[208:209], v[164:167], off offset:576
	v_pk_mul_f32 v[168:169], v[78:79], v[202:203]
	v_pk_mul_f32 v[170:171], v[80:81], v[198:199]
	v_pk_mul_f32 v[172:173], v[74:75], v[200:201]
	v_pk_mul_f32 v[174:175], v[76:77], v[194:195]
	s_nop 1
	v_permlane32_swap_b32_e32 v168, v172
	v_permlane32_swap_b32_e32 v169, v173
	v_permlane32_swap_b32_e32 v170, v174
	v_permlane32_swap_b32_e32 v171, v175
	s_nop 0
	global_store_dwordx4 v[210:211], v[168:171], off
	global_store_dwordx4 v[210:211], v[172:175], off offset:64
	v_pk_mul_f32 v[176:177], v[70:71], v[196:197]
	v_pk_mul_f32 v[178:179], v[72:73], v[190:191]
	v_pk_mul_f32 v[180:181], v[66:67], v[192:193]
	v_pk_mul_f32 v[182:183], v[68:69], v[188:189]
	s_nop 1
	v_permlane32_swap_b32_e32 v176, v180
	v_permlane32_swap_b32_e32 v177, v181
	v_permlane32_swap_b32_e32 v178, v182
	v_permlane32_swap_b32_e32 v179, v183
	s_nop 0
	global_store_dwordx4 v[210:211], v[176:179], off offset:512
	global_store_dwordx4 v[210:211], v[180:183], off offset:576
	v_pk_mul_f32 v[152:153], v[62:63], v[202:203]
	v_pk_mul_f32 v[154:155], v[64:65], v[198:199]
	v_pk_mul_f32 v[156:157], v[58:59], v[200:201]
	v_pk_mul_f32 v[158:159], v[60:61], v[194:195]
	s_nop 1
	v_permlane32_swap_b32_e32 v152, v156
	v_permlane32_swap_b32_e32 v153, v157
	v_permlane32_swap_b32_e32 v154, v158
	v_permlane32_swap_b32_e32 v155, v159
	s_nop 0
	global_store_dwordx4 v[212:213], v[152:155], off
	global_store_dwordx4 v[212:213], v[156:159], off offset:64
	v_pk_mul_f32 v[160:161], v[54:55], v[196:197]
	v_pk_mul_f32 v[162:163], v[56:57], v[190:191]
	v_pk_mul_f32 v[164:165], v[50:51], v[192:193]
	v_pk_mul_f32 v[166:167], v[52:53], v[188:189]
	s_nop 1
	v_permlane32_swap_b32_e32 v160, v164
	v_permlane32_swap_b32_e32 v161, v165
	v_permlane32_swap_b32_e32 v162, v166
	v_permlane32_swap_b32_e32 v163, v167
	s_nop 0
	global_store_dwordx4 v[212:213], v[160:163], off offset:512
	global_store_dwordx4 v[212:213], v[164:167], off offset:576
	v_pk_mul_f32 v[168:169], v[46:47], v[202:203]
	v_pk_mul_f32 v[170:171], v[48:49], v[198:199]
	v_pk_mul_f32 v[172:173], v[42:43], v[200:201]
	v_pk_mul_f32 v[174:175], v[44:45], v[194:195]
	s_nop 1
	v_permlane32_swap_b32_e32 v168, v172
	v_permlane32_swap_b32_e32 v169, v173
	v_permlane32_swap_b32_e32 v170, v174
	v_permlane32_swap_b32_e32 v171, v175
	s_nop 0
	global_store_dwordx4 v[214:215], v[168:171], off
	global_store_dwordx4 v[214:215], v[172:175], off offset:64
	v_pk_mul_f32 v[176:177], v[38:39], v[196:197]
	v_pk_mul_f32 v[178:179], v[40:41], v[190:191]
	v_pk_mul_f32 v[180:181], v[34:35], v[192:193]
	v_pk_mul_f32 v[182:183], v[36:37], v[188:189]
	s_nop 1
	v_permlane32_swap_b32_e32 v176, v180
	v_permlane32_swap_b32_e32 v177, v181
	v_permlane32_swap_b32_e32 v178, v182
	v_permlane32_swap_b32_e32 v179, v183
	s_nop 0
	global_store_dwordx4 v[214:215], v[176:179], off offset:512
	global_store_dwordx4 v[214:215], v[180:183], off offset:576
	v_pk_mul_f32 v[152:153], v[28:29], v[202:203]
	v_pk_mul_f32 v[154:155], v[30:31], v[198:199]
	v_pk_mul_f32 v[156:157], v[24:25], v[200:201]
	v_pk_mul_f32 v[158:159], v[26:27], v[194:195]
	s_nop 1
	v_permlane32_swap_b32_e32 v152, v156
	v_permlane32_swap_b32_e32 v153, v157
	v_permlane32_swap_b32_e32 v154, v158
	v_permlane32_swap_b32_e32 v155, v159
	s_nop 0
	global_store_dwordx4 v[216:217], v[152:155], off
	global_store_dwordx4 v[216:217], v[156:159], off offset:64
	v_pk_mul_f32 v[160:161], v[20:21], v[196:197]
	v_pk_mul_f32 v[162:163], v[22:23], v[190:191]
	v_pk_mul_f32 v[164:165], v[16:17], v[192:193]
	v_pk_mul_f32 v[166:167], v[18:19], v[188:189]
	s_nop 1
	v_permlane32_swap_b32_e32 v160, v164
	v_permlane32_swap_b32_e32 v161, v165
	v_permlane32_swap_b32_e32 v162, v166
	v_permlane32_swap_b32_e32 v163, v167
	s_nop 0
	global_store_dwordx4 v[216:217], v[160:163], off offset:512
	global_store_dwordx4 v[216:217], v[164:167], off offset:576
	v_pk_mul_f32 v[168:169], v[12:13], v[202:203]
	v_pk_mul_f32 v[170:171], v[14:15], v[198:199]
	v_pk_mul_f32 v[172:173], v[8:9], v[200:201]
	v_pk_mul_f32 v[174:175], v[10:11], v[194:195]
	s_nop 1
	v_permlane32_swap_b32_e32 v168, v172
	v_permlane32_swap_b32_e32 v169, v173
	v_permlane32_swap_b32_e32 v170, v174
	v_permlane32_swap_b32_e32 v171, v175
	s_nop 0
	global_store_dwordx4 v[218:219], v[168:171], off
	global_store_dwordx4 v[218:219], v[172:175], off offset:64
	v_pk_mul_f32 v[176:177], v[4:5], v[196:197]
	v_pk_mul_f32 v[178:179], v[6:7], v[190:191]
	v_pk_mul_f32 v[180:181], v[0:1], v[192:193]
	v_pk_mul_f32 v[182:183], v[2:3], v[188:189]
	s_nop 1
	v_permlane32_swap_b32_e32 v176, v180
	v_permlane32_swap_b32_e32 v177, v181
	v_permlane32_swap_b32_e32 v178, v182
	v_permlane32_swap_b32_e32 v179, v183
	s_nop 0
	global_store_dwordx4 v[218:219], v[176:179], off offset:512
	global_store_dwordx4 v[218:219], v[180:183], off offset:576
	s_cbranch_execnz .LBB0_1352
	s_branch .LBB0_1351
